# init phase no longer copies x to the residual stream: the first LayerNorm reads x directly (only with the 256-workgroup fast path; generic path unchanged)
# speedup vs baseline: 1.0066x; 1.0009x over previous
.LBB0_40:
	v_lshl_add_u64 v[8:9], s[76:77], 0, v[2:3]
	global_load_dwordx4 v[8:11], v[8:9], off nt
	v_and_b32_e32 v16, 0x3fc, v6
	v_alignbit_b32 v17, v1, v0, 19
	v_mov_b64_e32 v[14:15], s[34:35]
	v_mad_u64_u32 v[14:15], s[0:1], v17, s15, v[14:15]
	v_lshlrev_b32_e32 v32, 2, v16
	v_lshl_add_u64 v[16:17], v[14:15], 0, v[32:33]
	v_lshl_add_u64 v[12:13], s[68:69], 0, v[2:3]
	v_add_co_u32_e32 v14, vcc, s25, v16
	v_lshl_add_u64 v[0:1], v[0:1], 0, s[16:17]
	s_nop 0
	v_addc_co_u32_e32 v15, vcc, 0, v17, vcc
	s_mov_b64 s[0:1], 0x7fffff
	v_cmp_lt_u64_e32 vcc, s[0:1], v[0:1]
	v_lshl_add_u64 v[2:3], v[2:3], 0, s[18:19]
	v_lshl_add_u64 v[6:7], v[6:7], 0, s[22:23]
	s_or_b64 s[40:41], vcc, s[40:41]
	s_waitcnt vmcnt(0)
	v_readlane_b32 s0, v252, 8
	s_cmpk_eq_i32 s0, 0x800
	s_cbranch_scc1 .Linit_nocopy
	global_store_dwordx4 v[12:13], v[8:11], off
.Linit_nocopy:
	global_load_dwordx4 v[12:15], v[14:15], off
	s_nop 0
	global_load_dwordx4 v[16:19], v[16:17], off
	s_waitcnt vmcnt(1)
	v_pk_add_f32 v[14:15], v[14:15], 1.0 op_sel_hi:[1,0]
	v_pk_add_f32 v[12:13], v[12:13], 1.0 op_sel_hi:[1,0]
	s_waitcnt vmcnt(0)
	v_pk_fma_f32 v[10:11], v[10:11], v[14:15], v[18:19]
	v_pk_fma_f32 v[8:9], v[8:9], v[12:13], v[16:17]
	s_nop 0
	v_cvt_pk_bf16_f32 v8, v8, v9
	v_cvt_pk_bf16_f32 v9, v10, v11
	global_store_dwordx2 v[4:5], v[8:9], off
	v_lshl_add_u64 v[4:5], v[4:5], 0, s[20:21]
	s_andn2_b64 exec, exec, s[40:41]
	s_cbranch_execnz .LBB0_40

.LBB0_49:
	s_and_b64 vcc, exec, s[42:43]
	s_cbranch_vccz .LBB0_226
	v_mov_b32_e32 v0, v135
	v_readlane_b32 s1, v252, 49
	v_readfirstlane_b32 s0, v0
	s_ashr_i32 s0, s0, 6
	s_add_i32 s6, s0, s1
	s_cmpk_gt_i32 s6, 0x7fff
	v_readlane_b32 s3, v252, 8
	s_cbranch_scc1 .LBB0_53
	s_mul_i32 s0, s16, 0x90000
	v_readlane_b32 s1, v252, 4
	s_add_u32 s7, s1, s0
	v_readlane_b32 s0, v252, 5
	s_addc_u32 s18, s0, 0
	s_cmp_eq_u32 s64, 1
	s_cselect_b64 s[0:1], -1, 0
	v_cndmask_b32_e64 v8, 0.5, 1.0, s[0:1]
	s_and_b64 s[0:1], s[0:1], s[92:93]
	s_and_b64 s[0:1], s[0:1], exec
	s_brev_b32 s0, 16
	s_cselect_b32 s0, s0, 0xc000000
	v_readlane_b32 s20, v252, 2
	v_readlane_b32 s21, v252, 3
	s_add_u32 s0, s20, s0
	s_addc_u32 s1, s21, 0
	s_cmp_lt_u32 s86, 39
	s_mul_i32 s30, s64, 0xc00
	s_cselect_b64 s[20:21], -1, 0
	s_add_i32 s25, s30, 0xc00
	s_cmp_eq_u32 s64, 2
	s_cselect_b64 s[22:23], -1, 0
	s_and_b64 s[34:35], s[22:23], exec
	s_cselect_b32 s34, 0, s25
	s_and_b64 s[20:21], s[22:23], s[20:21]
	s_and_b64 s[20:21], s[20:21], exec
	s_cselect_b32 s20, 0x90000, 0
	s_add_u32 s25, s7, s20
	s_addc_u32 s40, s18, 0
	s_lshl_b64 s[20:21], s[30:31], 2
	s_add_u32 s20, s7, s20
	s_mov_b32 s35, s31
	s_addc_u32 s21, s18, s21
	s_lshl_b64 s[22:23], s[34:35], 2
	s_add_u32 s22, s25, s22
	s_mul_i32 s7, s16, 3
	s_addc_u32 s23, s40, s23
	s_add_i32 s7, s64, s7
	v_lshlrev_b32_e32 v0, 2, v0
	s_lshl_b32 s30, s7, 10
	v_readlane_b32 s40, v254, 24
	v_and_b32_e32 v1, 0xfc, v0
	s_movk_i32 s7, 0x80
	v_bfrev_b32_e32 v2, 0.5
	s_lshl_b64 s[34:35], s[30:31], 2
	v_readlane_b32 s50, v254, 34
	s_waitcnt vmcnt(0)
	v_bitop3_b32 v52, v0, s7, v2 bitop3:0x6c
	v_lshlrev_b32_e32 v32, 2, v1
	v_lshlrev_b32_e32 v0, 1, v1
	v_mov_b32_e32 v1, v33
	v_readlane_b32 s41, v254, 25
	v_readlane_b32 s51, v254, 35
	s_add_u32 s40, s50, s34
	v_lshl_add_u64 v[18:19], s[0:1], 0, v[0:1]
	v_lshl_add_u64 v[2:3], s[20:21], 0, v[32:33]
	s_mov_b64 s[0:1], 0x2000
	v_readlane_b32 s48, v254, 32
	s_addc_u32 s41, s51, s35
	v_lshl_add_u64 v[20:21], v[2:3], 0, s[0:1]
	v_lshl_add_u64 v[22:23], s[22:23], 0, v[32:33]
	s_mov_b64 s[0:1], 0x1000
	v_readlane_b32 s49, v254, 33
	s_add_u32 s34, s48, s34
	v_lshl_add_u64 v[24:25], v[22:23], 0, s[0:1]
	v_readlane_b32 s0, v252, 6
	s_addc_u32 s35, s49, s35
	v_readlane_b32 s1, v252, 7
	v_mov_b32_e32 v10, v8
	v_mov_b32_e32 v11, v8
	v_lshl_add_u64 v[12:13], s[34:35], 0, v[32:33]
	v_lshl_add_u64 v[14:15], s[40:41], 0, v[32:33]
	v_lshl_add_u64 v[16:17], s[68:69], 0, v[32:33]
	v_lshl_add_u64 v[26:27], s[0:1], 0, v[0:1]
	v_readlane_b32 s42, v254, 26
	v_readlane_b32 s43, v254, 27
	v_readlane_b32 s44, v254, 28
	v_readlane_b32 s45, v254, 29
	v_readlane_b32 s46, v254, 30
	v_readlane_b32 s47, v254, 31
	v_readlane_b32 s52, v254, 36
	v_readlane_b32 s53, v254, 37
	v_readlane_b32 s54, v254, 38
	v_readlane_b32 s55, v254, 39
	s_cmpk_lg_i32 s3, 0x800
	s_cbranch_scc1 .LBB0_52
	v_mov_b32_e32 v96, v52
	s_lshr_b32 s0, s6, 7
	s_and_b32 s7, s6, 7
	s_andn2_b32 s6, s6, 7
	s_lshl_b32 s6, s6, 4
	s_or_b32 s6, s6, s7
	v_mad_i64_i32 v[28:29], s[22:23], s0, v193, v[20:21]
	v_mad_i64_i32 v[30:31], s[22:23], s0, v193, v[22:23]
	v_mad_i64_i32 v[0:1], s[22:23], s0, v193, v[24:25]
	global_load_dwordx4 v[194:197], v[28:29], off
	global_load_dwordx4 v[198:201], v[28:29], off offset:1024
	global_load_dwordx4 v[202:205], v[28:29], off offset:2048
	global_load_dwordx4 v[206:209], v[28:29], off offset:3072
	global_load_dwordx4 v[210:213], v[30:31], off
	global_load_dwordx4 v[214:217], v[30:31], off offset:1024
	global_load_dwordx4 v[218:221], v[30:31], off offset:2048
	global_load_dwordx4 v[222:225], v[30:31], off offset:3072
	global_load_dwordx4 v[226:229], v[0:1], off
	global_load_dwordx4 v[230:233], v[0:1], off offset:1024
	global_load_dwordx4 v[234:237], v[0:1], off offset:2048
	global_load_dwordx4 v[238:241], v[0:1], off offset:3072
	global_load_dwordx4 v[140:143], v[12:13], off
	global_load_dwordx4 v[144:147], v[12:13], off offset:1024
	global_load_dwordx4 v[148:151], v[12:13], off offset:2048
	global_load_dwordx4 v[152:155], v[12:13], off offset:3072
	global_load_dwordx4 v[98:101], v[14:15], off
	global_load_dwordx4 v[102:105], v[14:15], off offset:1024
	global_load_dwordx4 v[106:109], v[14:15], off offset:2048
	global_load_dwordx4 v[110:113], v[14:15], off offset:3072
	s_ashr_i32 s7, s6, 31
	s_lshl_b64 s[40:41], s[6:7], 12
	s_lshl_b64 s[20:21], s[6:7], 11
	v_lshl_add_u64 v[82:83], v[16:17], 0, s[40:41]
	v_lshl_add_u64 v[84:85], v[18:19], 0, s[20:21]
	v_lshl_add_u64 v[88:89], v[26:27], 0, s[20:21]
	v_lshl_add_u64 v[86:87], v[16:17], 0, s[40:41]
	s_or_b32 s0, s16, s64
	s_cmp_lg_u32 s0, 0
	s_cbranch_scc1 .Lln_nox
	v_readlane_b32 s0, v254, 24
	v_readlane_b32 s1, v254, 25
	s_nop 1
	s_add_u32 s0, s0, s40
	s_addc_u32 s1, s1, s41
	v_lshl_add_u64 v[82:83], v[32:33], 0, s[0:1]
.Lln_nox:
	s_mov_b64 s[0:1], 0x8000
	s_mov_b64 s[20:21], 0x4000
	global_load_dwordx4 v[34:37], v[82:83], off nt
	global_load_dwordx4 v[38:41], v[82:83], off offset:1024 nt
	global_load_dwordx4 v[42:45], v[82:83], off offset:2048 nt
	global_load_dwordx4 v[46:49], v[82:83], off offset:3072 nt
	global_load_dwordx2 v[50:51], v[84:85], off
	global_load_dwordx2 v[52:53], v[84:85], off offset:512
	global_load_dwordx2 v[54:55], v[84:85], off offset:1024
	global_load_dwordx2 v[56:57], v[84:85], off offset:1536
	v_lshl_add_u64 v[82:83], v[82:83], 0, s[0:1]
	v_lshl_add_u64 v[84:85], v[84:85], 0, s[20:21]
	global_load_dwordx4 v[58:61], v[82:83], off nt
	global_load_dwordx4 v[62:65], v[82:83], off offset:1024 nt
	global_load_dwordx4 v[66:69], v[82:83], off offset:2048 nt
	global_load_dwordx4 v[70:73], v[82:83], off offset:3072 nt
	global_load_dwordx2 v[74:75], v[84:85], off
	global_load_dwordx2 v[76:77], v[84:85], off offset:512
	global_load_dwordx2 v[78:79], v[84:85], off offset:1024
	global_load_dwordx2 v[80:81], v[84:85], off offset:1536
	v_lshl_add_u64 v[82:83], v[82:83], 0, s[0:1]
	v_lshl_add_u64 v[84:85], v[84:85], 0, s[20:21]
	global_load_dwordx4 v[20:23], v[82:83], off nt
	global_load_dwordx4 v[24:27], v[82:83], off offset:1024 nt
	global_load_dwordx4 v[0:3], v[82:83], off offset:2048 nt
	global_load_dwordx4 v[4:7], v[82:83], off offset:3072 nt
	global_load_dwordx2 v[12:13], v[84:85], off
	global_load_dwordx2 v[14:15], v[84:85], off offset:512
	global_load_dwordx2 v[16:17], v[84:85], off offset:1024
	global_load_dwordx2 v[18:19], v[84:85], off offset:1536
	v_lshl_add_u64 v[82:83], v[82:83], 0, s[0:1]
	v_lshl_add_u64 v[84:85], v[84:85], 0, s[20:21]
	s_waitcnt vmcnt(24)
	v_pk_add_f32 v[194:195], v[194:195], 1.0 op_sel_hi:[1,0]
	v_pk_add_f32 v[196:197], v[196:197], 1.0 op_sel_hi:[1,0]
	v_pk_add_f32 v[198:199], v[198:199], 1.0 op_sel_hi:[1,0]
	v_pk_add_f32 v[200:201], v[200:201], 1.0 op_sel_hi:[1,0]
	v_pk_add_f32 v[202:203], v[202:203], 1.0 op_sel_hi:[1,0]
	v_pk_add_f32 v[204:205], v[204:205], 1.0 op_sel_hi:[1,0]
	v_pk_add_f32 v[206:207], v[206:207], 1.0 op_sel_hi:[1,0]
	v_pk_add_f32 v[208:209], v[208:209], 1.0 op_sel_hi:[1,0]
	v_pk_add_f32 v[226:227], v[226:227], 1.0 op_sel_hi:[1,0]
	v_pk_add_f32 v[228:229], v[228:229], 1.0 op_sel_hi:[1,0]
	v_pk_add_f32 v[230:231], v[230:231], 1.0 op_sel_hi:[1,0]
	v_pk_add_f32 v[232:233], v[232:233], 1.0 op_sel_hi:[1,0]
	v_pk_add_f32 v[234:235], v[234:235], 1.0 op_sel_hi:[1,0]
	v_pk_add_f32 v[236:237], v[236:237], 1.0 op_sel_hi:[1,0]
	v_pk_add_f32 v[238:239], v[238:239], 1.0 op_sel_hi:[1,0]
	v_pk_add_f32 v[240:241], v[240:241], 1.0 op_sel_hi:[1,0]
	s_waitcnt vmcnt(16)
	v_lshlrev_b32_e32 v156, 16, v50
	v_and_b32_e32 v157, 0xffff0000, v50
	v_lshlrev_b32_e32 v50, 16, v51
	v_and_b32_e32 v51, 0xffff0000, v51
	v_lshlrev_b32_e32 v158, 16, v52
	v_and_b32_e32 v159, 0xffff0000, v52
	v_lshlrev_b32_e32 v52, 16, v53
	v_and_b32_e32 v53, 0xffff0000, v53
	v_lshlrev_b32_e32 v160, 16, v54
	v_and_b32_e32 v161, 0xffff0000, v54
	v_lshlrev_b32_e32 v54, 16, v55
	v_and_b32_e32 v55, 0xffff0000, v55
	v_lshlrev_b32_e32 v162, 16, v56
	v_and_b32_e32 v163, 0xffff0000, v56
	v_lshlrev_b32_e32 v56, 16, v57
	v_and_b32_e32 v57, 0xffff0000, v57
	v_pk_mul_f32 v[114:115], v[194:195], v[156:157]
	v_pk_mul_f32 v[116:117], v[196:197], v[50:51]
	v_pk_mul_f32 v[118:119], v[198:199], v[158:159]
	v_pk_mul_f32 v[120:121], v[200:201], v[52:53]
	v_pk_mul_f32 v[122:123], v[202:203], v[160:161]
	v_pk_mul_f32 v[124:125], v[204:205], v[54:55]
	v_pk_mul_f32 v[126:127], v[206:207], v[162:163]
	v_pk_mul_f32 v[128:129], v[208:209], v[56:57]
	v_pk_mul_f32 v[114:115], v[10:11], v[114:115]
	v_pk_mul_f32 v[116:117], v[10:11], v[116:117]
	v_pk_mul_f32 v[118:119], v[10:11], v[118:119]
	v_pk_mul_f32 v[120:121], v[10:11], v[120:121]
	v_pk_mul_f32 v[122:123], v[10:11], v[122:123]
	v_pk_mul_f32 v[124:125], v[10:11], v[124:125]
	v_pk_mul_f32 v[126:127], v[10:11], v[126:127]
	v_pk_mul_f32 v[128:129], v[10:11], v[128:129]
	v_pk_fma_f32 v[114:115], v[34:35], s[28:29], v[114:115] op_sel_hi:[1,0,1]
	v_pk_fma_f32 v[116:117], v[36:37], s[28:29], v[116:117] op_sel_hi:[1,0,1]
	v_pk_fma_f32 v[118:119], v[38:39], s[28:29], v[118:119] op_sel_hi:[1,0,1]
	v_pk_fma_f32 v[120:121], v[40:41], s[28:29], v[120:121] op_sel_hi:[1,0,1]
	v_pk_fma_f32 v[122:123], v[42:43], s[28:29], v[122:123] op_sel_hi:[1,0,1]
	v_pk_fma_f32 v[124:125], v[44:45], s[28:29], v[124:125] op_sel_hi:[1,0,1]
	v_pk_fma_f32 v[126:127], v[46:47], s[28:29], v[126:127] op_sel_hi:[1,0,1]
	v_pk_fma_f32 v[128:129], v[48:49], s[28:29], v[128:129] op_sel_hi:[1,0,1]
	v_add_f32_e32 v164, v114, v115
	v_add_f32_e32 v165, v116, v117
	v_add_f32_e32 v166, v118, v119
	v_add_f32_e32 v167, v120, v121
	v_add_f32_e32 v168, v122, v123
	v_add_f32_e32 v169, v124, v125
	v_add_f32_e32 v242, v126, v127
	v_add_f32_e32 v243, v128, v129
	v_add_f32_e32 v164, v164, v165
	v_add_f32_e32 v166, v166, v167
	v_add_f32_e32 v168, v168, v169
	v_add_f32_e32 v242, v242, v243
	v_add_f32_e32 v9, 0, v164
	v_add_f32_e32 v9, v9, v166
	v_add_f32_e32 v9, v9, v168
	v_add_f32_e32 v9, v9, v242
	ds_bpermute_b32 v28, v96, v9
	s_waitcnt lgkmcnt(0)
	v_add_f32_e32 v9, v9, v28
	ds_swizzle_b32 v28, v9 offset:swizzle(SWAP,16)
	s_waitcnt lgkmcnt(0)
	v_add_f32_e32 v9, v9, v28
	ds_swizzle_b32 v28, v9 offset:swizzle(SWAP,8)
	s_waitcnt lgkmcnt(0)
	v_add_f32_e32 v9, v9, v28
	ds_swizzle_b32 v28, v9 offset:swizzle(SWAP,4)
	s_waitcnt lgkmcnt(0)
	v_add_f32_e32 v9, v9, v28
	ds_swizzle_b32 v28, v9 offset:swizzle(SWAP,2)
	s_waitcnt lgkmcnt(0)
	v_add_f32_e32 v9, v9, v28
	ds_swizzle_b32 v28, v9 offset:swizzle(SWAP,1)
	s_waitcnt lgkmcnt(0)
	v_add_f32_e32 v9, v9, v28
	v_fmac_f32_e32 v114, 0xba800000, v9
	v_fmac_f32_e32 v115, 0xba800000, v9
	v_fmac_f32_e32 v116, 0xba800000, v9
	v_fmac_f32_e32 v117, 0xba800000, v9
	v_fmac_f32_e32 v118, 0xba800000, v9
	v_fmac_f32_e32 v119, 0xba800000, v9
	v_fmac_f32_e32 v120, 0xba800000, v9
	v_fmac_f32_e32 v121, 0xba800000, v9
	v_fmac_f32_e32 v122, 0xba800000, v9
	v_fmac_f32_e32 v123, 0xba800000, v9
	v_fmac_f32_e32 v124, 0xba800000, v9
	v_fmac_f32_e32 v125, 0xba800000, v9
	v_fmac_f32_e32 v126, 0xba800000, v9
	v_fmac_f32_e32 v127, 0xba800000, v9
	v_fmac_f32_e32 v128, 0xba800000, v9
	v_fmac_f32_e32 v129, 0xba800000, v9
	v_pk_mul_f32 v[244:245], v[114:115], v[114:115]
	v_pk_mul_f32 v[246:247], v[116:117], v[116:117]
	v_add_f32_e32 v244, v245, v244
	v_add_f32_e32 v246, v246, v247
	v_add_f32_e32 v164, v244, v246
	v_pk_mul_f32 v[244:245], v[118:119], v[118:119]
	v_pk_mul_f32 v[246:247], v[120:121], v[120:121]
	v_add_f32_e32 v244, v245, v244
	v_add_f32_e32 v246, v246, v247
	v_add_f32_e32 v165, v244, v246
	v_mul_f32_e32 v248, v122, v122
	v_mul_f32_e32 v249, v124, v124
	v_fmac_f32_e32 v248, v123, v123
	v_fmac_f32_e32 v249, v125, v125
	v_add_f32_e32 v166, v248, v249
	v_pk_mul_f32 v[244:245], v[126:127], v[126:127]
	v_pk_mul_f32 v[246:247], v[128:129], v[128:129]
	v_add_f32_e32 v244, v244, v245
	v_add_f32_e32 v246, v246, v247
	v_add_f32_e32 v167, v244, v246
	v_add_f32_e32 v164, v164, v165
	v_add_f32_e32 v164, v166, v164
	v_add_f32_e32 v9, v167, v164
	ds_bpermute_b32 v28, v96, v9
	s_waitcnt lgkmcnt(0)
	v_add_f32_e32 v9, v9, v28
	ds_swizzle_b32 v28, v9 offset:swizzle(SWAP,16)
	s_waitcnt lgkmcnt(0)
	v_add_f32_e32 v9, v9, v28
	ds_swizzle_b32 v28, v9 offset:swizzle(SWAP,8)
	s_waitcnt lgkmcnt(0)
	v_add_f32_e32 v9, v9, v28
	ds_swizzle_b32 v28, v9 offset:swizzle(SWAP,4)
	s_waitcnt lgkmcnt(0)
	v_add_f32_e32 v9, v9, v28
	ds_swizzle_b32 v28, v9 offset:swizzle(SWAP,2)
	s_waitcnt lgkmcnt(0)
	v_add_f32_e32 v9, v9, v28
	ds_swizzle_b32 v28, v9 offset:swizzle(SWAP,1)
	s_waitcnt lgkmcnt(0)
	v_add_f32_e32 v9, v9, v28
	v_mov_b32_e32 v28, 0x3727c5ac
	v_fmamk_f32 v9, v9, 0x3a800000, v28
	v_mul_f32_e32 v28, 0x4b800000, v9
	v_cmp_gt_f32_e32 vcc, s37, v9
	s_nop 1
	v_cndmask_b32_e32 v9, v9, v28, vcc
	v_rsq_f32_e32 v9, v9
	s_nop 0
	v_mul_f32_e32 v28, 0x45800000, v9
	v_cndmask_b32_e32 v30, v9, v28, vcc
	v_pk_mul_f32 v[114:115], v[114:115], v[30:31] op_sel_hi:[1,0]
	v_pk_mul_f32 v[116:117], v[116:117], v[30:31] op_sel_hi:[1,0]
	v_pk_fma_f32 v[34:35], v[140:141], v[114:115], v[98:99]
	v_pk_fma_f32 v[36:37], v[142:143], v[116:117], v[100:101]
	global_store_dwordx4 v[86:87], v[34:37], off sc1 nt
	v_pk_fma_f32 v[114:115], v[226:227], v[34:35], v[210:211]
	v_pk_fma_f32 v[116:117], v[228:229], v[36:37], v[212:213]
	s_nop 0
	v_cvt_pk_bf16_f32 v50, v114, v115
	v_cvt_pk_bf16_f32 v51, v116, v117
	global_store_dwordx2 v[88:89], v[50:51], off sc1
	v_pk_mul_f32 v[118:119], v[118:119], v[30:31] op_sel_hi:[1,0]
	v_pk_mul_f32 v[120:121], v[120:121], v[30:31] op_sel_hi:[1,0]
	v_pk_fma_f32 v[38:39], v[144:145], v[118:119], v[102:103]
	v_pk_fma_f32 v[40:41], v[146:147], v[120:121], v[104:105]
	global_store_dwordx4 v[86:87], v[38:41], off offset:1024 sc1 nt
	v_pk_fma_f32 v[118:119], v[230:231], v[38:39], v[214:215]
	v_pk_fma_f32 v[120:121], v[232:233], v[40:41], v[216:217]
	s_nop 0
	v_cvt_pk_bf16_f32 v52, v118, v119
	v_cvt_pk_bf16_f32 v53, v120, v121
	global_store_dwordx2 v[88:89], v[52:53], off offset:512 sc1
	v_pk_mul_f32 v[122:123], v[122:123], v[30:31] op_sel_hi:[1,0]
	v_pk_mul_f32 v[124:125], v[124:125], v[30:31] op_sel_hi:[1,0]
	v_pk_fma_f32 v[42:43], v[148:149], v[122:123], v[106:107]
	v_pk_fma_f32 v[44:45], v[150:151], v[124:125], v[108:109]
	global_store_dwordx4 v[86:87], v[42:45], off offset:2048 sc1 nt
	v_pk_fma_f32 v[122:123], v[234:235], v[42:43], v[218:219]
	v_pk_fma_f32 v[124:125], v[236:237], v[44:45], v[220:221]
	s_nop 0
	v_cvt_pk_bf16_f32 v54, v122, v123
	v_cvt_pk_bf16_f32 v55, v124, v125
	global_store_dwordx2 v[88:89], v[54:55], off offset:1024 sc1
	v_pk_mul_f32 v[126:127], v[126:127], v[30:31] op_sel_hi:[1,0]
	v_pk_mul_f32 v[128:129], v[128:129], v[30:31] op_sel_hi:[1,0]
	v_pk_fma_f32 v[46:47], v[152:153], v[126:127], v[110:111]
	v_pk_fma_f32 v[48:49], v[154:155], v[128:129], v[112:113]
	global_store_dwordx4 v[86:87], v[46:49], off offset:3072 sc1 nt
	v_pk_fma_f32 v[126:127], v[238:239], v[46:47], v[222:223]
	v_pk_fma_f32 v[128:129], v[240:241], v[48:49], v[224:225]
	s_nop 0
	v_cvt_pk_bf16_f32 v56, v126, v127
	v_cvt_pk_bf16_f32 v57, v128, v129
	global_store_dwordx2 v[88:89], v[56:57], off offset:1536 sc1
	v_lshl_add_u64 v[86:87], v[86:87], 0, s[0:1]
	v_lshl_add_u64 v[88:89], v[88:89], 0, s[20:21]
	global_load_dwordx4 v[34:37], v[82:83], off nt
	global_load_dwordx4 v[38:41], v[82:83], off offset:1024 nt
	global_load_dwordx4 v[42:45], v[82:83], off offset:2048 nt
	global_load_dwordx4 v[46:49], v[82:83], off offset:3072 nt
	global_load_dwordx2 v[50:51], v[84:85], off
	global_load_dwordx2 v[52:53], v[84:85], off offset:512
	global_load_dwordx2 v[54:55], v[84:85], off offset:1024
	global_load_dwordx2 v[56:57], v[84:85], off offset:1536
	v_lshl_add_u64 v[82:83], v[82:83], 0, s[0:1]
	v_lshl_add_u64 v[84:85], v[84:85], 0, s[20:21]
	s_waitcnt vmcnt(24)
	v_lshlrev_b32_e32 v156, 16, v74
	v_and_b32_e32 v157, 0xffff0000, v74
	v_lshlrev_b32_e32 v74, 16, v75
	v_and_b32_e32 v75, 0xffff0000, v75
	v_lshlrev_b32_e32 v158, 16, v76
	v_and_b32_e32 v159, 0xffff0000, v76
	v_lshlrev_b32_e32 v76, 16, v77
	v_and_b32_e32 v77, 0xffff0000, v77
	v_lshlrev_b32_e32 v160, 16, v78
	v_and_b32_e32 v161, 0xffff0000, v78
	v_lshlrev_b32_e32 v78, 16, v79
	v_and_b32_e32 v79, 0xffff0000, v79
	v_lshlrev_b32_e32 v162, 16, v80
	v_and_b32_e32 v163, 0xffff0000, v80
	v_lshlrev_b32_e32 v80, 16, v81
	v_and_b32_e32 v81, 0xffff0000, v81
	v_pk_mul_f32 v[114:115], v[194:195], v[156:157]
	v_pk_mul_f32 v[116:117], v[196:197], v[74:75]
	v_pk_mul_f32 v[118:119], v[198:199], v[158:159]
	v_pk_mul_f32 v[120:121], v[200:201], v[76:77]
	v_pk_mul_f32 v[122:123], v[202:203], v[160:161]
	v_pk_mul_f32 v[124:125], v[204:205], v[78:79]
	v_pk_mul_f32 v[126:127], v[206:207], v[162:163]
	v_pk_mul_f32 v[128:129], v[208:209], v[80:81]
	v_pk_mul_f32 v[114:115], v[10:11], v[114:115]
	v_pk_mul_f32 v[116:117], v[10:11], v[116:117]
	v_pk_mul_f32 v[118:119], v[10:11], v[118:119]
	v_pk_mul_f32 v[120:121], v[10:11], v[120:121]
	v_pk_mul_f32 v[122:123], v[10:11], v[122:123]
	v_pk_mul_f32 v[124:125], v[10:11], v[124:125]
	v_pk_mul_f32 v[126:127], v[10:11], v[126:127]
	v_pk_mul_f32 v[128:129], v[10:11], v[128:129]
	v_pk_fma_f32 v[114:115], v[58:59], s[28:29], v[114:115] op_sel_hi:[1,0,1]
	v_pk_fma_f32 v[116:117], v[60:61], s[28:29], v[116:117] op_sel_hi:[1,0,1]
	v_pk_fma_f32 v[118:119], v[62:63], s[28:29], v[118:119] op_sel_hi:[1,0,1]
	v_pk_fma_f32 v[120:121], v[64:65], s[28:29], v[120:121] op_sel_hi:[1,0,1]
	v_pk_fma_f32 v[122:123], v[66:67], s[28:29], v[122:123] op_sel_hi:[1,0,1]
	v_pk_fma_f32 v[124:125], v[68:69], s[28:29], v[124:125] op_sel_hi:[1,0,1]
	v_pk_fma_f32 v[126:127], v[70:71], s[28:29], v[126:127] op_sel_hi:[1,0,1]
	v_pk_fma_f32 v[128:129], v[72:73], s[28:29], v[128:129] op_sel_hi:[1,0,1]
	v_add_f32_e32 v164, v114, v115
	v_add_f32_e32 v165, v116, v117
	v_add_f32_e32 v166, v118, v119
	v_add_f32_e32 v167, v120, v121
	v_add_f32_e32 v168, v122, v123
	v_add_f32_e32 v169, v124, v125
	v_add_f32_e32 v242, v126, v127
	v_add_f32_e32 v243, v128, v129
	v_add_f32_e32 v164, v164, v165
	v_add_f32_e32 v166, v166, v167
	v_add_f32_e32 v168, v168, v169
	v_add_f32_e32 v242, v242, v243
	v_add_f32_e32 v9, 0, v164
	v_add_f32_e32 v9, v9, v166
	v_add_f32_e32 v9, v9, v168
	v_add_f32_e32 v9, v9, v242
	ds_bpermute_b32 v28, v96, v9
	s_waitcnt lgkmcnt(0)
	v_add_f32_e32 v9, v9, v28
	ds_swizzle_b32 v28, v9 offset:swizzle(SWAP,16)
	s_waitcnt lgkmcnt(0)
	v_add_f32_e32 v9, v9, v28
	ds_swizzle_b32 v28, v9 offset:swizzle(SWAP,8)
	s_waitcnt lgkmcnt(0)
	v_add_f32_e32 v9, v9, v28
	ds_swizzle_b32 v28, v9 offset:swizzle(SWAP,4)
	s_waitcnt lgkmcnt(0)
	v_add_f32_e32 v9, v9, v28
	ds_swizzle_b32 v28, v9 offset:swizzle(SWAP,2)
	s_waitcnt lgkmcnt(0)
	v_add_f32_e32 v9, v9, v28
	ds_swizzle_b32 v28, v9 offset:swizzle(SWAP,1)
	s_waitcnt lgkmcnt(0)
	v_add_f32_e32 v9, v9, v28
	v_fmac_f32_e32 v114, 0xba800000, v9
	v_fmac_f32_e32 v115, 0xba800000, v9
	v_fmac_f32_e32 v116, 0xba800000, v9
	v_fmac_f32_e32 v117, 0xba800000, v9
	v_fmac_f32_e32 v118, 0xba800000, v9
	v_fmac_f32_e32 v119, 0xba800000, v9
	v_fmac_f32_e32 v120, 0xba800000, v9
	v_fmac_f32_e32 v121, 0xba800000, v9
	v_fmac_f32_e32 v122, 0xba800000, v9
	v_fmac_f32_e32 v123, 0xba800000, v9
	v_fmac_f32_e32 v124, 0xba800000, v9
	v_fmac_f32_e32 v125, 0xba800000, v9
	v_fmac_f32_e32 v126, 0xba800000, v9
	v_fmac_f32_e32 v127, 0xba800000, v9
	v_fmac_f32_e32 v128, 0xba800000, v9
	v_fmac_f32_e32 v129, 0xba800000, v9
	v_pk_mul_f32 v[244:245], v[114:115], v[114:115]
	v_pk_mul_f32 v[246:247], v[116:117], v[116:117]
	v_add_f32_e32 v244, v245, v244
	v_add_f32_e32 v246, v246, v247
	v_add_f32_e32 v164, v244, v246
	v_pk_mul_f32 v[244:245], v[118:119], v[118:119]
	v_pk_mul_f32 v[246:247], v[120:121], v[120:121]
	v_add_f32_e32 v244, v245, v244
	v_add_f32_e32 v246, v246, v247
	v_add_f32_e32 v165, v244, v246
	v_mul_f32_e32 v248, v122, v122
	v_mul_f32_e32 v249, v124, v124
	v_fmac_f32_e32 v248, v123, v123
	v_fmac_f32_e32 v249, v125, v125
	v_add_f32_e32 v166, v248, v249
	v_pk_mul_f32 v[244:245], v[126:127], v[126:127]
	v_pk_mul_f32 v[246:247], v[128:129], v[128:129]
	v_add_f32_e32 v244, v244, v245
	v_add_f32_e32 v246, v246, v247
	v_add_f32_e32 v167, v244, v246
	v_add_f32_e32 v164, v164, v165
	v_add_f32_e32 v164, v166, v164
	v_add_f32_e32 v9, v167, v164
	ds_bpermute_b32 v28, v96, v9
	s_waitcnt lgkmcnt(0)
	v_add_f32_e32 v9, v9, v28
	ds_swizzle_b32 v28, v9 offset:swizzle(SWAP,16)
	s_waitcnt lgkmcnt(0)
	v_add_f32_e32 v9, v9, v28
	ds_swizzle_b32 v28, v9 offset:swizzle(SWAP,8)
	s_waitcnt lgkmcnt(0)
	v_add_f32_e32 v9, v9, v28
	ds_swizzle_b32 v28, v9 offset:swizzle(SWAP,4)
	s_waitcnt lgkmcnt(0)
	v_add_f32_e32 v9, v9, v28
	ds_swizzle_b32 v28, v9 offset:swizzle(SWAP,2)
	s_waitcnt lgkmcnt(0)
	v_add_f32_e32 v9, v9, v28
	ds_swizzle_b32 v28, v9 offset:swizzle(SWAP,1)
	s_waitcnt lgkmcnt(0)
	v_add_f32_e32 v9, v9, v28
	v_mov_b32_e32 v28, 0x3727c5ac
	v_fmamk_f32 v9, v9, 0x3a800000, v28
	v_mul_f32_e32 v28, 0x4b800000, v9
	v_cmp_gt_f32_e32 vcc, s37, v9
	s_nop 1
	v_cndmask_b32_e32 v9, v9, v28, vcc
	v_rsq_f32_e32 v9, v9
	s_nop 0
	v_mul_f32_e32 v28, 0x45800000, v9
	v_cndmask_b32_e32 v30, v9, v28, vcc
	v_pk_mul_f32 v[114:115], v[114:115], v[30:31] op_sel_hi:[1,0]
	v_pk_mul_f32 v[116:117], v[116:117], v[30:31] op_sel_hi:[1,0]
	v_pk_fma_f32 v[58:59], v[140:141], v[114:115], v[98:99]
	v_pk_fma_f32 v[60:61], v[142:143], v[116:117], v[100:101]
	global_store_dwordx4 v[86:87], v[58:61], off sc1 nt
	v_pk_fma_f32 v[114:115], v[226:227], v[58:59], v[210:211]
	v_pk_fma_f32 v[116:117], v[228:229], v[60:61], v[212:213]
	s_nop 0
	v_cvt_pk_bf16_f32 v74, v114, v115
	v_cvt_pk_bf16_f32 v75, v116, v117
	global_store_dwordx2 v[88:89], v[74:75], off sc1
	v_pk_mul_f32 v[118:119], v[118:119], v[30:31] op_sel_hi:[1,0]
	v_pk_mul_f32 v[120:121], v[120:121], v[30:31] op_sel_hi:[1,0]
	v_pk_fma_f32 v[62:63], v[144:145], v[118:119], v[102:103]
	v_pk_fma_f32 v[64:65], v[146:147], v[120:121], v[104:105]
	global_store_dwordx4 v[86:87], v[62:65], off offset:1024 sc1 nt
	v_pk_fma_f32 v[118:119], v[230:231], v[62:63], v[214:215]
	v_pk_fma_f32 v[120:121], v[232:233], v[64:65], v[216:217]
	s_nop 0
	v_cvt_pk_bf16_f32 v76, v118, v119
	v_cvt_pk_bf16_f32 v77, v120, v121
	global_store_dwordx2 v[88:89], v[76:77], off offset:512 sc1
	v_pk_mul_f32 v[122:123], v[122:123], v[30:31] op_sel_hi:[1,0]
	v_pk_mul_f32 v[124:125], v[124:125], v[30:31] op_sel_hi:[1,0]
	v_pk_fma_f32 v[66:67], v[148:149], v[122:123], v[106:107]
	v_pk_fma_f32 v[68:69], v[150:151], v[124:125], v[108:109]
	global_store_dwordx4 v[86:87], v[66:69], off offset:2048 sc1 nt
	v_pk_fma_f32 v[122:123], v[234:235], v[66:67], v[218:219]
	v_pk_fma_f32 v[124:125], v[236:237], v[68:69], v[220:221]
	s_nop 0
	v_cvt_pk_bf16_f32 v78, v122, v123
	v_cvt_pk_bf16_f32 v79, v124, v125
	global_store_dwordx2 v[88:89], v[78:79], off offset:1024 sc1
	v_pk_mul_f32 v[126:127], v[126:127], v[30:31] op_sel_hi:[1,0]
	v_pk_mul_f32 v[128:129], v[128:129], v[30:31] op_sel_hi:[1,0]
	v_pk_fma_f32 v[70:71], v[152:153], v[126:127], v[110:111]
	v_pk_fma_f32 v[72:73], v[154:155], v[128:129], v[112:113]
	global_store_dwordx4 v[86:87], v[70:73], off offset:3072 sc1 nt
	v_pk_fma_f32 v[126:127], v[238:239], v[70:71], v[222:223]
	v_pk_fma_f32 v[128:129], v[240:241], v[72:73], v[224:225]
	s_nop 0
	v_cvt_pk_bf16_f32 v80, v126, v127
	v_cvt_pk_bf16_f32 v81, v128, v129
	global_store_dwordx2 v[88:89], v[80:81], off offset:1536 sc1
	v_lshl_add_u64 v[86:87], v[86:87], 0, s[0:1]
	v_lshl_add_u64 v[88:89], v[88:89], 0, s[20:21]
	global_load_dwordx4 v[58:61], v[82:83], off nt
	global_load_dwordx4 v[62:65], v[82:83], off offset:1024 nt
	global_load_dwordx4 v[66:69], v[82:83], off offset:2048 nt
	global_load_dwordx4 v[70:73], v[82:83], off offset:3072 nt
	global_load_dwordx2 v[74:75], v[84:85], off
	global_load_dwordx2 v[76:77], v[84:85], off offset:512
	global_load_dwordx2 v[78:79], v[84:85], off offset:1024
	global_load_dwordx2 v[80:81], v[84:85], off offset:1536
	v_lshl_add_u64 v[82:83], v[82:83], 0, s[0:1]
	v_lshl_add_u64 v[84:85], v[84:85], 0, s[20:21]
	s_waitcnt vmcnt(32)
	v_lshlrev_b32_e32 v156, 16, v12
	v_and_b32_e32 v157, 0xffff0000, v12
	v_lshlrev_b32_e32 v12, 16, v13
	v_and_b32_e32 v13, 0xffff0000, v13
	v_lshlrev_b32_e32 v158, 16, v14
	v_and_b32_e32 v159, 0xffff0000, v14
	v_lshlrev_b32_e32 v14, 16, v15
	v_and_b32_e32 v15, 0xffff0000, v15
	v_lshlrev_b32_e32 v160, 16, v16
	v_and_b32_e32 v161, 0xffff0000, v16
	v_lshlrev_b32_e32 v16, 16, v17
	v_and_b32_e32 v17, 0xffff0000, v17
	v_lshlrev_b32_e32 v162, 16, v18
	v_and_b32_e32 v163, 0xffff0000, v18
	v_lshlrev_b32_e32 v18, 16, v19
	v_and_b32_e32 v19, 0xffff0000, v19
	v_pk_mul_f32 v[114:115], v[194:195], v[156:157]
	v_pk_mul_f32 v[116:117], v[196:197], v[12:13]
	v_pk_mul_f32 v[118:119], v[198:199], v[158:159]
	v_pk_mul_f32 v[120:121], v[200:201], v[14:15]
	v_pk_mul_f32 v[122:123], v[202:203], v[160:161]
	v_pk_mul_f32 v[124:125], v[204:205], v[16:17]
	v_pk_mul_f32 v[126:127], v[206:207], v[162:163]
	v_pk_mul_f32 v[128:129], v[208:209], v[18:19]
	v_pk_mul_f32 v[114:115], v[10:11], v[114:115]
	v_pk_mul_f32 v[116:117], v[10:11], v[116:117]
	v_pk_mul_f32 v[118:119], v[10:11], v[118:119]
	v_pk_mul_f32 v[120:121], v[10:11], v[120:121]
	v_pk_mul_f32 v[122:123], v[10:11], v[122:123]
	v_pk_mul_f32 v[124:125], v[10:11], v[124:125]
	v_pk_mul_f32 v[126:127], v[10:11], v[126:127]
	v_pk_mul_f32 v[128:129], v[10:11], v[128:129]
	v_pk_fma_f32 v[114:115], v[20:21], s[28:29], v[114:115] op_sel_hi:[1,0,1]
	v_pk_fma_f32 v[116:117], v[22:23], s[28:29], v[116:117] op_sel_hi:[1,0,1]
	v_pk_fma_f32 v[118:119], v[24:25], s[28:29], v[118:119] op_sel_hi:[1,0,1]
	v_pk_fma_f32 v[120:121], v[26:27], s[28:29], v[120:121] op_sel_hi:[1,0,1]
	v_pk_fma_f32 v[122:123], v[0:1], s[28:29], v[122:123] op_sel_hi:[1,0,1]
	v_pk_fma_f32 v[124:125], v[2:3], s[28:29], v[124:125] op_sel_hi:[1,0,1]
	v_pk_fma_f32 v[126:127], v[4:5], s[28:29], v[126:127] op_sel_hi:[1,0,1]
	v_pk_fma_f32 v[128:129], v[6:7], s[28:29], v[128:129] op_sel_hi:[1,0,1]
	v_add_f32_e32 v164, v114, v115
	v_add_f32_e32 v165, v116, v117
	v_add_f32_e32 v166, v118, v119
	v_add_f32_e32 v167, v120, v121
	v_add_f32_e32 v168, v122, v123
	v_add_f32_e32 v169, v124, v125
	v_add_f32_e32 v242, v126, v127
	v_add_f32_e32 v243, v128, v129
	v_add_f32_e32 v164, v164, v165
	v_add_f32_e32 v166, v166, v167
	v_add_f32_e32 v168, v168, v169
	v_add_f32_e32 v242, v242, v243
	v_add_f32_e32 v9, 0, v164
	v_add_f32_e32 v9, v9, v166
	v_add_f32_e32 v9, v9, v168
	v_add_f32_e32 v9, v9, v242
	ds_bpermute_b32 v28, v96, v9
	s_waitcnt lgkmcnt(0)
	v_add_f32_e32 v9, v9, v28
	ds_swizzle_b32 v28, v9 offset:swizzle(SWAP,16)
	s_waitcnt lgkmcnt(0)
	v_add_f32_e32 v9, v9, v28
	ds_swizzle_b32 v28, v9 offset:swizzle(SWAP,8)
	s_waitcnt lgkmcnt(0)
	v_add_f32_e32 v9, v9, v28
	ds_swizzle_b32 v28, v9 offset:swizzle(SWAP,4)
	s_waitcnt lgkmcnt(0)
	v_add_f32_e32 v9, v9, v28
	ds_swizzle_b32 v28, v9 offset:swizzle(SWAP,2)
	s_waitcnt lgkmcnt(0)
	v_add_f32_e32 v9, v9, v28
	ds_swizzle_b32 v28, v9 offset:swizzle(SWAP,1)
	s_waitcnt lgkmcnt(0)
	v_add_f32_e32 v9, v9, v28
	v_fmac_f32_e32 v114, 0xba800000, v9
	v_fmac_f32_e32 v115, 0xba800000, v9
	v_fmac_f32_e32 v116, 0xba800000, v9
	v_fmac_f32_e32 v117, 0xba800000, v9
	v_fmac_f32_e32 v118, 0xba800000, v9
	v_fmac_f32_e32 v119, 0xba800000, v9
	v_fmac_f32_e32 v120, 0xba800000, v9
	v_fmac_f32_e32 v121, 0xba800000, v9
	v_fmac_f32_e32 v122, 0xba800000, v9
	v_fmac_f32_e32 v123, 0xba800000, v9
	v_fmac_f32_e32 v124, 0xba800000, v9
	v_fmac_f32_e32 v125, 0xba800000, v9
	v_fmac_f32_e32 v126, 0xba800000, v9
	v_fmac_f32_e32 v127, 0xba800000, v9
	v_fmac_f32_e32 v128, 0xba800000, v9
	v_fmac_f32_e32 v129, 0xba800000, v9
	v_pk_mul_f32 v[244:245], v[114:115], v[114:115]
	v_pk_mul_f32 v[246:247], v[116:117], v[116:117]
	v_add_f32_e32 v244, v245, v244
	v_add_f32_e32 v246, v246, v247
	v_add_f32_e32 v164, v244, v246
	v_pk_mul_f32 v[244:245], v[118:119], v[118:119]
	v_pk_mul_f32 v[246:247], v[120:121], v[120:121]
	v_add_f32_e32 v244, v245, v244
	v_add_f32_e32 v246, v246, v247
	v_add_f32_e32 v165, v244, v246
	v_mul_f32_e32 v248, v122, v122
	v_mul_f32_e32 v249, v124, v124
	v_fmac_f32_e32 v248, v123, v123
	v_fmac_f32_e32 v249, v125, v125
	v_add_f32_e32 v166, v248, v249
	v_pk_mul_f32 v[244:245], v[126:127], v[126:127]
	v_pk_mul_f32 v[246:247], v[128:129], v[128:129]
	v_add_f32_e32 v244, v244, v245
	v_add_f32_e32 v246, v246, v247
	v_add_f32_e32 v167, v244, v246
	v_add_f32_e32 v164, v164, v165
	v_add_f32_e32 v164, v166, v164
	v_add_f32_e32 v9, v167, v164
	ds_bpermute_b32 v28, v96, v9
	s_waitcnt lgkmcnt(0)
	v_add_f32_e32 v9, v9, v28
	ds_swizzle_b32 v28, v9 offset:swizzle(SWAP,16)
	s_waitcnt lgkmcnt(0)
	v_add_f32_e32 v9, v9, v28
	ds_swizzle_b32 v28, v9 offset:swizzle(SWAP,8)
	s_waitcnt lgkmcnt(0)
	v_add_f32_e32 v9, v9, v28
	ds_swizzle_b32 v28, v9 offset:swizzle(SWAP,4)
	s_waitcnt lgkmcnt(0)
	v_add_f32_e32 v9, v9, v28
	ds_swizzle_b32 v28, v9 offset:swizzle(SWAP,2)
	s_waitcnt lgkmcnt(0)
	v_add_f32_e32 v9, v9, v28
	ds_swizzle_b32 v28, v9 offset:swizzle(SWAP,1)
	s_waitcnt lgkmcnt(0)
	v_add_f32_e32 v9, v9, v28
	v_mov_b32_e32 v28, 0x3727c5ac
	v_fmamk_f32 v9, v9, 0x3a800000, v28
	v_mul_f32_e32 v28, 0x4b800000, v9
	v_cmp_gt_f32_e32 vcc, s37, v9
	s_nop 1
	v_cndmask_b32_e32 v9, v9, v28, vcc
	v_rsq_f32_e32 v9, v9
	s_nop 0
	v_mul_f32_e32 v28, 0x45800000, v9
	v_cndmask_b32_e32 v30, v9, v28, vcc
	v_pk_mul_f32 v[114:115], v[114:115], v[30:31] op_sel_hi:[1,0]
	v_pk_mul_f32 v[116:117], v[116:117], v[30:31] op_sel_hi:[1,0]
	v_pk_fma_f32 v[20:21], v[140:141], v[114:115], v[98:99]
	v_pk_fma_f32 v[22:23], v[142:143], v[116:117], v[100:101]
	global_store_dwordx4 v[86:87], v[20:23], off sc1 nt
	v_pk_fma_f32 v[114:115], v[226:227], v[20:21], v[210:211]
	v_pk_fma_f32 v[116:117], v[228:229], v[22:23], v[212:213]
	s_nop 0
	v_cvt_pk_bf16_f32 v12, v114, v115
	v_cvt_pk_bf16_f32 v13, v116, v117
	global_store_dwordx2 v[88:89], v[12:13], off sc1
	v_pk_mul_f32 v[118:119], v[118:119], v[30:31] op_sel_hi:[1,0]
	v_pk_mul_f32 v[120:121], v[120:121], v[30:31] op_sel_hi:[1,0]
	v_pk_fma_f32 v[24:25], v[144:145], v[118:119], v[102:103]
	v_pk_fma_f32 v[26:27], v[146:147], v[120:121], v[104:105]
	global_store_dwordx4 v[86:87], v[24:27], off offset:1024 sc1 nt
	v_pk_fma_f32 v[118:119], v[230:231], v[24:25], v[214:215]
	v_pk_fma_f32 v[120:121], v[232:233], v[26:27], v[216:217]
	s_nop 0
	v_cvt_pk_bf16_f32 v14, v118, v119
	v_cvt_pk_bf16_f32 v15, v120, v121
	global_store_dwordx2 v[88:89], v[14:15], off offset:512 sc1
	v_pk_mul_f32 v[122:123], v[122:123], v[30:31] op_sel_hi:[1,0]
	v_pk_mul_f32 v[124:125], v[124:125], v[30:31] op_sel_hi:[1,0]
	v_pk_fma_f32 v[0:1], v[148:149], v[122:123], v[106:107]
	v_pk_fma_f32 v[2:3], v[150:151], v[124:125], v[108:109]
	global_store_dwordx4 v[86:87], v[0:3], off offset:2048 sc1 nt
	v_pk_fma_f32 v[122:123], v[234:235], v[0:1], v[218:219]
	v_pk_fma_f32 v[124:125], v[236:237], v[2:3], v[220:221]
	s_nop 0
	v_cvt_pk_bf16_f32 v16, v122, v123
	v_cvt_pk_bf16_f32 v17, v124, v125
	global_store_dwordx2 v[88:89], v[16:17], off offset:1024 sc1
	v_pk_mul_f32 v[126:127], v[126:127], v[30:31] op_sel_hi:[1,0]
	v_pk_mul_f32 v[128:129], v[128:129], v[30:31] op_sel_hi:[1,0]
	v_pk_fma_f32 v[4:5], v[152:153], v[126:127], v[110:111]
	v_pk_fma_f32 v[6:7], v[154:155], v[128:129], v[112:113]
	global_store_dwordx4 v[86:87], v[4:7], off offset:3072 sc1 nt
	v_pk_fma_f32 v[126:127], v[238:239], v[4:5], v[222:223]
	v_pk_fma_f32 v[128:129], v[240:241], v[6:7], v[224:225]
	s_nop 0
	v_cvt_pk_bf16_f32 v18, v126, v127
	v_cvt_pk_bf16_f32 v19, v128, v129
	global_store_dwordx2 v[88:89], v[18:19], off offset:1536 sc1
	v_lshl_add_u64 v[86:87], v[86:87], 0, s[0:1]
	v_lshl_add_u64 v[88:89], v[88:89], 0, s[20:21]
	global_load_dwordx4 v[20:23], v[82:83], off nt
	global_load_dwordx4 v[24:27], v[82:83], off offset:1024 nt
	global_load_dwordx4 v[0:3], v[82:83], off offset:2048 nt
	global_load_dwordx4 v[4:7], v[82:83], off offset:3072 nt
	global_load_dwordx2 v[12:13], v[84:85], off
	global_load_dwordx2 v[14:15], v[84:85], off offset:512
	global_load_dwordx2 v[16:17], v[84:85], off offset:1024
	global_load_dwordx2 v[18:19], v[84:85], off offset:1536
	v_lshl_add_u64 v[82:83], v[82:83], 0, s[0:1]
	v_lshl_add_u64 v[84:85], v[84:85], 0, s[20:21]
	s_waitcnt vmcnt(32)
	v_lshlrev_b32_e32 v156, 16, v50
	v_and_b32_e32 v157, 0xffff0000, v50
	v_lshlrev_b32_e32 v50, 16, v51
	v_and_b32_e32 v51, 0xffff0000, v51
	v_lshlrev_b32_e32 v158, 16, v52
	v_and_b32_e32 v159, 0xffff0000, v52
	v_lshlrev_b32_e32 v52, 16, v53
	v_and_b32_e32 v53, 0xffff0000, v53
	v_lshlrev_b32_e32 v160, 16, v54
	v_and_b32_e32 v161, 0xffff0000, v54
	v_lshlrev_b32_e32 v54, 16, v55
	v_and_b32_e32 v55, 0xffff0000, v55
	v_lshlrev_b32_e32 v162, 16, v56
	v_and_b32_e32 v163, 0xffff0000, v56
	v_lshlrev_b32_e32 v56, 16, v57
	v_and_b32_e32 v57, 0xffff0000, v57
	v_pk_mul_f32 v[114:115], v[194:195], v[156:157]
	v_pk_mul_f32 v[116:117], v[196:197], v[50:51]
	v_pk_mul_f32 v[118:119], v[198:199], v[158:159]
	v_pk_mul_f32 v[120:121], v[200:201], v[52:53]
	v_pk_mul_f32 v[122:123], v[202:203], v[160:161]
	v_pk_mul_f32 v[124:125], v[204:205], v[54:55]
	v_pk_mul_f32 v[126:127], v[206:207], v[162:163]
	v_pk_mul_f32 v[128:129], v[208:209], v[56:57]
	v_pk_mul_f32 v[114:115], v[10:11], v[114:115]
	v_pk_mul_f32 v[116:117], v[10:11], v[116:117]
	v_pk_mul_f32 v[118:119], v[10:11], v[118:119]
	v_pk_mul_f32 v[120:121], v[10:11], v[120:121]
	v_pk_mul_f32 v[122:123], v[10:11], v[122:123]
	v_pk_mul_f32 v[124:125], v[10:11], v[124:125]
	v_pk_mul_f32 v[126:127], v[10:11], v[126:127]
	v_pk_mul_f32 v[128:129], v[10:11], v[128:129]
	v_pk_fma_f32 v[114:115], v[34:35], s[28:29], v[114:115] op_sel_hi:[1,0,1]
	v_pk_fma_f32 v[116:117], v[36:37], s[28:29], v[116:117] op_sel_hi:[1,0,1]
	v_pk_fma_f32 v[118:119], v[38:39], s[28:29], v[118:119] op_sel_hi:[1,0,1]
	v_pk_fma_f32 v[120:121], v[40:41], s[28:29], v[120:121] op_sel_hi:[1,0,1]
	v_pk_fma_f32 v[122:123], v[42:43], s[28:29], v[122:123] op_sel_hi:[1,0,1]
	v_pk_fma_f32 v[124:125], v[44:45], s[28:29], v[124:125] op_sel_hi:[1,0,1]
	v_pk_fma_f32 v[126:127], v[46:47], s[28:29], v[126:127] op_sel_hi:[1,0,1]
	v_pk_fma_f32 v[128:129], v[48:49], s[28:29], v[128:129] op_sel_hi:[1,0,1]
	v_add_f32_e32 v164, v114, v115
	v_add_f32_e32 v165, v116, v117
	v_add_f32_e32 v166, v118, v119
	v_add_f32_e32 v167, v120, v121
	v_add_f32_e32 v168, v122, v123
	v_add_f32_e32 v169, v124, v125
	v_add_f32_e32 v242, v126, v127
	v_add_f32_e32 v243, v128, v129
	v_add_f32_e32 v164, v164, v165
	v_add_f32_e32 v166, v166, v167
	v_add_f32_e32 v168, v168, v169
	v_add_f32_e32 v242, v242, v243
	v_add_f32_e32 v9, 0, v164
	v_add_f32_e32 v9, v9, v166
	v_add_f32_e32 v9, v9, v168
	v_add_f32_e32 v9, v9, v242
	ds_bpermute_b32 v28, v96, v9
	s_waitcnt lgkmcnt(0)
	v_add_f32_e32 v9, v9, v28
	ds_swizzle_b32 v28, v9 offset:swizzle(SWAP,16)
	s_waitcnt lgkmcnt(0)
	v_add_f32_e32 v9, v9, v28
	ds_swizzle_b32 v28, v9 offset:swizzle(SWAP,8)
	s_waitcnt lgkmcnt(0)
	v_add_f32_e32 v9, v9, v28
	ds_swizzle_b32 v28, v9 offset:swizzle(SWAP,4)
	s_waitcnt lgkmcnt(0)
	v_add_f32_e32 v9, v9, v28
	ds_swizzle_b32 v28, v9 offset:swizzle(SWAP,2)
	s_waitcnt lgkmcnt(0)
	v_add_f32_e32 v9, v9, v28
	ds_swizzle_b32 v28, v9 offset:swizzle(SWAP,1)
	s_waitcnt lgkmcnt(0)
	v_add_f32_e32 v9, v9, v28
	v_fmac_f32_e32 v114, 0xba800000, v9
	v_fmac_f32_e32 v115, 0xba800000, v9
	v_fmac_f32_e32 v116, 0xba800000, v9
	v_fmac_f32_e32 v117, 0xba800000, v9
	v_fmac_f32_e32 v118, 0xba800000, v9
	v_fmac_f32_e32 v119, 0xba800000, v9
	v_fmac_f32_e32 v120, 0xba800000, v9
	v_fmac_f32_e32 v121, 0xba800000, v9
	v_fmac_f32_e32 v122, 0xba800000, v9
	v_fmac_f32_e32 v123, 0xba800000, v9
	v_fmac_f32_e32 v124, 0xba800000, v9
	v_fmac_f32_e32 v125, 0xba800000, v9
	v_fmac_f32_e32 v126, 0xba800000, v9
	v_fmac_f32_e32 v127, 0xba800000, v9
	v_fmac_f32_e32 v128, 0xba800000, v9
	v_fmac_f32_e32 v129, 0xba800000, v9
	v_pk_mul_f32 v[244:245], v[114:115], v[114:115]
	v_pk_mul_f32 v[246:247], v[116:117], v[116:117]
	v_add_f32_e32 v244, v245, v244
	v_add_f32_e32 v246, v246, v247
	v_add_f32_e32 v164, v244, v246
	v_pk_mul_f32 v[244:245], v[118:119], v[118:119]
	v_pk_mul_f32 v[246:247], v[120:121], v[120:121]
	v_add_f32_e32 v244, v245, v244
	v_add_f32_e32 v246, v246, v247
	v_add_f32_e32 v165, v244, v246
	v_mul_f32_e32 v248, v122, v122
	v_mul_f32_e32 v249, v124, v124
	v_fmac_f32_e32 v248, v123, v123
	v_fmac_f32_e32 v249, v125, v125
	v_add_f32_e32 v166, v248, v249
	v_pk_mul_f32 v[244:245], v[126:127], v[126:127]
	v_pk_mul_f32 v[246:247], v[128:129], v[128:129]
	v_add_f32_e32 v244, v244, v245
	v_add_f32_e32 v246, v246, v247
	v_add_f32_e32 v167, v244, v246
	v_add_f32_e32 v164, v164, v165
	v_add_f32_e32 v164, v166, v164
	v_add_f32_e32 v9, v167, v164
	ds_bpermute_b32 v28, v96, v9
	s_waitcnt lgkmcnt(0)
	v_add_f32_e32 v9, v9, v28
	ds_swizzle_b32 v28, v9 offset:swizzle(SWAP,16)
	s_waitcnt lgkmcnt(0)
	v_add_f32_e32 v9, v9, v28
	ds_swizzle_b32 v28, v9 offset:swizzle(SWAP,8)
	s_waitcnt lgkmcnt(0)
	v_add_f32_e32 v9, v9, v28
	ds_swizzle_b32 v28, v9 offset:swizzle(SWAP,4)
	s_waitcnt lgkmcnt(0)
	v_add_f32_e32 v9, v9, v28
	ds_swizzle_b32 v28, v9 offset:swizzle(SWAP,2)
	s_waitcnt lgkmcnt(0)
	v_add_f32_e32 v9, v9, v28
	ds_swizzle_b32 v28, v9 offset:swizzle(SWAP,1)
	s_waitcnt lgkmcnt(0)
	v_add_f32_e32 v9, v9, v28
	v_mov_b32_e32 v28, 0x3727c5ac
	v_fmamk_f32 v9, v9, 0x3a800000, v28
	v_mul_f32_e32 v28, 0x4b800000, v9
	v_cmp_gt_f32_e32 vcc, s37, v9
	s_nop 1
	v_cndmask_b32_e32 v9, v9, v28, vcc
	v_rsq_f32_e32 v9, v9
	s_nop 0
	v_mul_f32_e32 v28, 0x45800000, v9
	v_cndmask_b32_e32 v30, v9, v28, vcc
	v_pk_mul_f32 v[114:115], v[114:115], v[30:31] op_sel_hi:[1,0]
	v_pk_mul_f32 v[116:117], v[116:117], v[30:31] op_sel_hi:[1,0]
	v_pk_fma_f32 v[34:35], v[140:141], v[114:115], v[98:99]
	v_pk_fma_f32 v[36:37], v[142:143], v[116:117], v[100:101]
	global_store_dwordx4 v[86:87], v[34:37], off sc1 nt
	v_pk_fma_f32 v[114:115], v[226:227], v[34:35], v[210:211]
	v_pk_fma_f32 v[116:117], v[228:229], v[36:37], v[212:213]
	s_nop 0
	v_cvt_pk_bf16_f32 v50, v114, v115
	v_cvt_pk_bf16_f32 v51, v116, v117
	global_store_dwordx2 v[88:89], v[50:51], off sc1
	v_pk_mul_f32 v[118:119], v[118:119], v[30:31] op_sel_hi:[1,0]
	v_pk_mul_f32 v[120:121], v[120:121], v[30:31] op_sel_hi:[1,0]
	v_pk_fma_f32 v[38:39], v[144:145], v[118:119], v[102:103]
	v_pk_fma_f32 v[40:41], v[146:147], v[120:121], v[104:105]
	global_store_dwordx4 v[86:87], v[38:41], off offset:1024 sc1 nt
	v_pk_fma_f32 v[118:119], v[230:231], v[38:39], v[214:215]
	v_pk_fma_f32 v[120:121], v[232:233], v[40:41], v[216:217]
	s_nop 0
	v_cvt_pk_bf16_f32 v52, v118, v119
	v_cvt_pk_bf16_f32 v53, v120, v121
	global_store_dwordx2 v[88:89], v[52:53], off offset:512 sc1
	v_pk_mul_f32 v[122:123], v[122:123], v[30:31] op_sel_hi:[1,0]
	v_pk_mul_f32 v[124:125], v[124:125], v[30:31] op_sel_hi:[1,0]
	v_pk_fma_f32 v[42:43], v[148:149], v[122:123], v[106:107]
	v_pk_fma_f32 v[44:45], v[150:151], v[124:125], v[108:109]
	global_store_dwordx4 v[86:87], v[42:45], off offset:2048 sc1 nt
	v_pk_fma_f32 v[122:123], v[234:235], v[42:43], v[218:219]
	v_pk_fma_f32 v[124:125], v[236:237], v[44:45], v[220:221]
	s_nop 0
	v_cvt_pk_bf16_f32 v54, v122, v123
	v_cvt_pk_bf16_f32 v55, v124, v125
	global_store_dwordx2 v[88:89], v[54:55], off offset:1024 sc1
	v_pk_mul_f32 v[126:127], v[126:127], v[30:31] op_sel_hi:[1,0]
	v_pk_mul_f32 v[128:129], v[128:129], v[30:31] op_sel_hi:[1,0]
	v_pk_fma_f32 v[46:47], v[152:153], v[126:127], v[110:111]
	v_pk_fma_f32 v[48:49], v[154:155], v[128:129], v[112:113]
	global_store_dwordx4 v[86:87], v[46:49], off offset:3072 sc1 nt
	v_pk_fma_f32 v[126:127], v[238:239], v[46:47], v[222:223]
	v_pk_fma_f32 v[128:129], v[240:241], v[48:49], v[224:225]
	s_nop 0
	v_cvt_pk_bf16_f32 v56, v126, v127
	v_cvt_pk_bf16_f32 v57, v128, v129
	global_store_dwordx2 v[88:89], v[56:57], off offset:1536 sc1
	v_lshl_add_u64 v[86:87], v[86:87], 0, s[0:1]
	v_lshl_add_u64 v[88:89], v[88:89], 0, s[20:21]
	global_load_dwordx4 v[34:37], v[82:83], off nt
	global_load_dwordx4 v[38:41], v[82:83], off offset:1024 nt
	global_load_dwordx4 v[42:45], v[82:83], off offset:2048 nt
	global_load_dwordx4 v[46:49], v[82:83], off offset:3072 nt
	global_load_dwordx2 v[50:51], v[84:85], off
	global_load_dwordx2 v[52:53], v[84:85], off offset:512
	global_load_dwordx2 v[54:55], v[84:85], off offset:1024
	global_load_dwordx2 v[56:57], v[84:85], off offset:1536
	v_lshl_add_u64 v[82:83], v[82:83], 0, s[0:1]
	v_lshl_add_u64 v[84:85], v[84:85], 0, s[20:21]
	s_waitcnt vmcnt(32)
	v_lshlrev_b32_e32 v156, 16, v74
	v_and_b32_e32 v157, 0xffff0000, v74
	v_lshlrev_b32_e32 v74, 16, v75
	v_and_b32_e32 v75, 0xffff0000, v75
	v_lshlrev_b32_e32 v158, 16, v76
	v_and_b32_e32 v159, 0xffff0000, v76
	v_lshlrev_b32_e32 v76, 16, v77
	v_and_b32_e32 v77, 0xffff0000, v77
	v_lshlrev_b32_e32 v160, 16, v78
	v_and_b32_e32 v161, 0xffff0000, v78
	v_lshlrev_b32_e32 v78, 16, v79
	v_and_b32_e32 v79, 0xffff0000, v79
	v_lshlrev_b32_e32 v162, 16, v80
	v_and_b32_e32 v163, 0xffff0000, v80
	v_lshlrev_b32_e32 v80, 16, v81
	v_and_b32_e32 v81, 0xffff0000, v81
	v_pk_mul_f32 v[114:115], v[194:195], v[156:157]
	v_pk_mul_f32 v[116:117], v[196:197], v[74:75]
	v_pk_mul_f32 v[118:119], v[198:199], v[158:159]
	v_pk_mul_f32 v[120:121], v[200:201], v[76:77]
	v_pk_mul_f32 v[122:123], v[202:203], v[160:161]
	v_pk_mul_f32 v[124:125], v[204:205], v[78:79]
	v_pk_mul_f32 v[126:127], v[206:207], v[162:163]
	v_pk_mul_f32 v[128:129], v[208:209], v[80:81]
	v_pk_mul_f32 v[114:115], v[10:11], v[114:115]
	v_pk_mul_f32 v[116:117], v[10:11], v[116:117]
	v_pk_mul_f32 v[118:119], v[10:11], v[118:119]
	v_pk_mul_f32 v[120:121], v[10:11], v[120:121]
	v_pk_mul_f32 v[122:123], v[10:11], v[122:123]
	v_pk_mul_f32 v[124:125], v[10:11], v[124:125]
	v_pk_mul_f32 v[126:127], v[10:11], v[126:127]
	v_pk_mul_f32 v[128:129], v[10:11], v[128:129]
	v_pk_fma_f32 v[114:115], v[58:59], s[28:29], v[114:115] op_sel_hi:[1,0,1]
	v_pk_fma_f32 v[116:117], v[60:61], s[28:29], v[116:117] op_sel_hi:[1,0,1]
	v_pk_fma_f32 v[118:119], v[62:63], s[28:29], v[118:119] op_sel_hi:[1,0,1]
	v_pk_fma_f32 v[120:121], v[64:65], s[28:29], v[120:121] op_sel_hi:[1,0,1]
	v_pk_fma_f32 v[122:123], v[66:67], s[28:29], v[122:123] op_sel_hi:[1,0,1]
	v_pk_fma_f32 v[124:125], v[68:69], s[28:29], v[124:125] op_sel_hi:[1,0,1]
	v_pk_fma_f32 v[126:127], v[70:71], s[28:29], v[126:127] op_sel_hi:[1,0,1]
	v_pk_fma_f32 v[128:129], v[72:73], s[28:29], v[128:129] op_sel_hi:[1,0,1]
	v_add_f32_e32 v164, v114, v115
	v_add_f32_e32 v165, v116, v117
	v_add_f32_e32 v166, v118, v119
	v_add_f32_e32 v167, v120, v121
	v_add_f32_e32 v168, v122, v123
	v_add_f32_e32 v169, v124, v125
	v_add_f32_e32 v242, v126, v127
	v_add_f32_e32 v243, v128, v129
	v_add_f32_e32 v164, v164, v165
	v_add_f32_e32 v166, v166, v167
	v_add_f32_e32 v168, v168, v169
	v_add_f32_e32 v242, v242, v243
	v_add_f32_e32 v9, 0, v164
	v_add_f32_e32 v9, v9, v166
	v_add_f32_e32 v9, v9, v168
	v_add_f32_e32 v9, v9, v242
	ds_bpermute_b32 v28, v96, v9
	s_waitcnt lgkmcnt(0)
	v_add_f32_e32 v9, v9, v28
	ds_swizzle_b32 v28, v9 offset:swizzle(SWAP,16)
	s_waitcnt lgkmcnt(0)
	v_add_f32_e32 v9, v9, v28
	ds_swizzle_b32 v28, v9 offset:swizzle(SWAP,8)
	s_waitcnt lgkmcnt(0)
	v_add_f32_e32 v9, v9, v28
	ds_swizzle_b32 v28, v9 offset:swizzle(SWAP,4)
	s_waitcnt lgkmcnt(0)
	v_add_f32_e32 v9, v9, v28
	ds_swizzle_b32 v28, v9 offset:swizzle(SWAP,2)
	s_waitcnt lgkmcnt(0)
	v_add_f32_e32 v9, v9, v28
	ds_swizzle_b32 v28, v9 offset:swizzle(SWAP,1)
	s_waitcnt lgkmcnt(0)
	v_add_f32_e32 v9, v9, v28
	v_fmac_f32_e32 v114, 0xba800000, v9
	v_fmac_f32_e32 v115, 0xba800000, v9
	v_fmac_f32_e32 v116, 0xba800000, v9
	v_fmac_f32_e32 v117, 0xba800000, v9
	v_fmac_f32_e32 v118, 0xba800000, v9
	v_fmac_f32_e32 v119, 0xba800000, v9
	v_fmac_f32_e32 v120, 0xba800000, v9
	v_fmac_f32_e32 v121, 0xba800000, v9
	v_fmac_f32_e32 v122, 0xba800000, v9
	v_fmac_f32_e32 v123, 0xba800000, v9
	v_fmac_f32_e32 v124, 0xba800000, v9
	v_fmac_f32_e32 v125, 0xba800000, v9
	v_fmac_f32_e32 v126, 0xba800000, v9
	v_fmac_f32_e32 v127, 0xba800000, v9
	v_fmac_f32_e32 v128, 0xba800000, v9
	v_fmac_f32_e32 v129, 0xba800000, v9
	v_pk_mul_f32 v[244:245], v[114:115], v[114:115]
	v_pk_mul_f32 v[246:247], v[116:117], v[116:117]
	v_add_f32_e32 v244, v245, v244
	v_add_f32_e32 v246, v246, v247
	v_add_f32_e32 v164, v244, v246
	v_pk_mul_f32 v[244:245], v[118:119], v[118:119]
	v_pk_mul_f32 v[246:247], v[120:121], v[120:121]
	v_add_f32_e32 v244, v245, v244
	v_add_f32_e32 v246, v246, v247
	v_add_f32_e32 v165, v244, v246
	v_mul_f32_e32 v248, v122, v122
	v_mul_f32_e32 v249, v124, v124
	v_fmac_f32_e32 v248, v123, v123
	v_fmac_f32_e32 v249, v125, v125
	v_add_f32_e32 v166, v248, v249
	v_pk_mul_f32 v[244:245], v[126:127], v[126:127]
	v_pk_mul_f32 v[246:247], v[128:129], v[128:129]
	v_add_f32_e32 v244, v244, v245
	v_add_f32_e32 v246, v246, v247
	v_add_f32_e32 v167, v244, v246
	v_add_f32_e32 v164, v164, v165
	v_add_f32_e32 v164, v166, v164
	v_add_f32_e32 v9, v167, v164
	ds_bpermute_b32 v28, v96, v9
	s_waitcnt lgkmcnt(0)
	v_add_f32_e32 v9, v9, v28
	ds_swizzle_b32 v28, v9 offset:swizzle(SWAP,16)
	s_waitcnt lgkmcnt(0)
	v_add_f32_e32 v9, v9, v28
	ds_swizzle_b32 v28, v9 offset:swizzle(SWAP,8)
	s_waitcnt lgkmcnt(0)
	v_add_f32_e32 v9, v9, v28
	ds_swizzle_b32 v28, v9 offset:swizzle(SWAP,4)
	s_waitcnt lgkmcnt(0)
	v_add_f32_e32 v9, v9, v28
	ds_swizzle_b32 v28, v9 offset:swizzle(SWAP,2)
	s_waitcnt lgkmcnt(0)
	v_add_f32_e32 v9, v9, v28
	ds_swizzle_b32 v28, v9 offset:swizzle(SWAP,1)
	s_waitcnt lgkmcnt(0)
	v_add_f32_e32 v9, v9, v28
	v_mov_b32_e32 v28, 0x3727c5ac
	v_fmamk_f32 v9, v9, 0x3a800000, v28
	v_mul_f32_e32 v28, 0x4b800000, v9
	v_cmp_gt_f32_e32 vcc, s37, v9
	s_nop 1
	v_cndmask_b32_e32 v9, v9, v28, vcc
	v_rsq_f32_e32 v9, v9
	s_nop 0
	v_mul_f32_e32 v28, 0x45800000, v9
	v_cndmask_b32_e32 v30, v9, v28, vcc
	v_pk_mul_f32 v[114:115], v[114:115], v[30:31] op_sel_hi:[1,0]
	v_pk_mul_f32 v[116:117], v[116:117], v[30:31] op_sel_hi:[1,0]
	v_pk_fma_f32 v[58:59], v[140:141], v[114:115], v[98:99]
	v_pk_fma_f32 v[60:61], v[142:143], v[116:117], v[100:101]
	global_store_dwordx4 v[86:87], v[58:61], off sc1 nt
	v_pk_fma_f32 v[114:115], v[226:227], v[58:59], v[210:211]
	v_pk_fma_f32 v[116:117], v[228:229], v[60:61], v[212:213]
	s_nop 0
	v_cvt_pk_bf16_f32 v74, v114, v115
	v_cvt_pk_bf16_f32 v75, v116, v117
	global_store_dwordx2 v[88:89], v[74:75], off sc1
	v_pk_mul_f32 v[118:119], v[118:119], v[30:31] op_sel_hi:[1,0]
	v_pk_mul_f32 v[120:121], v[120:121], v[30:31] op_sel_hi:[1,0]
	v_pk_fma_f32 v[62:63], v[144:145], v[118:119], v[102:103]
	v_pk_fma_f32 v[64:65], v[146:147], v[120:121], v[104:105]
	global_store_dwordx4 v[86:87], v[62:65], off offset:1024 sc1 nt
	v_pk_fma_f32 v[118:119], v[230:231], v[62:63], v[214:215]
	v_pk_fma_f32 v[120:121], v[232:233], v[64:65], v[216:217]
	s_nop 0
	v_cvt_pk_bf16_f32 v76, v118, v119
	v_cvt_pk_bf16_f32 v77, v120, v121
	global_store_dwordx2 v[88:89], v[76:77], off offset:512 sc1
	v_pk_mul_f32 v[122:123], v[122:123], v[30:31] op_sel_hi:[1,0]
	v_pk_mul_f32 v[124:125], v[124:125], v[30:31] op_sel_hi:[1,0]
	v_pk_fma_f32 v[66:67], v[148:149], v[122:123], v[106:107]
	v_pk_fma_f32 v[68:69], v[150:151], v[124:125], v[108:109]
	global_store_dwordx4 v[86:87], v[66:69], off offset:2048 sc1 nt
	v_pk_fma_f32 v[122:123], v[234:235], v[66:67], v[218:219]
	v_pk_fma_f32 v[124:125], v[236:237], v[68:69], v[220:221]
	s_nop 0
	v_cvt_pk_bf16_f32 v78, v122, v123
	v_cvt_pk_bf16_f32 v79, v124, v125
	global_store_dwordx2 v[88:89], v[78:79], off offset:1024 sc1
	v_pk_mul_f32 v[126:127], v[126:127], v[30:31] op_sel_hi:[1,0]
	v_pk_mul_f32 v[128:129], v[128:129], v[30:31] op_sel_hi:[1,0]
	v_pk_fma_f32 v[70:71], v[152:153], v[126:127], v[110:111]
	v_pk_fma_f32 v[72:73], v[154:155], v[128:129], v[112:113]
	global_store_dwordx4 v[86:87], v[70:73], off offset:3072 sc1 nt
	v_pk_fma_f32 v[126:127], v[238:239], v[70:71], v[222:223]
	v_pk_fma_f32 v[128:129], v[240:241], v[72:73], v[224:225]
	s_nop 0
	v_cvt_pk_bf16_f32 v80, v126, v127
	v_cvt_pk_bf16_f32 v81, v128, v129
	global_store_dwordx2 v[88:89], v[80:81], off offset:1536 sc1
	v_lshl_add_u64 v[86:87], v[86:87], 0, s[0:1]
	v_lshl_add_u64 v[88:89], v[88:89], 0, s[20:21]
	global_load_dwordx4 v[58:61], v[82:83], off nt
	global_load_dwordx4 v[62:65], v[82:83], off offset:1024 nt
	global_load_dwordx4 v[66:69], v[82:83], off offset:2048 nt
	global_load_dwordx4 v[70:73], v[82:83], off offset:3072 nt
	global_load_dwordx2 v[74:75], v[84:85], off
	global_load_dwordx2 v[76:77], v[84:85], off offset:512
	global_load_dwordx2 v[78:79], v[84:85], off offset:1024
	global_load_dwordx2 v[80:81], v[84:85], off offset:1536
	v_lshl_add_u64 v[82:83], v[82:83], 0, s[0:1]
	v_lshl_add_u64 v[84:85], v[84:85], 0, s[20:21]
	s_waitcnt vmcnt(32)
	v_lshlrev_b32_e32 v156, 16, v12
	v_and_b32_e32 v157, 0xffff0000, v12
	v_lshlrev_b32_e32 v12, 16, v13
	v_and_b32_e32 v13, 0xffff0000, v13
	v_lshlrev_b32_e32 v158, 16, v14
	v_and_b32_e32 v159, 0xffff0000, v14
	v_lshlrev_b32_e32 v14, 16, v15
	v_and_b32_e32 v15, 0xffff0000, v15
	v_lshlrev_b32_e32 v160, 16, v16
	v_and_b32_e32 v161, 0xffff0000, v16
	v_lshlrev_b32_e32 v16, 16, v17
	v_and_b32_e32 v17, 0xffff0000, v17
	v_lshlrev_b32_e32 v162, 16, v18
	v_and_b32_e32 v163, 0xffff0000, v18
	v_lshlrev_b32_e32 v18, 16, v19
	v_and_b32_e32 v19, 0xffff0000, v19
	v_pk_mul_f32 v[114:115], v[194:195], v[156:157]
	v_pk_mul_f32 v[116:117], v[196:197], v[12:13]
	v_pk_mul_f32 v[118:119], v[198:199], v[158:159]
	v_pk_mul_f32 v[120:121], v[200:201], v[14:15]
	v_pk_mul_f32 v[122:123], v[202:203], v[160:161]
	v_pk_mul_f32 v[124:125], v[204:205], v[16:17]
	v_pk_mul_f32 v[126:127], v[206:207], v[162:163]
	v_pk_mul_f32 v[128:129], v[208:209], v[18:19]
	v_pk_mul_f32 v[114:115], v[10:11], v[114:115]
	v_pk_mul_f32 v[116:117], v[10:11], v[116:117]
	v_pk_mul_f32 v[118:119], v[10:11], v[118:119]
	v_pk_mul_f32 v[120:121], v[10:11], v[120:121]
	v_pk_mul_f32 v[122:123], v[10:11], v[122:123]
	v_pk_mul_f32 v[124:125], v[10:11], v[124:125]
	v_pk_mul_f32 v[126:127], v[10:11], v[126:127]
	v_pk_mul_f32 v[128:129], v[10:11], v[128:129]
	v_pk_fma_f32 v[114:115], v[20:21], s[28:29], v[114:115] op_sel_hi:[1,0,1]
	v_pk_fma_f32 v[116:117], v[22:23], s[28:29], v[116:117] op_sel_hi:[1,0,1]
	v_pk_fma_f32 v[118:119], v[24:25], s[28:29], v[118:119] op_sel_hi:[1,0,1]
	v_pk_fma_f32 v[120:121], v[26:27], s[28:29], v[120:121] op_sel_hi:[1,0,1]
	v_pk_fma_f32 v[122:123], v[0:1], s[28:29], v[122:123] op_sel_hi:[1,0,1]
	v_pk_fma_f32 v[124:125], v[2:3], s[28:29], v[124:125] op_sel_hi:[1,0,1]
	v_pk_fma_f32 v[126:127], v[4:5], s[28:29], v[126:127] op_sel_hi:[1,0,1]
	v_pk_fma_f32 v[128:129], v[6:7], s[28:29], v[128:129] op_sel_hi:[1,0,1]
	v_add_f32_e32 v164, v114, v115
	v_add_f32_e32 v165, v116, v117
	v_add_f32_e32 v166, v118, v119
	v_add_f32_e32 v167, v120, v121
	v_add_f32_e32 v168, v122, v123
	v_add_f32_e32 v169, v124, v125
	v_add_f32_e32 v242, v126, v127
	v_add_f32_e32 v243, v128, v129
	v_add_f32_e32 v164, v164, v165
	v_add_f32_e32 v166, v166, v167
	v_add_f32_e32 v168, v168, v169
	v_add_f32_e32 v242, v242, v243
	v_add_f32_e32 v9, 0, v164
	v_add_f32_e32 v9, v9, v166
	v_add_f32_e32 v9, v9, v168
	v_add_f32_e32 v9, v9, v242
	ds_bpermute_b32 v28, v96, v9
	s_waitcnt lgkmcnt(0)
	v_add_f32_e32 v9, v9, v28
	ds_swizzle_b32 v28, v9 offset:swizzle(SWAP,16)
	s_waitcnt lgkmcnt(0)
	v_add_f32_e32 v9, v9, v28
	ds_swizzle_b32 v28, v9 offset:swizzle(SWAP,8)
	s_waitcnt lgkmcnt(0)
	v_add_f32_e32 v9, v9, v28
	ds_swizzle_b32 v28, v9 offset:swizzle(SWAP,4)
	s_waitcnt lgkmcnt(0)
	v_add_f32_e32 v9, v9, v28
	ds_swizzle_b32 v28, v9 offset:swizzle(SWAP,2)
	s_waitcnt lgkmcnt(0)
	v_add_f32_e32 v9, v9, v28
	ds_swizzle_b32 v28, v9 offset:swizzle(SWAP,1)
	s_waitcnt lgkmcnt(0)
	v_add_f32_e32 v9, v9, v28
	v_fmac_f32_e32 v114, 0xba800000, v9
	v_fmac_f32_e32 v115, 0xba800000, v9
	v_fmac_f32_e32 v116, 0xba800000, v9
	v_fmac_f32_e32 v117, 0xba800000, v9
	v_fmac_f32_e32 v118, 0xba800000, v9
	v_fmac_f32_e32 v119, 0xba800000, v9
	v_fmac_f32_e32 v120, 0xba800000, v9
	v_fmac_f32_e32 v121, 0xba800000, v9
	v_fmac_f32_e32 v122, 0xba800000, v9
	v_fmac_f32_e32 v123, 0xba800000, v9
	v_fmac_f32_e32 v124, 0xba800000, v9
	v_fmac_f32_e32 v125, 0xba800000, v9
	v_fmac_f32_e32 v126, 0xba800000, v9
	v_fmac_f32_e32 v127, 0xba800000, v9
	v_fmac_f32_e32 v128, 0xba800000, v9
	v_fmac_f32_e32 v129, 0xba800000, v9
	v_pk_mul_f32 v[244:245], v[114:115], v[114:115]
	v_pk_mul_f32 v[246:247], v[116:117], v[116:117]
	v_add_f32_e32 v244, v245, v244
	v_add_f32_e32 v246, v246, v247
	v_add_f32_e32 v164, v244, v246
	v_pk_mul_f32 v[244:245], v[118:119], v[118:119]
	v_pk_mul_f32 v[246:247], v[120:121], v[120:121]
	v_add_f32_e32 v244, v245, v244
	v_add_f32_e32 v246, v246, v247
	v_add_f32_e32 v165, v244, v246
	v_mul_f32_e32 v248, v122, v122
	v_mul_f32_e32 v249, v124, v124
	v_fmac_f32_e32 v248, v123, v123
	v_fmac_f32_e32 v249, v125, v125
	v_add_f32_e32 v166, v248, v249
	v_pk_mul_f32 v[244:245], v[126:127], v[126:127]
	v_pk_mul_f32 v[246:247], v[128:129], v[128:129]
	v_add_f32_e32 v244, v244, v245
	v_add_f32_e32 v246, v246, v247
	v_add_f32_e32 v167, v244, v246
	v_add_f32_e32 v164, v164, v165
	v_add_f32_e32 v164, v166, v164
	v_add_f32_e32 v9, v167, v164
	ds_bpermute_b32 v28, v96, v9
	s_waitcnt lgkmcnt(0)
	v_add_f32_e32 v9, v9, v28
	ds_swizzle_b32 v28, v9 offset:swizzle(SWAP,16)
	s_waitcnt lgkmcnt(0)
	v_add_f32_e32 v9, v9, v28
	ds_swizzle_b32 v28, v9 offset:swizzle(SWAP,8)
	s_waitcnt lgkmcnt(0)
	v_add_f32_e32 v9, v9, v28
	ds_swizzle_b32 v28, v9 offset:swizzle(SWAP,4)
	s_waitcnt lgkmcnt(0)
	v_add_f32_e32 v9, v9, v28
	ds_swizzle_b32 v28, v9 offset:swizzle(SWAP,2)
	s_waitcnt lgkmcnt(0)
	v_add_f32_e32 v9, v9, v28
	ds_swizzle_b32 v28, v9 offset:swizzle(SWAP,1)
	s_waitcnt lgkmcnt(0)
	v_add_f32_e32 v9, v9, v28
	v_mov_b32_e32 v28, 0x3727c5ac
	v_fmamk_f32 v9, v9, 0x3a800000, v28
	v_mul_f32_e32 v28, 0x4b800000, v9
	v_cmp_gt_f32_e32 vcc, s37, v9
	s_nop 1
	v_cndmask_b32_e32 v9, v9, v28, vcc
	v_rsq_f32_e32 v9, v9
	s_nop 0
	v_mul_f32_e32 v28, 0x45800000, v9
	v_cndmask_b32_e32 v30, v9, v28, vcc
	v_pk_mul_f32 v[114:115], v[114:115], v[30:31] op_sel_hi:[1,0]
	v_pk_mul_f32 v[116:117], v[116:117], v[30:31] op_sel_hi:[1,0]
	v_pk_fma_f32 v[20:21], v[140:141], v[114:115], v[98:99]
	v_pk_fma_f32 v[22:23], v[142:143], v[116:117], v[100:101]
	global_store_dwordx4 v[86:87], v[20:23], off sc1 nt
	v_pk_fma_f32 v[114:115], v[226:227], v[20:21], v[210:211]
	v_pk_fma_f32 v[116:117], v[228:229], v[22:23], v[212:213]
	s_nop 0
	v_cvt_pk_bf16_f32 v12, v114, v115
	v_cvt_pk_bf16_f32 v13, v116, v117
	global_store_dwordx2 v[88:89], v[12:13], off sc1
	v_pk_mul_f32 v[118:119], v[118:119], v[30:31] op_sel_hi:[1,0]
	v_pk_mul_f32 v[120:121], v[120:121], v[30:31] op_sel_hi:[1,0]
	v_pk_fma_f32 v[24:25], v[144:145], v[118:119], v[102:103]
	v_pk_fma_f32 v[26:27], v[146:147], v[120:121], v[104:105]
	global_store_dwordx4 v[86:87], v[24:27], off offset:1024 sc1 nt
	v_pk_fma_f32 v[118:119], v[230:231], v[24:25], v[214:215]
	v_pk_fma_f32 v[120:121], v[232:233], v[26:27], v[216:217]
	s_nop 0
	v_cvt_pk_bf16_f32 v14, v118, v119
	v_cvt_pk_bf16_f32 v15, v120, v121
	global_store_dwordx2 v[88:89], v[14:15], off offset:512 sc1
	v_pk_mul_f32 v[122:123], v[122:123], v[30:31] op_sel_hi:[1,0]
	v_pk_mul_f32 v[124:125], v[124:125], v[30:31] op_sel_hi:[1,0]
	v_pk_fma_f32 v[0:1], v[148:149], v[122:123], v[106:107]
	v_pk_fma_f32 v[2:3], v[150:151], v[124:125], v[108:109]
	global_store_dwordx4 v[86:87], v[0:3], off offset:2048 sc1 nt
	v_pk_fma_f32 v[122:123], v[234:235], v[0:1], v[218:219]
	v_pk_fma_f32 v[124:125], v[236:237], v[2:3], v[220:221]
	s_nop 0
	v_cvt_pk_bf16_f32 v16, v122, v123
	v_cvt_pk_bf16_f32 v17, v124, v125
	global_store_dwordx2 v[88:89], v[16:17], off offset:1024 sc1
	v_pk_mul_f32 v[126:127], v[126:127], v[30:31] op_sel_hi:[1,0]
	v_pk_mul_f32 v[128:129], v[128:129], v[30:31] op_sel_hi:[1,0]
	v_pk_fma_f32 v[4:5], v[152:153], v[126:127], v[110:111]
	v_pk_fma_f32 v[6:7], v[154:155], v[128:129], v[112:113]
	global_store_dwordx4 v[86:87], v[4:7], off offset:3072 sc1 nt
	v_pk_fma_f32 v[126:127], v[238:239], v[4:5], v[222:223]
	v_pk_fma_f32 v[128:129], v[240:241], v[6:7], v[224:225]
	s_nop 0
	v_cvt_pk_bf16_f32 v18, v126, v127
	v_cvt_pk_bf16_f32 v19, v128, v129
	global_store_dwordx2 v[88:89], v[18:19], off offset:1536 sc1
	v_lshl_add_u64 v[86:87], v[86:87], 0, s[0:1]
	v_lshl_add_u64 v[88:89], v[88:89], 0, s[20:21]
	global_load_dwordx4 v[20:23], v[82:83], off nt
	global_load_dwordx4 v[24:27], v[82:83], off offset:1024 nt
	global_load_dwordx4 v[0:3], v[82:83], off offset:2048 nt
	global_load_dwordx4 v[4:7], v[82:83], off offset:3072 nt
	global_load_dwordx2 v[12:13], v[84:85], off
	global_load_dwordx2 v[14:15], v[84:85], off offset:512
	global_load_dwordx2 v[16:17], v[84:85], off offset:1024
	global_load_dwordx2 v[18:19], v[84:85], off offset:1536
	v_lshl_add_u64 v[82:83], v[82:83], 0, s[0:1]
	v_lshl_add_u64 v[84:85], v[84:85], 0, s[20:21]
	s_waitcnt vmcnt(32)
	v_lshlrev_b32_e32 v156, 16, v50
	v_and_b32_e32 v157, 0xffff0000, v50
	v_lshlrev_b32_e32 v50, 16, v51
	v_and_b32_e32 v51, 0xffff0000, v51
	v_lshlrev_b32_e32 v158, 16, v52
	v_and_b32_e32 v159, 0xffff0000, v52
	v_lshlrev_b32_e32 v52, 16, v53
	v_and_b32_e32 v53, 0xffff0000, v53
	v_lshlrev_b32_e32 v160, 16, v54
	v_and_b32_e32 v161, 0xffff0000, v54
	v_lshlrev_b32_e32 v54, 16, v55
	v_and_b32_e32 v55, 0xffff0000, v55
	v_lshlrev_b32_e32 v162, 16, v56
	v_and_b32_e32 v163, 0xffff0000, v56
	v_lshlrev_b32_e32 v56, 16, v57
	v_and_b32_e32 v57, 0xffff0000, v57
	v_pk_mul_f32 v[114:115], v[194:195], v[156:157]
	v_pk_mul_f32 v[116:117], v[196:197], v[50:51]
	v_pk_mul_f32 v[118:119], v[198:199], v[158:159]
	v_pk_mul_f32 v[120:121], v[200:201], v[52:53]
	v_pk_mul_f32 v[122:123], v[202:203], v[160:161]
	v_pk_mul_f32 v[124:125], v[204:205], v[54:55]
	v_pk_mul_f32 v[126:127], v[206:207], v[162:163]
	v_pk_mul_f32 v[128:129], v[208:209], v[56:57]
	v_pk_mul_f32 v[114:115], v[10:11], v[114:115]
	v_pk_mul_f32 v[116:117], v[10:11], v[116:117]
	v_pk_mul_f32 v[118:119], v[10:11], v[118:119]
	v_pk_mul_f32 v[120:121], v[10:11], v[120:121]
	v_pk_mul_f32 v[122:123], v[10:11], v[122:123]
	v_pk_mul_f32 v[124:125], v[10:11], v[124:125]
	v_pk_mul_f32 v[126:127], v[10:11], v[126:127]
	v_pk_mul_f32 v[128:129], v[10:11], v[128:129]
	v_pk_fma_f32 v[114:115], v[34:35], s[28:29], v[114:115] op_sel_hi:[1,0,1]
	v_pk_fma_f32 v[116:117], v[36:37], s[28:29], v[116:117] op_sel_hi:[1,0,1]
	v_pk_fma_f32 v[118:119], v[38:39], s[28:29], v[118:119] op_sel_hi:[1,0,1]
	v_pk_fma_f32 v[120:121], v[40:41], s[28:29], v[120:121] op_sel_hi:[1,0,1]
	v_pk_fma_f32 v[122:123], v[42:43], s[28:29], v[122:123] op_sel_hi:[1,0,1]
	v_pk_fma_f32 v[124:125], v[44:45], s[28:29], v[124:125] op_sel_hi:[1,0,1]
	v_pk_fma_f32 v[126:127], v[46:47], s[28:29], v[126:127] op_sel_hi:[1,0,1]
	v_pk_fma_f32 v[128:129], v[48:49], s[28:29], v[128:129] op_sel_hi:[1,0,1]
	v_add_f32_e32 v164, v114, v115
	v_add_f32_e32 v165, v116, v117
	v_add_f32_e32 v166, v118, v119
	v_add_f32_e32 v167, v120, v121
	v_add_f32_e32 v168, v122, v123
	v_add_f32_e32 v169, v124, v125
	v_add_f32_e32 v242, v126, v127
	v_add_f32_e32 v243, v128, v129
	v_add_f32_e32 v164, v164, v165
	v_add_f32_e32 v166, v166, v167
	v_add_f32_e32 v168, v168, v169
	v_add_f32_e32 v242, v242, v243
	v_add_f32_e32 v9, 0, v164
	v_add_f32_e32 v9, v9, v166
	v_add_f32_e32 v9, v9, v168
	v_add_f32_e32 v9, v9, v242
	ds_bpermute_b32 v28, v96, v9
	s_waitcnt lgkmcnt(0)
	v_add_f32_e32 v9, v9, v28
	ds_swizzle_b32 v28, v9 offset:swizzle(SWAP,16)
	s_waitcnt lgkmcnt(0)
	v_add_f32_e32 v9, v9, v28
	ds_swizzle_b32 v28, v9 offset:swizzle(SWAP,8)
	s_waitcnt lgkmcnt(0)
	v_add_f32_e32 v9, v9, v28
	ds_swizzle_b32 v28, v9 offset:swizzle(SWAP,4)
	s_waitcnt lgkmcnt(0)
	v_add_f32_e32 v9, v9, v28
	ds_swizzle_b32 v28, v9 offset:swizzle(SWAP,2)
	s_waitcnt lgkmcnt(0)
	v_add_f32_e32 v9, v9, v28
	ds_swizzle_b32 v28, v9 offset:swizzle(SWAP,1)
	s_waitcnt lgkmcnt(0)
	v_add_f32_e32 v9, v9, v28
	v_fmac_f32_e32 v114, 0xba800000, v9
	v_fmac_f32_e32 v115, 0xba800000, v9
	v_fmac_f32_e32 v116, 0xba800000, v9
	v_fmac_f32_e32 v117, 0xba800000, v9
	v_fmac_f32_e32 v118, 0xba800000, v9
	v_fmac_f32_e32 v119, 0xba800000, v9
	v_fmac_f32_e32 v120, 0xba800000, v9
	v_fmac_f32_e32 v121, 0xba800000, v9
	v_fmac_f32_e32 v122, 0xba800000, v9
	v_fmac_f32_e32 v123, 0xba800000, v9
	v_fmac_f32_e32 v124, 0xba800000, v9
	v_fmac_f32_e32 v125, 0xba800000, v9
	v_fmac_f32_e32 v126, 0xba800000, v9
	v_fmac_f32_e32 v127, 0xba800000, v9
	v_fmac_f32_e32 v128, 0xba800000, v9
	v_fmac_f32_e32 v129, 0xba800000, v9
	v_pk_mul_f32 v[244:245], v[114:115], v[114:115]
	v_pk_mul_f32 v[246:247], v[116:117], v[116:117]
	v_add_f32_e32 v244, v245, v244
	v_add_f32_e32 v246, v246, v247
	v_add_f32_e32 v164, v244, v246
	v_pk_mul_f32 v[244:245], v[118:119], v[118:119]
	v_pk_mul_f32 v[246:247], v[120:121], v[120:121]
	v_add_f32_e32 v244, v245, v244
	v_add_f32_e32 v246, v246, v247
	v_add_f32_e32 v165, v244, v246
	v_mul_f32_e32 v248, v122, v122
	v_mul_f32_e32 v249, v124, v124
	v_fmac_f32_e32 v248, v123, v123
	v_fmac_f32_e32 v249, v125, v125
	v_add_f32_e32 v166, v248, v249
	v_pk_mul_f32 v[244:245], v[126:127], v[126:127]
	v_pk_mul_f32 v[246:247], v[128:129], v[128:129]
	v_add_f32_e32 v244, v244, v245
	v_add_f32_e32 v246, v246, v247
	v_add_f32_e32 v167, v244, v246
	v_add_f32_e32 v164, v164, v165
	v_add_f32_e32 v164, v166, v164
	v_add_f32_e32 v9, v167, v164
	ds_bpermute_b32 v28, v96, v9
	s_waitcnt lgkmcnt(0)
	v_add_f32_e32 v9, v9, v28
	ds_swizzle_b32 v28, v9 offset:swizzle(SWAP,16)
	s_waitcnt lgkmcnt(0)
	v_add_f32_e32 v9, v9, v28
	ds_swizzle_b32 v28, v9 offset:swizzle(SWAP,8)
	s_waitcnt lgkmcnt(0)
	v_add_f32_e32 v9, v9, v28
	ds_swizzle_b32 v28, v9 offset:swizzle(SWAP,4)
	s_waitcnt lgkmcnt(0)
	v_add_f32_e32 v9, v9, v28
	ds_swizzle_b32 v28, v9 offset:swizzle(SWAP,2)
	s_waitcnt lgkmcnt(0)
	v_add_f32_e32 v9, v9, v28
	ds_swizzle_b32 v28, v9 offset:swizzle(SWAP,1)
	s_waitcnt lgkmcnt(0)
	v_add_f32_e32 v9, v9, v28
	v_mov_b32_e32 v28, 0x3727c5ac
	v_fmamk_f32 v9, v9, 0x3a800000, v28
	v_mul_f32_e32 v28, 0x4b800000, v9
	v_cmp_gt_f32_e32 vcc, s37, v9
	s_nop 1
	v_cndmask_b32_e32 v9, v9, v28, vcc
	v_rsq_f32_e32 v9, v9
	s_nop 0
	v_mul_f32_e32 v28, 0x45800000, v9
	v_cndmask_b32_e32 v30, v9, v28, vcc
	v_pk_mul_f32 v[114:115], v[114:115], v[30:31] op_sel_hi:[1,0]
	v_pk_mul_f32 v[116:117], v[116:117], v[30:31] op_sel_hi:[1,0]
	v_pk_fma_f32 v[34:35], v[140:141], v[114:115], v[98:99]
	v_pk_fma_f32 v[36:37], v[142:143], v[116:117], v[100:101]
	global_store_dwordx4 v[86:87], v[34:37], off sc1 nt
	v_pk_fma_f32 v[114:115], v[226:227], v[34:35], v[210:211]
	v_pk_fma_f32 v[116:117], v[228:229], v[36:37], v[212:213]
	s_nop 0
	v_cvt_pk_bf16_f32 v50, v114, v115
	v_cvt_pk_bf16_f32 v51, v116, v117
	global_store_dwordx2 v[88:89], v[50:51], off sc1
	v_pk_mul_f32 v[118:119], v[118:119], v[30:31] op_sel_hi:[1,0]
	v_pk_mul_f32 v[120:121], v[120:121], v[30:31] op_sel_hi:[1,0]
	v_pk_fma_f32 v[38:39], v[144:145], v[118:119], v[102:103]
	v_pk_fma_f32 v[40:41], v[146:147], v[120:121], v[104:105]
	global_store_dwordx4 v[86:87], v[38:41], off offset:1024 sc1 nt
	v_pk_fma_f32 v[118:119], v[230:231], v[38:39], v[214:215]
	v_pk_fma_f32 v[120:121], v[232:233], v[40:41], v[216:217]
	s_nop 0
	v_cvt_pk_bf16_f32 v52, v118, v119
	v_cvt_pk_bf16_f32 v53, v120, v121
	global_store_dwordx2 v[88:89], v[52:53], off offset:512 sc1
	v_pk_mul_f32 v[122:123], v[122:123], v[30:31] op_sel_hi:[1,0]
	v_pk_mul_f32 v[124:125], v[124:125], v[30:31] op_sel_hi:[1,0]
	v_pk_fma_f32 v[42:43], v[148:149], v[122:123], v[106:107]
	v_pk_fma_f32 v[44:45], v[150:151], v[124:125], v[108:109]
	global_store_dwordx4 v[86:87], v[42:45], off offset:2048 sc1 nt
	v_pk_fma_f32 v[122:123], v[234:235], v[42:43], v[218:219]
	v_pk_fma_f32 v[124:125], v[236:237], v[44:45], v[220:221]
	s_nop 0
	v_cvt_pk_bf16_f32 v54, v122, v123
	v_cvt_pk_bf16_f32 v55, v124, v125
	global_store_dwordx2 v[88:89], v[54:55], off offset:1024 sc1
	v_pk_mul_f32 v[126:127], v[126:127], v[30:31] op_sel_hi:[1,0]
	v_pk_mul_f32 v[128:129], v[128:129], v[30:31] op_sel_hi:[1,0]
	v_pk_fma_f32 v[46:47], v[152:153], v[126:127], v[110:111]
	v_pk_fma_f32 v[48:49], v[154:155], v[128:129], v[112:113]
	global_store_dwordx4 v[86:87], v[46:49], off offset:3072 sc1 nt
	v_pk_fma_f32 v[126:127], v[238:239], v[46:47], v[222:223]
	v_pk_fma_f32 v[128:129], v[240:241], v[48:49], v[224:225]
	s_nop 0
	v_cvt_pk_bf16_f32 v56, v126, v127
	v_cvt_pk_bf16_f32 v57, v128, v129
	global_store_dwordx2 v[88:89], v[56:57], off offset:1536 sc1
	v_lshl_add_u64 v[86:87], v[86:87], 0, s[0:1]
	v_lshl_add_u64 v[88:89], v[88:89], 0, s[20:21]
	global_load_dwordx4 v[34:37], v[82:83], off nt
	global_load_dwordx4 v[38:41], v[82:83], off offset:1024 nt
	global_load_dwordx4 v[42:45], v[82:83], off offset:2048 nt
	global_load_dwordx4 v[46:49], v[82:83], off offset:3072 nt
	global_load_dwordx2 v[50:51], v[84:85], off
	global_load_dwordx2 v[52:53], v[84:85], off offset:512
	global_load_dwordx2 v[54:55], v[84:85], off offset:1024
	global_load_dwordx2 v[56:57], v[84:85], off offset:1536
	v_lshl_add_u64 v[82:83], v[82:83], 0, s[0:1]
	v_lshl_add_u64 v[84:85], v[84:85], 0, s[20:21]
	s_waitcnt vmcnt(32)
	v_lshlrev_b32_e32 v156, 16, v74
	v_and_b32_e32 v157, 0xffff0000, v74
	v_lshlrev_b32_e32 v74, 16, v75
	v_and_b32_e32 v75, 0xffff0000, v75
	v_lshlrev_b32_e32 v158, 16, v76
	v_and_b32_e32 v159, 0xffff0000, v76
	v_lshlrev_b32_e32 v76, 16, v77
	v_and_b32_e32 v77, 0xffff0000, v77
	v_lshlrev_b32_e32 v160, 16, v78
	v_and_b32_e32 v161, 0xffff0000, v78
	v_lshlrev_b32_e32 v78, 16, v79
	v_and_b32_e32 v79, 0xffff0000, v79
	v_lshlrev_b32_e32 v162, 16, v80
	v_and_b32_e32 v163, 0xffff0000, v80
	v_lshlrev_b32_e32 v80, 16, v81
	v_and_b32_e32 v81, 0xffff0000, v81
	v_pk_mul_f32 v[114:115], v[194:195], v[156:157]
	v_pk_mul_f32 v[116:117], v[196:197], v[74:75]
	v_pk_mul_f32 v[118:119], v[198:199], v[158:159]
	v_pk_mul_f32 v[120:121], v[200:201], v[76:77]
	v_pk_mul_f32 v[122:123], v[202:203], v[160:161]
	v_pk_mul_f32 v[124:125], v[204:205], v[78:79]
	v_pk_mul_f32 v[126:127], v[206:207], v[162:163]
	v_pk_mul_f32 v[128:129], v[208:209], v[80:81]
	v_pk_mul_f32 v[114:115], v[10:11], v[114:115]
	v_pk_mul_f32 v[116:117], v[10:11], v[116:117]
	v_pk_mul_f32 v[118:119], v[10:11], v[118:119]
	v_pk_mul_f32 v[120:121], v[10:11], v[120:121]
	v_pk_mul_f32 v[122:123], v[10:11], v[122:123]
	v_pk_mul_f32 v[124:125], v[10:11], v[124:125]
	v_pk_mul_f32 v[126:127], v[10:11], v[126:127]
	v_pk_mul_f32 v[128:129], v[10:11], v[128:129]
	v_pk_fma_f32 v[114:115], v[58:59], s[28:29], v[114:115] op_sel_hi:[1,0,1]
	v_pk_fma_f32 v[116:117], v[60:61], s[28:29], v[116:117] op_sel_hi:[1,0,1]
	v_pk_fma_f32 v[118:119], v[62:63], s[28:29], v[118:119] op_sel_hi:[1,0,1]
	v_pk_fma_f32 v[120:121], v[64:65], s[28:29], v[120:121] op_sel_hi:[1,0,1]
	v_pk_fma_f32 v[122:123], v[66:67], s[28:29], v[122:123] op_sel_hi:[1,0,1]
	v_pk_fma_f32 v[124:125], v[68:69], s[28:29], v[124:125] op_sel_hi:[1,0,1]
	v_pk_fma_f32 v[126:127], v[70:71], s[28:29], v[126:127] op_sel_hi:[1,0,1]
	v_pk_fma_f32 v[128:129], v[72:73], s[28:29], v[128:129] op_sel_hi:[1,0,1]
	v_add_f32_e32 v164, v114, v115
	v_add_f32_e32 v165, v116, v117
	v_add_f32_e32 v166, v118, v119
	v_add_f32_e32 v167, v120, v121
	v_add_f32_e32 v168, v122, v123
	v_add_f32_e32 v169, v124, v125
	v_add_f32_e32 v242, v126, v127
	v_add_f32_e32 v243, v128, v129
	v_add_f32_e32 v164, v164, v165
	v_add_f32_e32 v166, v166, v167
	v_add_f32_e32 v168, v168, v169
	v_add_f32_e32 v242, v242, v243
	v_add_f32_e32 v9, 0, v164
	v_add_f32_e32 v9, v9, v166
	v_add_f32_e32 v9, v9, v168
	v_add_f32_e32 v9, v9, v242
	ds_bpermute_b32 v28, v96, v9
	s_waitcnt lgkmcnt(0)
	v_add_f32_e32 v9, v9, v28
	ds_swizzle_b32 v28, v9 offset:swizzle(SWAP,16)
	s_waitcnt lgkmcnt(0)
	v_add_f32_e32 v9, v9, v28
	ds_swizzle_b32 v28, v9 offset:swizzle(SWAP,8)
	s_waitcnt lgkmcnt(0)
	v_add_f32_e32 v9, v9, v28
	ds_swizzle_b32 v28, v9 offset:swizzle(SWAP,4)
	s_waitcnt lgkmcnt(0)
	v_add_f32_e32 v9, v9, v28
	ds_swizzle_b32 v28, v9 offset:swizzle(SWAP,2)
	s_waitcnt lgkmcnt(0)
	v_add_f32_e32 v9, v9, v28
	ds_swizzle_b32 v28, v9 offset:swizzle(SWAP,1)
	s_waitcnt lgkmcnt(0)
	v_add_f32_e32 v9, v9, v28
	v_fmac_f32_e32 v114, 0xba800000, v9
	v_fmac_f32_e32 v115, 0xba800000, v9
	v_fmac_f32_e32 v116, 0xba800000, v9
	v_fmac_f32_e32 v117, 0xba800000, v9
	v_fmac_f32_e32 v118, 0xba800000, v9
	v_fmac_f32_e32 v119, 0xba800000, v9
	v_fmac_f32_e32 v120, 0xba800000, v9
	v_fmac_f32_e32 v121, 0xba800000, v9
	v_fmac_f32_e32 v122, 0xba800000, v9
	v_fmac_f32_e32 v123, 0xba800000, v9
	v_fmac_f32_e32 v124, 0xba800000, v9
	v_fmac_f32_e32 v125, 0xba800000, v9
	v_fmac_f32_e32 v126, 0xba800000, v9
	v_fmac_f32_e32 v127, 0xba800000, v9
	v_fmac_f32_e32 v128, 0xba800000, v9
	v_fmac_f32_e32 v129, 0xba800000, v9
	v_pk_mul_f32 v[244:245], v[114:115], v[114:115]
	v_pk_mul_f32 v[246:247], v[116:117], v[116:117]
	v_add_f32_e32 v244, v245, v244
	v_add_f32_e32 v246, v246, v247
	v_add_f32_e32 v164, v244, v246
	v_pk_mul_f32 v[244:245], v[118:119], v[118:119]
	v_pk_mul_f32 v[246:247], v[120:121], v[120:121]
	v_add_f32_e32 v244, v245, v244
	v_add_f32_e32 v246, v246, v247
	v_add_f32_e32 v165, v244, v246
	v_mul_f32_e32 v248, v122, v122
	v_mul_f32_e32 v249, v124, v124
	v_fmac_f32_e32 v248, v123, v123
	v_fmac_f32_e32 v249, v125, v125
	v_add_f32_e32 v166, v248, v249
	v_pk_mul_f32 v[244:245], v[126:127], v[126:127]
	v_pk_mul_f32 v[246:247], v[128:129], v[128:129]
	v_add_f32_e32 v244, v244, v245
	v_add_f32_e32 v246, v246, v247
	v_add_f32_e32 v167, v244, v246
	v_add_f32_e32 v164, v164, v165
	v_add_f32_e32 v164, v166, v164
	v_add_f32_e32 v9, v167, v164
	ds_bpermute_b32 v28, v96, v9
	s_waitcnt lgkmcnt(0)
	v_add_f32_e32 v9, v9, v28
	ds_swizzle_b32 v28, v9 offset:swizzle(SWAP,16)
	s_waitcnt lgkmcnt(0)
	v_add_f32_e32 v9, v9, v28
	ds_swizzle_b32 v28, v9 offset:swizzle(SWAP,8)
	s_waitcnt lgkmcnt(0)
	v_add_f32_e32 v9, v9, v28
	ds_swizzle_b32 v28, v9 offset:swizzle(SWAP,4)
	s_waitcnt lgkmcnt(0)
	v_add_f32_e32 v9, v9, v28
	ds_swizzle_b32 v28, v9 offset:swizzle(SWAP,2)
	s_waitcnt lgkmcnt(0)
	v_add_f32_e32 v9, v9, v28
	ds_swizzle_b32 v28, v9 offset:swizzle(SWAP,1)
	s_waitcnt lgkmcnt(0)
	v_add_f32_e32 v9, v9, v28
	v_mov_b32_e32 v28, 0x3727c5ac
	v_fmamk_f32 v9, v9, 0x3a800000, v28
	v_mul_f32_e32 v28, 0x4b800000, v9
	v_cmp_gt_f32_e32 vcc, s37, v9
	s_nop 1
	v_cndmask_b32_e32 v9, v9, v28, vcc
	v_rsq_f32_e32 v9, v9
	s_nop 0
	v_mul_f32_e32 v28, 0x45800000, v9
	v_cndmask_b32_e32 v30, v9, v28, vcc
	v_pk_mul_f32 v[114:115], v[114:115], v[30:31] op_sel_hi:[1,0]
	v_pk_mul_f32 v[116:117], v[116:117], v[30:31] op_sel_hi:[1,0]
	v_pk_fma_f32 v[58:59], v[140:141], v[114:115], v[98:99]
	v_pk_fma_f32 v[60:61], v[142:143], v[116:117], v[100:101]
	global_store_dwordx4 v[86:87], v[58:61], off sc1 nt
	v_pk_fma_f32 v[114:115], v[226:227], v[58:59], v[210:211]
	v_pk_fma_f32 v[116:117], v[228:229], v[60:61], v[212:213]
	s_nop 0
	v_cvt_pk_bf16_f32 v74, v114, v115
	v_cvt_pk_bf16_f32 v75, v116, v117
	global_store_dwordx2 v[88:89], v[74:75], off sc1
	v_pk_mul_f32 v[118:119], v[118:119], v[30:31] op_sel_hi:[1,0]
	v_pk_mul_f32 v[120:121], v[120:121], v[30:31] op_sel_hi:[1,0]
	v_pk_fma_f32 v[62:63], v[144:145], v[118:119], v[102:103]
	v_pk_fma_f32 v[64:65], v[146:147], v[120:121], v[104:105]
	global_store_dwordx4 v[86:87], v[62:65], off offset:1024 sc1 nt
	v_pk_fma_f32 v[118:119], v[230:231], v[62:63], v[214:215]
	v_pk_fma_f32 v[120:121], v[232:233], v[64:65], v[216:217]
	s_nop 0
	v_cvt_pk_bf16_f32 v76, v118, v119
	v_cvt_pk_bf16_f32 v77, v120, v121
	global_store_dwordx2 v[88:89], v[76:77], off offset:512 sc1
	v_pk_mul_f32 v[122:123], v[122:123], v[30:31] op_sel_hi:[1,0]
	v_pk_mul_f32 v[124:125], v[124:125], v[30:31] op_sel_hi:[1,0]
	v_pk_fma_f32 v[66:67], v[148:149], v[122:123], v[106:107]
	v_pk_fma_f32 v[68:69], v[150:151], v[124:125], v[108:109]
	global_store_dwordx4 v[86:87], v[66:69], off offset:2048 sc1 nt
	v_pk_fma_f32 v[122:123], v[234:235], v[66:67], v[218:219]
	v_pk_fma_f32 v[124:125], v[236:237], v[68:69], v[220:221]
	s_nop 0
	v_cvt_pk_bf16_f32 v78, v122, v123
	v_cvt_pk_bf16_f32 v79, v124, v125
	global_store_dwordx2 v[88:89], v[78:79], off offset:1024 sc1
	v_pk_mul_f32 v[126:127], v[126:127], v[30:31] op_sel_hi:[1,0]
	v_pk_mul_f32 v[128:129], v[128:129], v[30:31] op_sel_hi:[1,0]
	v_pk_fma_f32 v[70:71], v[152:153], v[126:127], v[110:111]
	v_pk_fma_f32 v[72:73], v[154:155], v[128:129], v[112:113]
	global_store_dwordx4 v[86:87], v[70:73], off offset:3072 sc1 nt
	v_pk_fma_f32 v[126:127], v[238:239], v[70:71], v[222:223]
	v_pk_fma_f32 v[128:129], v[240:241], v[72:73], v[224:225]
	s_nop 0
	v_cvt_pk_bf16_f32 v80, v126, v127
	v_cvt_pk_bf16_f32 v81, v128, v129
	global_store_dwordx2 v[88:89], v[80:81], off offset:1536 sc1
	v_lshl_add_u64 v[86:87], v[86:87], 0, s[0:1]
	v_lshl_add_u64 v[88:89], v[88:89], 0, s[20:21]
	global_load_dwordx4 v[58:61], v[82:83], off nt
	global_load_dwordx4 v[62:65], v[82:83], off offset:1024 nt
	global_load_dwordx4 v[66:69], v[82:83], off offset:2048 nt
	global_load_dwordx4 v[70:73], v[82:83], off offset:3072 nt
	global_load_dwordx2 v[74:75], v[84:85], off
	global_load_dwordx2 v[76:77], v[84:85], off offset:512
	global_load_dwordx2 v[78:79], v[84:85], off offset:1024
	global_load_dwordx2 v[80:81], v[84:85], off offset:1536
	v_lshl_add_u64 v[82:83], v[82:83], 0, s[0:1]
	v_lshl_add_u64 v[84:85], v[84:85], 0, s[20:21]
	s_waitcnt vmcnt(32)
	v_lshlrev_b32_e32 v156, 16, v12
	v_and_b32_e32 v157, 0xffff0000, v12
	v_lshlrev_b32_e32 v12, 16, v13
	v_and_b32_e32 v13, 0xffff0000, v13
	v_lshlrev_b32_e32 v158, 16, v14
	v_and_b32_e32 v159, 0xffff0000, v14
	v_lshlrev_b32_e32 v14, 16, v15
	v_and_b32_e32 v15, 0xffff0000, v15
	v_lshlrev_b32_e32 v160, 16, v16
	v_and_b32_e32 v161, 0xffff0000, v16
	v_lshlrev_b32_e32 v16, 16, v17
	v_and_b32_e32 v17, 0xffff0000, v17
	v_lshlrev_b32_e32 v162, 16, v18
	v_and_b32_e32 v163, 0xffff0000, v18
	v_lshlrev_b32_e32 v18, 16, v19
	v_and_b32_e32 v19, 0xffff0000, v19
	v_pk_mul_f32 v[114:115], v[194:195], v[156:157]
	v_pk_mul_f32 v[116:117], v[196:197], v[12:13]
	v_pk_mul_f32 v[118:119], v[198:199], v[158:159]
	v_pk_mul_f32 v[120:121], v[200:201], v[14:15]
	v_pk_mul_f32 v[122:123], v[202:203], v[160:161]
	v_pk_mul_f32 v[124:125], v[204:205], v[16:17]
	v_pk_mul_f32 v[126:127], v[206:207], v[162:163]
	v_pk_mul_f32 v[128:129], v[208:209], v[18:19]
	v_pk_mul_f32 v[114:115], v[10:11], v[114:115]
	v_pk_mul_f32 v[116:117], v[10:11], v[116:117]
	v_pk_mul_f32 v[118:119], v[10:11], v[118:119]
	v_pk_mul_f32 v[120:121], v[10:11], v[120:121]
	v_pk_mul_f32 v[122:123], v[10:11], v[122:123]
	v_pk_mul_f32 v[124:125], v[10:11], v[124:125]
	v_pk_mul_f32 v[126:127], v[10:11], v[126:127]
	v_pk_mul_f32 v[128:129], v[10:11], v[128:129]
	v_pk_fma_f32 v[114:115], v[20:21], s[28:29], v[114:115] op_sel_hi:[1,0,1]
	v_pk_fma_f32 v[116:117], v[22:23], s[28:29], v[116:117] op_sel_hi:[1,0,1]
	v_pk_fma_f32 v[118:119], v[24:25], s[28:29], v[118:119] op_sel_hi:[1,0,1]
	v_pk_fma_f32 v[120:121], v[26:27], s[28:29], v[120:121] op_sel_hi:[1,0,1]
	v_pk_fma_f32 v[122:123], v[0:1], s[28:29], v[122:123] op_sel_hi:[1,0,1]
	v_pk_fma_f32 v[124:125], v[2:3], s[28:29], v[124:125] op_sel_hi:[1,0,1]
	v_pk_fma_f32 v[126:127], v[4:5], s[28:29], v[126:127] op_sel_hi:[1,0,1]
	v_pk_fma_f32 v[128:129], v[6:7], s[28:29], v[128:129] op_sel_hi:[1,0,1]
	v_add_f32_e32 v164, v114, v115
	v_add_f32_e32 v165, v116, v117
	v_add_f32_e32 v166, v118, v119
	v_add_f32_e32 v167, v120, v121
	v_add_f32_e32 v168, v122, v123
	v_add_f32_e32 v169, v124, v125
	v_add_f32_e32 v242, v126, v127
	v_add_f32_e32 v243, v128, v129
	v_add_f32_e32 v164, v164, v165
	v_add_f32_e32 v166, v166, v167
	v_add_f32_e32 v168, v168, v169
	v_add_f32_e32 v242, v242, v243
	v_add_f32_e32 v9, 0, v164
	v_add_f32_e32 v9, v9, v166
	v_add_f32_e32 v9, v9, v168
	v_add_f32_e32 v9, v9, v242
	ds_bpermute_b32 v28, v96, v9
	s_waitcnt lgkmcnt(0)
	v_add_f32_e32 v9, v9, v28
	ds_swizzle_b32 v28, v9 offset:swizzle(SWAP,16)
	s_waitcnt lgkmcnt(0)
	v_add_f32_e32 v9, v9, v28
	ds_swizzle_b32 v28, v9 offset:swizzle(SWAP,8)
	s_waitcnt lgkmcnt(0)
	v_add_f32_e32 v9, v9, v28
	ds_swizzle_b32 v28, v9 offset:swizzle(SWAP,4)
	s_waitcnt lgkmcnt(0)
	v_add_f32_e32 v9, v9, v28
	ds_swizzle_b32 v28, v9 offset:swizzle(SWAP,2)
	s_waitcnt lgkmcnt(0)
	v_add_f32_e32 v9, v9, v28
	ds_swizzle_b32 v28, v9 offset:swizzle(SWAP,1)
	s_waitcnt lgkmcnt(0)
	v_add_f32_e32 v9, v9, v28
	v_fmac_f32_e32 v114, 0xba800000, v9
	v_fmac_f32_e32 v115, 0xba800000, v9
	v_fmac_f32_e32 v116, 0xba800000, v9
	v_fmac_f32_e32 v117, 0xba800000, v9
	v_fmac_f32_e32 v118, 0xba800000, v9
	v_fmac_f32_e32 v119, 0xba800000, v9
	v_fmac_f32_e32 v120, 0xba800000, v9
	v_fmac_f32_e32 v121, 0xba800000, v9
	v_fmac_f32_e32 v122, 0xba800000, v9
	v_fmac_f32_e32 v123, 0xba800000, v9
	v_fmac_f32_e32 v124, 0xba800000, v9
	v_fmac_f32_e32 v125, 0xba800000, v9
	v_fmac_f32_e32 v126, 0xba800000, v9
	v_fmac_f32_e32 v127, 0xba800000, v9
	v_fmac_f32_e32 v128, 0xba800000, v9
	v_fmac_f32_e32 v129, 0xba800000, v9
	v_pk_mul_f32 v[244:245], v[114:115], v[114:115]
	v_pk_mul_f32 v[246:247], v[116:117], v[116:117]
	v_add_f32_e32 v244, v245, v244
	v_add_f32_e32 v246, v246, v247
	v_add_f32_e32 v164, v244, v246
	v_pk_mul_f32 v[244:245], v[118:119], v[118:119]
	v_pk_mul_f32 v[246:247], v[120:121], v[120:121]
	v_add_f32_e32 v244, v245, v244
	v_add_f32_e32 v246, v246, v247
	v_add_f32_e32 v165, v244, v246
	v_mul_f32_e32 v248, v122, v122
	v_mul_f32_e32 v249, v124, v124
	v_fmac_f32_e32 v248, v123, v123
	v_fmac_f32_e32 v249, v125, v125
	v_add_f32_e32 v166, v248, v249
	v_pk_mul_f32 v[244:245], v[126:127], v[126:127]
	v_pk_mul_f32 v[246:247], v[128:129], v[128:129]
	v_add_f32_e32 v244, v244, v245
	v_add_f32_e32 v246, v246, v247
	v_add_f32_e32 v167, v244, v246
	v_add_f32_e32 v164, v164, v165
	v_add_f32_e32 v164, v166, v164
	v_add_f32_e32 v9, v167, v164
	ds_bpermute_b32 v28, v96, v9
	s_waitcnt lgkmcnt(0)
	v_add_f32_e32 v9, v9, v28
	ds_swizzle_b32 v28, v9 offset:swizzle(SWAP,16)
	s_waitcnt lgkmcnt(0)
	v_add_f32_e32 v9, v9, v28
	ds_swizzle_b32 v28, v9 offset:swizzle(SWAP,8)
	s_waitcnt lgkmcnt(0)
	v_add_f32_e32 v9, v9, v28
	ds_swizzle_b32 v28, v9 offset:swizzle(SWAP,4)
	s_waitcnt lgkmcnt(0)
	v_add_f32_e32 v9, v9, v28
	ds_swizzle_b32 v28, v9 offset:swizzle(SWAP,2)
	s_waitcnt lgkmcnt(0)
	v_add_f32_e32 v9, v9, v28
	ds_swizzle_b32 v28, v9 offset:swizzle(SWAP,1)
	s_waitcnt lgkmcnt(0)
	v_add_f32_e32 v9, v9, v28
	v_mov_b32_e32 v28, 0x3727c5ac
	v_fmamk_f32 v9, v9, 0x3a800000, v28
	v_mul_f32_e32 v28, 0x4b800000, v9
	v_cmp_gt_f32_e32 vcc, s37, v9
	s_nop 1
	v_cndmask_b32_e32 v9, v9, v28, vcc
	v_rsq_f32_e32 v9, v9
	s_nop 0
	v_mul_f32_e32 v28, 0x45800000, v9
	v_cndmask_b32_e32 v30, v9, v28, vcc
	v_pk_mul_f32 v[114:115], v[114:115], v[30:31] op_sel_hi:[1,0]
	v_pk_mul_f32 v[116:117], v[116:117], v[30:31] op_sel_hi:[1,0]
	v_pk_fma_f32 v[20:21], v[140:141], v[114:115], v[98:99]
	v_pk_fma_f32 v[22:23], v[142:143], v[116:117], v[100:101]
	global_store_dwordx4 v[86:87], v[20:23], off sc1 nt
	v_pk_fma_f32 v[114:115], v[226:227], v[20:21], v[210:211]
	v_pk_fma_f32 v[116:117], v[228:229], v[22:23], v[212:213]
	s_nop 0
	v_cvt_pk_bf16_f32 v12, v114, v115
	v_cvt_pk_bf16_f32 v13, v116, v117
	global_store_dwordx2 v[88:89], v[12:13], off sc1
	v_pk_mul_f32 v[118:119], v[118:119], v[30:31] op_sel_hi:[1,0]
	v_pk_mul_f32 v[120:121], v[120:121], v[30:31] op_sel_hi:[1,0]
	v_pk_fma_f32 v[24:25], v[144:145], v[118:119], v[102:103]
	v_pk_fma_f32 v[26:27], v[146:147], v[120:121], v[104:105]
	global_store_dwordx4 v[86:87], v[24:27], off offset:1024 sc1 nt
	v_pk_fma_f32 v[118:119], v[230:231], v[24:25], v[214:215]
	v_pk_fma_f32 v[120:121], v[232:233], v[26:27], v[216:217]
	s_nop 0
	v_cvt_pk_bf16_f32 v14, v118, v119
	v_cvt_pk_bf16_f32 v15, v120, v121
	global_store_dwordx2 v[88:89], v[14:15], off offset:512 sc1
	v_pk_mul_f32 v[122:123], v[122:123], v[30:31] op_sel_hi:[1,0]
	v_pk_mul_f32 v[124:125], v[124:125], v[30:31] op_sel_hi:[1,0]
	v_pk_fma_f32 v[0:1], v[148:149], v[122:123], v[106:107]
	v_pk_fma_f32 v[2:3], v[150:151], v[124:125], v[108:109]
	global_store_dwordx4 v[86:87], v[0:3], off offset:2048 sc1 nt
	v_pk_fma_f32 v[122:123], v[234:235], v[0:1], v[218:219]
	v_pk_fma_f32 v[124:125], v[236:237], v[2:3], v[220:221]
	s_nop 0
	v_cvt_pk_bf16_f32 v16, v122, v123
	v_cvt_pk_bf16_f32 v17, v124, v125
	global_store_dwordx2 v[88:89], v[16:17], off offset:1024 sc1
	v_pk_mul_f32 v[126:127], v[126:127], v[30:31] op_sel_hi:[1,0]
	v_pk_mul_f32 v[128:129], v[128:129], v[30:31] op_sel_hi:[1,0]
	v_pk_fma_f32 v[4:5], v[152:153], v[126:127], v[110:111]
	v_pk_fma_f32 v[6:7], v[154:155], v[128:129], v[112:113]
	global_store_dwordx4 v[86:87], v[4:7], off offset:3072 sc1 nt
	v_pk_fma_f32 v[126:127], v[238:239], v[4:5], v[222:223]
	v_pk_fma_f32 v[128:129], v[240:241], v[6:7], v[224:225]
	s_nop 0
	v_cvt_pk_bf16_f32 v18, v126, v127
	v_cvt_pk_bf16_f32 v19, v128, v129
	global_store_dwordx2 v[88:89], v[18:19], off offset:1536 sc1
	v_lshl_add_u64 v[86:87], v[86:87], 0, s[0:1]
	v_lshl_add_u64 v[88:89], v[88:89], 0, s[20:21]
	global_load_dwordx4 v[20:23], v[82:83], off nt
	global_load_dwordx4 v[24:27], v[82:83], off offset:1024 nt
	global_load_dwordx4 v[0:3], v[82:83], off offset:2048 nt
	global_load_dwordx4 v[4:7], v[82:83], off offset:3072 nt
	global_load_dwordx2 v[12:13], v[84:85], off
	global_load_dwordx2 v[14:15], v[84:85], off offset:512
	global_load_dwordx2 v[16:17], v[84:85], off offset:1024
	global_load_dwordx2 v[18:19], v[84:85], off offset:1536
	v_lshl_add_u64 v[82:83], v[82:83], 0, s[0:1]
	v_lshl_add_u64 v[84:85], v[84:85], 0, s[20:21]
	s_waitcnt vmcnt(32)
	v_lshlrev_b32_e32 v156, 16, v50
	v_and_b32_e32 v157, 0xffff0000, v50
	v_lshlrev_b32_e32 v50, 16, v51
	v_and_b32_e32 v51, 0xffff0000, v51
	v_lshlrev_b32_e32 v158, 16, v52
	v_and_b32_e32 v159, 0xffff0000, v52
	v_lshlrev_b32_e32 v52, 16, v53
	v_and_b32_e32 v53, 0xffff0000, v53
	v_lshlrev_b32_e32 v160, 16, v54
	v_and_b32_e32 v161, 0xffff0000, v54
	v_lshlrev_b32_e32 v54, 16, v55
	v_and_b32_e32 v55, 0xffff0000, v55
	v_lshlrev_b32_e32 v162, 16, v56
	v_and_b32_e32 v163, 0xffff0000, v56
	v_lshlrev_b32_e32 v56, 16, v57
	v_and_b32_e32 v57, 0xffff0000, v57
	v_pk_mul_f32 v[114:115], v[194:195], v[156:157]
	v_pk_mul_f32 v[116:117], v[196:197], v[50:51]
	v_pk_mul_f32 v[118:119], v[198:199], v[158:159]
	v_pk_mul_f32 v[120:121], v[200:201], v[52:53]
	v_pk_mul_f32 v[122:123], v[202:203], v[160:161]
	v_pk_mul_f32 v[124:125], v[204:205], v[54:55]
	v_pk_mul_f32 v[126:127], v[206:207], v[162:163]
	v_pk_mul_f32 v[128:129], v[208:209], v[56:57]
	v_pk_mul_f32 v[114:115], v[10:11], v[114:115]
	v_pk_mul_f32 v[116:117], v[10:11], v[116:117]
	v_pk_mul_f32 v[118:119], v[10:11], v[118:119]
	v_pk_mul_f32 v[120:121], v[10:11], v[120:121]
	v_pk_mul_f32 v[122:123], v[10:11], v[122:123]
	v_pk_mul_f32 v[124:125], v[10:11], v[124:125]
	v_pk_mul_f32 v[126:127], v[10:11], v[126:127]
	v_pk_mul_f32 v[128:129], v[10:11], v[128:129]
	v_pk_fma_f32 v[114:115], v[34:35], s[28:29], v[114:115] op_sel_hi:[1,0,1]
	v_pk_fma_f32 v[116:117], v[36:37], s[28:29], v[116:117] op_sel_hi:[1,0,1]
	v_pk_fma_f32 v[118:119], v[38:39], s[28:29], v[118:119] op_sel_hi:[1,0,1]
	v_pk_fma_f32 v[120:121], v[40:41], s[28:29], v[120:121] op_sel_hi:[1,0,1]
	v_pk_fma_f32 v[122:123], v[42:43], s[28:29], v[122:123] op_sel_hi:[1,0,1]
	v_pk_fma_f32 v[124:125], v[44:45], s[28:29], v[124:125] op_sel_hi:[1,0,1]
	v_pk_fma_f32 v[126:127], v[46:47], s[28:29], v[126:127] op_sel_hi:[1,0,1]
	v_pk_fma_f32 v[128:129], v[48:49], s[28:29], v[128:129] op_sel_hi:[1,0,1]
	v_add_f32_e32 v164, v114, v115
	v_add_f32_e32 v165, v116, v117
	v_add_f32_e32 v166, v118, v119
	v_add_f32_e32 v167, v120, v121
	v_add_f32_e32 v168, v122, v123
	v_add_f32_e32 v169, v124, v125
	v_add_f32_e32 v242, v126, v127
	v_add_f32_e32 v243, v128, v129
	v_add_f32_e32 v164, v164, v165
	v_add_f32_e32 v166, v166, v167
	v_add_f32_e32 v168, v168, v169
	v_add_f32_e32 v242, v242, v243
	v_add_f32_e32 v9, 0, v164
	v_add_f32_e32 v9, v9, v166
	v_add_f32_e32 v9, v9, v168
	v_add_f32_e32 v9, v9, v242
	ds_bpermute_b32 v28, v96, v9
	s_waitcnt lgkmcnt(0)
	v_add_f32_e32 v9, v9, v28
	ds_swizzle_b32 v28, v9 offset:swizzle(SWAP,16)
	s_waitcnt lgkmcnt(0)
	v_add_f32_e32 v9, v9, v28
	ds_swizzle_b32 v28, v9 offset:swizzle(SWAP,8)
	s_waitcnt lgkmcnt(0)
	v_add_f32_e32 v9, v9, v28
	ds_swizzle_b32 v28, v9 offset:swizzle(SWAP,4)
	s_waitcnt lgkmcnt(0)
	v_add_f32_e32 v9, v9, v28
	ds_swizzle_b32 v28, v9 offset:swizzle(SWAP,2)
	s_waitcnt lgkmcnt(0)
	v_add_f32_e32 v9, v9, v28
	ds_swizzle_b32 v28, v9 offset:swizzle(SWAP,1)
	s_waitcnt lgkmcnt(0)
	v_add_f32_e32 v9, v9, v28
	v_fmac_f32_e32 v114, 0xba800000, v9
	v_fmac_f32_e32 v115, 0xba800000, v9
	v_fmac_f32_e32 v116, 0xba800000, v9
	v_fmac_f32_e32 v117, 0xba800000, v9
	v_fmac_f32_e32 v118, 0xba800000, v9
	v_fmac_f32_e32 v119, 0xba800000, v9
	v_fmac_f32_e32 v120, 0xba800000, v9
	v_fmac_f32_e32 v121, 0xba800000, v9
	v_fmac_f32_e32 v122, 0xba800000, v9
	v_fmac_f32_e32 v123, 0xba800000, v9
	v_fmac_f32_e32 v124, 0xba800000, v9
	v_fmac_f32_e32 v125, 0xba800000, v9
	v_fmac_f32_e32 v126, 0xba800000, v9
	v_fmac_f32_e32 v127, 0xba800000, v9
	v_fmac_f32_e32 v128, 0xba800000, v9
	v_fmac_f32_e32 v129, 0xba800000, v9
	v_pk_mul_f32 v[244:245], v[114:115], v[114:115]
	v_pk_mul_f32 v[246:247], v[116:117], v[116:117]
	v_add_f32_e32 v244, v245, v244
	v_add_f32_e32 v246, v246, v247
	v_add_f32_e32 v164, v244, v246
	v_pk_mul_f32 v[244:245], v[118:119], v[118:119]
	v_pk_mul_f32 v[246:247], v[120:121], v[120:121]
	v_add_f32_e32 v244, v245, v244
	v_add_f32_e32 v246, v246, v247
	v_add_f32_e32 v165, v244, v246
	v_mul_f32_e32 v248, v122, v122
	v_mul_f32_e32 v249, v124, v124
	v_fmac_f32_e32 v248, v123, v123
	v_fmac_f32_e32 v249, v125, v125
	v_add_f32_e32 v166, v248, v249
	v_pk_mul_f32 v[244:245], v[126:127], v[126:127]
	v_pk_mul_f32 v[246:247], v[128:129], v[128:129]
	v_add_f32_e32 v244, v244, v245
	v_add_f32_e32 v246, v246, v247
	v_add_f32_e32 v167, v244, v246
	v_add_f32_e32 v164, v164, v165
	v_add_f32_e32 v164, v166, v164
	v_add_f32_e32 v9, v167, v164
	ds_bpermute_b32 v28, v96, v9
	s_waitcnt lgkmcnt(0)
	v_add_f32_e32 v9, v9, v28
	ds_swizzle_b32 v28, v9 offset:swizzle(SWAP,16)
	s_waitcnt lgkmcnt(0)
	v_add_f32_e32 v9, v9, v28
	ds_swizzle_b32 v28, v9 offset:swizzle(SWAP,8)
	s_waitcnt lgkmcnt(0)
	v_add_f32_e32 v9, v9, v28
	ds_swizzle_b32 v28, v9 offset:swizzle(SWAP,4)
	s_waitcnt lgkmcnt(0)
	v_add_f32_e32 v9, v9, v28
	ds_swizzle_b32 v28, v9 offset:swizzle(SWAP,2)
	s_waitcnt lgkmcnt(0)
	v_add_f32_e32 v9, v9, v28
	ds_swizzle_b32 v28, v9 offset:swizzle(SWAP,1)
	s_waitcnt lgkmcnt(0)
	v_add_f32_e32 v9, v9, v28
	v_mov_b32_e32 v28, 0x3727c5ac
	v_fmamk_f32 v9, v9, 0x3a800000, v28
	v_mul_f32_e32 v28, 0x4b800000, v9
	v_cmp_gt_f32_e32 vcc, s37, v9
	s_nop 1
	v_cndmask_b32_e32 v9, v9, v28, vcc
	v_rsq_f32_e32 v9, v9
	s_nop 0
	v_mul_f32_e32 v28, 0x45800000, v9
	v_cndmask_b32_e32 v30, v9, v28, vcc
	v_pk_mul_f32 v[114:115], v[114:115], v[30:31] op_sel_hi:[1,0]
	v_pk_mul_f32 v[116:117], v[116:117], v[30:31] op_sel_hi:[1,0]
	v_pk_fma_f32 v[34:35], v[140:141], v[114:115], v[98:99]
	v_pk_fma_f32 v[36:37], v[142:143], v[116:117], v[100:101]
	global_store_dwordx4 v[86:87], v[34:37], off sc1 nt
	v_pk_fma_f32 v[114:115], v[226:227], v[34:35], v[210:211]
	v_pk_fma_f32 v[116:117], v[228:229], v[36:37], v[212:213]
	s_nop 0
	v_cvt_pk_bf16_f32 v50, v114, v115
	v_cvt_pk_bf16_f32 v51, v116, v117
	global_store_dwordx2 v[88:89], v[50:51], off sc1
	v_pk_mul_f32 v[118:119], v[118:119], v[30:31] op_sel_hi:[1,0]
	v_pk_mul_f32 v[120:121], v[120:121], v[30:31] op_sel_hi:[1,0]
	v_pk_fma_f32 v[38:39], v[144:145], v[118:119], v[102:103]
	v_pk_fma_f32 v[40:41], v[146:147], v[120:121], v[104:105]
	global_store_dwordx4 v[86:87], v[38:41], off offset:1024 sc1 nt
	v_pk_fma_f32 v[118:119], v[230:231], v[38:39], v[214:215]
	v_pk_fma_f32 v[120:121], v[232:233], v[40:41], v[216:217]
	s_nop 0
	v_cvt_pk_bf16_f32 v52, v118, v119
	v_cvt_pk_bf16_f32 v53, v120, v121
	global_store_dwordx2 v[88:89], v[52:53], off offset:512 sc1
	v_pk_mul_f32 v[122:123], v[122:123], v[30:31] op_sel_hi:[1,0]
	v_pk_mul_f32 v[124:125], v[124:125], v[30:31] op_sel_hi:[1,0]
	v_pk_fma_f32 v[42:43], v[148:149], v[122:123], v[106:107]
	v_pk_fma_f32 v[44:45], v[150:151], v[124:125], v[108:109]
	global_store_dwordx4 v[86:87], v[42:45], off offset:2048 sc1 nt
	v_pk_fma_f32 v[122:123], v[234:235], v[42:43], v[218:219]
	v_pk_fma_f32 v[124:125], v[236:237], v[44:45], v[220:221]
	s_nop 0
	v_cvt_pk_bf16_f32 v54, v122, v123
	v_cvt_pk_bf16_f32 v55, v124, v125
	global_store_dwordx2 v[88:89], v[54:55], off offset:1024 sc1
	v_pk_mul_f32 v[126:127], v[126:127], v[30:31] op_sel_hi:[1,0]
	v_pk_mul_f32 v[128:129], v[128:129], v[30:31] op_sel_hi:[1,0]
	v_pk_fma_f32 v[46:47], v[152:153], v[126:127], v[110:111]
	v_pk_fma_f32 v[48:49], v[154:155], v[128:129], v[112:113]
	global_store_dwordx4 v[86:87], v[46:49], off offset:3072 sc1 nt
	v_pk_fma_f32 v[126:127], v[238:239], v[46:47], v[222:223]
	v_pk_fma_f32 v[128:129], v[240:241], v[48:49], v[224:225]
	s_nop 0
	v_cvt_pk_bf16_f32 v56, v126, v127
	v_cvt_pk_bf16_f32 v57, v128, v129
	global_store_dwordx2 v[88:89], v[56:57], off offset:1536 sc1
	v_lshl_add_u64 v[86:87], v[86:87], 0, s[0:1]
	v_lshl_add_u64 v[88:89], v[88:89], 0, s[20:21]
	global_load_dwordx4 v[34:37], v[82:83], off nt
	global_load_dwordx4 v[38:41], v[82:83], off offset:1024 nt
	global_load_dwordx4 v[42:45], v[82:83], off offset:2048 nt
	global_load_dwordx4 v[46:49], v[82:83], off offset:3072 nt
	global_load_dwordx2 v[50:51], v[84:85], off
	global_load_dwordx2 v[52:53], v[84:85], off offset:512
	global_load_dwordx2 v[54:55], v[84:85], off offset:1024
	global_load_dwordx2 v[56:57], v[84:85], off offset:1536
	v_lshl_add_u64 v[82:83], v[82:83], 0, s[0:1]
	v_lshl_add_u64 v[84:85], v[84:85], 0, s[20:21]
	s_waitcnt vmcnt(32)
	v_lshlrev_b32_e32 v156, 16, v74
	v_and_b32_e32 v157, 0xffff0000, v74
	v_lshlrev_b32_e32 v74, 16, v75
	v_and_b32_e32 v75, 0xffff0000, v75
	v_lshlrev_b32_e32 v158, 16, v76
	v_and_b32_e32 v159, 0xffff0000, v76
	v_lshlrev_b32_e32 v76, 16, v77
	v_and_b32_e32 v77, 0xffff0000, v77
	v_lshlrev_b32_e32 v160, 16, v78
	v_and_b32_e32 v161, 0xffff0000, v78
	v_lshlrev_b32_e32 v78, 16, v79
	v_and_b32_e32 v79, 0xffff0000, v79
	v_lshlrev_b32_e32 v162, 16, v80
	v_and_b32_e32 v163, 0xffff0000, v80
	v_lshlrev_b32_e32 v80, 16, v81
	v_and_b32_e32 v81, 0xffff0000, v81
	v_pk_mul_f32 v[114:115], v[194:195], v[156:157]
	v_pk_mul_f32 v[116:117], v[196:197], v[74:75]
	v_pk_mul_f32 v[118:119], v[198:199], v[158:159]
	v_pk_mul_f32 v[120:121], v[200:201], v[76:77]
	v_pk_mul_f32 v[122:123], v[202:203], v[160:161]
	v_pk_mul_f32 v[124:125], v[204:205], v[78:79]
	v_pk_mul_f32 v[126:127], v[206:207], v[162:163]
	v_pk_mul_f32 v[128:129], v[208:209], v[80:81]
	v_pk_mul_f32 v[114:115], v[10:11], v[114:115]
	v_pk_mul_f32 v[116:117], v[10:11], v[116:117]
	v_pk_mul_f32 v[118:119], v[10:11], v[118:119]
	v_pk_mul_f32 v[120:121], v[10:11], v[120:121]
	v_pk_mul_f32 v[122:123], v[10:11], v[122:123]
	v_pk_mul_f32 v[124:125], v[10:11], v[124:125]
	v_pk_mul_f32 v[126:127], v[10:11], v[126:127]
	v_pk_mul_f32 v[128:129], v[10:11], v[128:129]
	v_pk_fma_f32 v[114:115], v[58:59], s[28:29], v[114:115] op_sel_hi:[1,0,1]
	v_pk_fma_f32 v[116:117], v[60:61], s[28:29], v[116:117] op_sel_hi:[1,0,1]
	v_pk_fma_f32 v[118:119], v[62:63], s[28:29], v[118:119] op_sel_hi:[1,0,1]
	v_pk_fma_f32 v[120:121], v[64:65], s[28:29], v[120:121] op_sel_hi:[1,0,1]
	v_pk_fma_f32 v[122:123], v[66:67], s[28:29], v[122:123] op_sel_hi:[1,0,1]
	v_pk_fma_f32 v[124:125], v[68:69], s[28:29], v[124:125] op_sel_hi:[1,0,1]
	v_pk_fma_f32 v[126:127], v[70:71], s[28:29], v[126:127] op_sel_hi:[1,0,1]
	v_pk_fma_f32 v[128:129], v[72:73], s[28:29], v[128:129] op_sel_hi:[1,0,1]
	v_add_f32_e32 v164, v114, v115
	v_add_f32_e32 v165, v116, v117
	v_add_f32_e32 v166, v118, v119
	v_add_f32_e32 v167, v120, v121
	v_add_f32_e32 v168, v122, v123
	v_add_f32_e32 v169, v124, v125
	v_add_f32_e32 v242, v126, v127
	v_add_f32_e32 v243, v128, v129
	v_add_f32_e32 v164, v164, v165
	v_add_f32_e32 v166, v166, v167
	v_add_f32_e32 v168, v168, v169
	v_add_f32_e32 v242, v242, v243
	v_add_f32_e32 v9, 0, v164
	v_add_f32_e32 v9, v9, v166
	v_add_f32_e32 v9, v9, v168
	v_add_f32_e32 v9, v9, v242
	ds_bpermute_b32 v28, v96, v9
	s_waitcnt lgkmcnt(0)
	v_add_f32_e32 v9, v9, v28
	ds_swizzle_b32 v28, v9 offset:swizzle(SWAP,16)
	s_waitcnt lgkmcnt(0)
	v_add_f32_e32 v9, v9, v28
	ds_swizzle_b32 v28, v9 offset:swizzle(SWAP,8)
	s_waitcnt lgkmcnt(0)
	v_add_f32_e32 v9, v9, v28
	ds_swizzle_b32 v28, v9 offset:swizzle(SWAP,4)
	s_waitcnt lgkmcnt(0)
	v_add_f32_e32 v9, v9, v28
	ds_swizzle_b32 v28, v9 offset:swizzle(SWAP,2)
	s_waitcnt lgkmcnt(0)
	v_add_f32_e32 v9, v9, v28
	ds_swizzle_b32 v28, v9 offset:swizzle(SWAP,1)
	s_waitcnt lgkmcnt(0)
	v_add_f32_e32 v9, v9, v28
	v_fmac_f32_e32 v114, 0xba800000, v9
	v_fmac_f32_e32 v115, 0xba800000, v9
	v_fmac_f32_e32 v116, 0xba800000, v9
	v_fmac_f32_e32 v117, 0xba800000, v9
	v_fmac_f32_e32 v118, 0xba800000, v9
	v_fmac_f32_e32 v119, 0xba800000, v9
	v_fmac_f32_e32 v120, 0xba800000, v9
	v_fmac_f32_e32 v121, 0xba800000, v9
	v_fmac_f32_e32 v122, 0xba800000, v9
	v_fmac_f32_e32 v123, 0xba800000, v9
	v_fmac_f32_e32 v124, 0xba800000, v9
	v_fmac_f32_e32 v125, 0xba800000, v9
	v_fmac_f32_e32 v126, 0xba800000, v9
	v_fmac_f32_e32 v127, 0xba800000, v9
	v_fmac_f32_e32 v128, 0xba800000, v9
	v_fmac_f32_e32 v129, 0xba800000, v9
	v_pk_mul_f32 v[244:245], v[114:115], v[114:115]
	v_pk_mul_f32 v[246:247], v[116:117], v[116:117]
	v_add_f32_e32 v244, v245, v244
	v_add_f32_e32 v246, v246, v247
	v_add_f32_e32 v164, v244, v246
	v_pk_mul_f32 v[244:245], v[118:119], v[118:119]
	v_pk_mul_f32 v[246:247], v[120:121], v[120:121]
	v_add_f32_e32 v244, v245, v244
	v_add_f32_e32 v246, v246, v247
	v_add_f32_e32 v165, v244, v246
	v_mul_f32_e32 v248, v122, v122
	v_mul_f32_e32 v249, v124, v124
	v_fmac_f32_e32 v248, v123, v123
	v_fmac_f32_e32 v249, v125, v125
	v_add_f32_e32 v166, v248, v249
	v_pk_mul_f32 v[244:245], v[126:127], v[126:127]
	v_pk_mul_f32 v[246:247], v[128:129], v[128:129]
	v_add_f32_e32 v244, v244, v245
	v_add_f32_e32 v246, v246, v247
	v_add_f32_e32 v167, v244, v246
	v_add_f32_e32 v164, v164, v165
	v_add_f32_e32 v164, v166, v164
	v_add_f32_e32 v9, v167, v164
	ds_bpermute_b32 v28, v96, v9
	s_waitcnt lgkmcnt(0)
	v_add_f32_e32 v9, v9, v28
	ds_swizzle_b32 v28, v9 offset:swizzle(SWAP,16)
	s_waitcnt lgkmcnt(0)
	v_add_f32_e32 v9, v9, v28
	ds_swizzle_b32 v28, v9 offset:swizzle(SWAP,8)
	s_waitcnt lgkmcnt(0)
	v_add_f32_e32 v9, v9, v28
	ds_swizzle_b32 v28, v9 offset:swizzle(SWAP,4)
	s_waitcnt lgkmcnt(0)
	v_add_f32_e32 v9, v9, v28
	ds_swizzle_b32 v28, v9 offset:swizzle(SWAP,2)
	s_waitcnt lgkmcnt(0)
	v_add_f32_e32 v9, v9, v28
	ds_swizzle_b32 v28, v9 offset:swizzle(SWAP,1)
	s_waitcnt lgkmcnt(0)
	v_add_f32_e32 v9, v9, v28
	v_mov_b32_e32 v28, 0x3727c5ac
	v_fmamk_f32 v9, v9, 0x3a800000, v28
	v_mul_f32_e32 v28, 0x4b800000, v9
	v_cmp_gt_f32_e32 vcc, s37, v9
	s_nop 1
	v_cndmask_b32_e32 v9, v9, v28, vcc
	v_rsq_f32_e32 v9, v9
	s_nop 0
	v_mul_f32_e32 v28, 0x45800000, v9
	v_cndmask_b32_e32 v30, v9, v28, vcc
	v_pk_mul_f32 v[114:115], v[114:115], v[30:31] op_sel_hi:[1,0]
	v_pk_mul_f32 v[116:117], v[116:117], v[30:31] op_sel_hi:[1,0]
	v_pk_fma_f32 v[58:59], v[140:141], v[114:115], v[98:99]
	v_pk_fma_f32 v[60:61], v[142:143], v[116:117], v[100:101]
	global_store_dwordx4 v[86:87], v[58:61], off sc1 nt
	v_pk_fma_f32 v[114:115], v[226:227], v[58:59], v[210:211]
	v_pk_fma_f32 v[116:117], v[228:229], v[60:61], v[212:213]
	s_nop 0
	v_cvt_pk_bf16_f32 v74, v114, v115
	v_cvt_pk_bf16_f32 v75, v116, v117
	global_store_dwordx2 v[88:89], v[74:75], off sc1
	v_pk_mul_f32 v[118:119], v[118:119], v[30:31] op_sel_hi:[1,0]
	v_pk_mul_f32 v[120:121], v[120:121], v[30:31] op_sel_hi:[1,0]
	v_pk_fma_f32 v[62:63], v[144:145], v[118:119], v[102:103]
	v_pk_fma_f32 v[64:65], v[146:147], v[120:121], v[104:105]
	global_store_dwordx4 v[86:87], v[62:65], off offset:1024 sc1 nt
	v_pk_fma_f32 v[118:119], v[230:231], v[62:63], v[214:215]
	v_pk_fma_f32 v[120:121], v[232:233], v[64:65], v[216:217]
	s_nop 0
	v_cvt_pk_bf16_f32 v76, v118, v119
	v_cvt_pk_bf16_f32 v77, v120, v121
	global_store_dwordx2 v[88:89], v[76:77], off offset:512 sc1
	v_pk_mul_f32 v[122:123], v[122:123], v[30:31] op_sel_hi:[1,0]
	v_pk_mul_f32 v[124:125], v[124:125], v[30:31] op_sel_hi:[1,0]
	v_pk_fma_f32 v[66:67], v[148:149], v[122:123], v[106:107]
	v_pk_fma_f32 v[68:69], v[150:151], v[124:125], v[108:109]
	global_store_dwordx4 v[86:87], v[66:69], off offset:2048 sc1 nt
	v_pk_fma_f32 v[122:123], v[234:235], v[66:67], v[218:219]
	v_pk_fma_f32 v[124:125], v[236:237], v[68:69], v[220:221]
	s_nop 0
	v_cvt_pk_bf16_f32 v78, v122, v123
	v_cvt_pk_bf16_f32 v79, v124, v125
	global_store_dwordx2 v[88:89], v[78:79], off offset:1024 sc1
	v_pk_mul_f32 v[126:127], v[126:127], v[30:31] op_sel_hi:[1,0]
	v_pk_mul_f32 v[128:129], v[128:129], v[30:31] op_sel_hi:[1,0]
	v_pk_fma_f32 v[70:71], v[152:153], v[126:127], v[110:111]
	v_pk_fma_f32 v[72:73], v[154:155], v[128:129], v[112:113]
	global_store_dwordx4 v[86:87], v[70:73], off offset:3072 sc1 nt
	v_pk_fma_f32 v[126:127], v[238:239], v[70:71], v[222:223]
	v_pk_fma_f32 v[128:129], v[240:241], v[72:73], v[224:225]
	s_nop 0
	v_cvt_pk_bf16_f32 v80, v126, v127
	v_cvt_pk_bf16_f32 v81, v128, v129
	global_store_dwordx2 v[88:89], v[80:81], off offset:1536 sc1
	v_lshl_add_u64 v[86:87], v[86:87], 0, s[0:1]
	v_lshl_add_u64 v[88:89], v[88:89], 0, s[20:21]
	global_load_dwordx4 v[58:61], v[82:83], off nt
	global_load_dwordx4 v[62:65], v[82:83], off offset:1024 nt
	global_load_dwordx4 v[66:69], v[82:83], off offset:2048 nt
	global_load_dwordx4 v[70:73], v[82:83], off offset:3072 nt
	global_load_dwordx2 v[74:75], v[84:85], off
	global_load_dwordx2 v[76:77], v[84:85], off offset:512
	global_load_dwordx2 v[78:79], v[84:85], off offset:1024
	global_load_dwordx2 v[80:81], v[84:85], off offset:1536
	v_lshl_add_u64 v[82:83], v[82:83], 0, s[0:1]
	v_lshl_add_u64 v[84:85], v[84:85], 0, s[20:21]
	s_waitcnt vmcnt(32)
	v_lshlrev_b32_e32 v156, 16, v12
	v_and_b32_e32 v157, 0xffff0000, v12
	v_lshlrev_b32_e32 v12, 16, v13
	v_and_b32_e32 v13, 0xffff0000, v13
	v_lshlrev_b32_e32 v158, 16, v14
	v_and_b32_e32 v159, 0xffff0000, v14
	v_lshlrev_b32_e32 v14, 16, v15
	v_and_b32_e32 v15, 0xffff0000, v15
	v_lshlrev_b32_e32 v160, 16, v16
	v_and_b32_e32 v161, 0xffff0000, v16
	v_lshlrev_b32_e32 v16, 16, v17
	v_and_b32_e32 v17, 0xffff0000, v17
	v_lshlrev_b32_e32 v162, 16, v18
	v_and_b32_e32 v163, 0xffff0000, v18
	v_lshlrev_b32_e32 v18, 16, v19
	v_and_b32_e32 v19, 0xffff0000, v19
	v_pk_mul_f32 v[114:115], v[194:195], v[156:157]
	v_pk_mul_f32 v[116:117], v[196:197], v[12:13]
	v_pk_mul_f32 v[118:119], v[198:199], v[158:159]
	v_pk_mul_f32 v[120:121], v[200:201], v[14:15]
	v_pk_mul_f32 v[122:123], v[202:203], v[160:161]
	v_pk_mul_f32 v[124:125], v[204:205], v[16:17]
	v_pk_mul_f32 v[126:127], v[206:207], v[162:163]
	v_pk_mul_f32 v[128:129], v[208:209], v[18:19]
	v_pk_mul_f32 v[114:115], v[10:11], v[114:115]
	v_pk_mul_f32 v[116:117], v[10:11], v[116:117]
	v_pk_mul_f32 v[118:119], v[10:11], v[118:119]
	v_pk_mul_f32 v[120:121], v[10:11], v[120:121]
	v_pk_mul_f32 v[122:123], v[10:11], v[122:123]
	v_pk_mul_f32 v[124:125], v[10:11], v[124:125]
	v_pk_mul_f32 v[126:127], v[10:11], v[126:127]
	v_pk_mul_f32 v[128:129], v[10:11], v[128:129]
	v_pk_fma_f32 v[114:115], v[20:21], s[28:29], v[114:115] op_sel_hi:[1,0,1]
	v_pk_fma_f32 v[116:117], v[22:23], s[28:29], v[116:117] op_sel_hi:[1,0,1]
	v_pk_fma_f32 v[118:119], v[24:25], s[28:29], v[118:119] op_sel_hi:[1,0,1]
	v_pk_fma_f32 v[120:121], v[26:27], s[28:29], v[120:121] op_sel_hi:[1,0,1]
	v_pk_fma_f32 v[122:123], v[0:1], s[28:29], v[122:123] op_sel_hi:[1,0,1]
	v_pk_fma_f32 v[124:125], v[2:3], s[28:29], v[124:125] op_sel_hi:[1,0,1]
	v_pk_fma_f32 v[126:127], v[4:5], s[28:29], v[126:127] op_sel_hi:[1,0,1]
	v_pk_fma_f32 v[128:129], v[6:7], s[28:29], v[128:129] op_sel_hi:[1,0,1]
	v_add_f32_e32 v164, v114, v115
	v_add_f32_e32 v165, v116, v117
	v_add_f32_e32 v166, v118, v119
	v_add_f32_e32 v167, v120, v121
	v_add_f32_e32 v168, v122, v123
	v_add_f32_e32 v169, v124, v125
	v_add_f32_e32 v242, v126, v127
	v_add_f32_e32 v243, v128, v129
	v_add_f32_e32 v164, v164, v165
	v_add_f32_e32 v166, v166, v167
	v_add_f32_e32 v168, v168, v169
	v_add_f32_e32 v242, v242, v243
	v_add_f32_e32 v9, 0, v164
	v_add_f32_e32 v9, v9, v166
	v_add_f32_e32 v9, v9, v168
	v_add_f32_e32 v9, v9, v242
	ds_bpermute_b32 v28, v96, v9
	s_waitcnt lgkmcnt(0)
	v_add_f32_e32 v9, v9, v28
	ds_swizzle_b32 v28, v9 offset:swizzle(SWAP,16)
	s_waitcnt lgkmcnt(0)
	v_add_f32_e32 v9, v9, v28
	ds_swizzle_b32 v28, v9 offset:swizzle(SWAP,8)
	s_waitcnt lgkmcnt(0)
	v_add_f32_e32 v9, v9, v28
	ds_swizzle_b32 v28, v9 offset:swizzle(SWAP,4)
	s_waitcnt lgkmcnt(0)
	v_add_f32_e32 v9, v9, v28
	ds_swizzle_b32 v28, v9 offset:swizzle(SWAP,2)
	s_waitcnt lgkmcnt(0)
	v_add_f32_e32 v9, v9, v28
	ds_swizzle_b32 v28, v9 offset:swizzle(SWAP,1)
	s_waitcnt lgkmcnt(0)
	v_add_f32_e32 v9, v9, v28
	v_fmac_f32_e32 v114, 0xba800000, v9
	v_fmac_f32_e32 v115, 0xba800000, v9
	v_fmac_f32_e32 v116, 0xba800000, v9
	v_fmac_f32_e32 v117, 0xba800000, v9
	v_fmac_f32_e32 v118, 0xba800000, v9
	v_fmac_f32_e32 v119, 0xba800000, v9
	v_fmac_f32_e32 v120, 0xba800000, v9
	v_fmac_f32_e32 v121, 0xba800000, v9
	v_fmac_f32_e32 v122, 0xba800000, v9
	v_fmac_f32_e32 v123, 0xba800000, v9
	v_fmac_f32_e32 v124, 0xba800000, v9
	v_fmac_f32_e32 v125, 0xba800000, v9
	v_fmac_f32_e32 v126, 0xba800000, v9
	v_fmac_f32_e32 v127, 0xba800000, v9
	v_fmac_f32_e32 v128, 0xba800000, v9
	v_fmac_f32_e32 v129, 0xba800000, v9
	v_pk_mul_f32 v[244:245], v[114:115], v[114:115]
	v_pk_mul_f32 v[246:247], v[116:117], v[116:117]
	v_add_f32_e32 v244, v245, v244
	v_add_f32_e32 v246, v246, v247
	v_add_f32_e32 v164, v244, v246
	v_pk_mul_f32 v[244:245], v[118:119], v[118:119]
	v_pk_mul_f32 v[246:247], v[120:121], v[120:121]
	v_add_f32_e32 v244, v245, v244
	v_add_f32_e32 v246, v246, v247
	v_add_f32_e32 v165, v244, v246
	v_mul_f32_e32 v248, v122, v122
	v_mul_f32_e32 v249, v124, v124
	v_fmac_f32_e32 v248, v123, v123
	v_fmac_f32_e32 v249, v125, v125
	v_add_f32_e32 v166, v248, v249
	v_pk_mul_f32 v[244:245], v[126:127], v[126:127]
	v_pk_mul_f32 v[246:247], v[128:129], v[128:129]
	v_add_f32_e32 v244, v244, v245
	v_add_f32_e32 v246, v246, v247
	v_add_f32_e32 v167, v244, v246
	v_add_f32_e32 v164, v164, v165
	v_add_f32_e32 v164, v166, v164
	v_add_f32_e32 v9, v167, v164
	ds_bpermute_b32 v28, v96, v9
	s_waitcnt lgkmcnt(0)
	v_add_f32_e32 v9, v9, v28
	ds_swizzle_b32 v28, v9 offset:swizzle(SWAP,16)
	s_waitcnt lgkmcnt(0)
	v_add_f32_e32 v9, v9, v28
	ds_swizzle_b32 v28, v9 offset:swizzle(SWAP,8)
	s_waitcnt lgkmcnt(0)
	v_add_f32_e32 v9, v9, v28
	ds_swizzle_b32 v28, v9 offset:swizzle(SWAP,4)
	s_waitcnt lgkmcnt(0)
	v_add_f32_e32 v9, v9, v28
	ds_swizzle_b32 v28, v9 offset:swizzle(SWAP,2)
	s_waitcnt lgkmcnt(0)
	v_add_f32_e32 v9, v9, v28
	ds_swizzle_b32 v28, v9 offset:swizzle(SWAP,1)
	s_waitcnt lgkmcnt(0)
	v_add_f32_e32 v9, v9, v28
	v_mov_b32_e32 v28, 0x3727c5ac
	v_fmamk_f32 v9, v9, 0x3a800000, v28
	v_mul_f32_e32 v28, 0x4b800000, v9
	v_cmp_gt_f32_e32 vcc, s37, v9
	s_nop 1
	v_cndmask_b32_e32 v9, v9, v28, vcc
	v_rsq_f32_e32 v9, v9
	s_nop 0
	v_mul_f32_e32 v28, 0x45800000, v9
	v_cndmask_b32_e32 v30, v9, v28, vcc
	v_pk_mul_f32 v[114:115], v[114:115], v[30:31] op_sel_hi:[1,0]
	v_pk_mul_f32 v[116:117], v[116:117], v[30:31] op_sel_hi:[1,0]
	v_pk_fma_f32 v[20:21], v[140:141], v[114:115], v[98:99]
	v_pk_fma_f32 v[22:23], v[142:143], v[116:117], v[100:101]
	global_store_dwordx4 v[86:87], v[20:23], off sc1 nt
	v_pk_fma_f32 v[114:115], v[226:227], v[20:21], v[210:211]
	v_pk_fma_f32 v[116:117], v[228:229], v[22:23], v[212:213]
	s_nop 0
	v_cvt_pk_bf16_f32 v12, v114, v115
	v_cvt_pk_bf16_f32 v13, v116, v117
	global_store_dwordx2 v[88:89], v[12:13], off sc1
	v_pk_mul_f32 v[118:119], v[118:119], v[30:31] op_sel_hi:[1,0]
	v_pk_mul_f32 v[120:121], v[120:121], v[30:31] op_sel_hi:[1,0]
	v_pk_fma_f32 v[24:25], v[144:145], v[118:119], v[102:103]
	v_pk_fma_f32 v[26:27], v[146:147], v[120:121], v[104:105]
	global_store_dwordx4 v[86:87], v[24:27], off offset:1024 sc1 nt
	v_pk_fma_f32 v[118:119], v[230:231], v[24:25], v[214:215]
	v_pk_fma_f32 v[120:121], v[232:233], v[26:27], v[216:217]
	s_nop 0
	v_cvt_pk_bf16_f32 v14, v118, v119
	v_cvt_pk_bf16_f32 v15, v120, v121
	global_store_dwordx2 v[88:89], v[14:15], off offset:512 sc1
	v_pk_mul_f32 v[122:123], v[122:123], v[30:31] op_sel_hi:[1,0]
	v_pk_mul_f32 v[124:125], v[124:125], v[30:31] op_sel_hi:[1,0]
	v_pk_fma_f32 v[0:1], v[148:149], v[122:123], v[106:107]
	v_pk_fma_f32 v[2:3], v[150:151], v[124:125], v[108:109]
	global_store_dwordx4 v[86:87], v[0:3], off offset:2048 sc1 nt
	v_pk_fma_f32 v[122:123], v[234:235], v[0:1], v[218:219]
	v_pk_fma_f32 v[124:125], v[236:237], v[2:3], v[220:221]
	s_nop 0
	v_cvt_pk_bf16_f32 v16, v122, v123
	v_cvt_pk_bf16_f32 v17, v124, v125
	global_store_dwordx2 v[88:89], v[16:17], off offset:1024 sc1
	v_pk_mul_f32 v[126:127], v[126:127], v[30:31] op_sel_hi:[1,0]
	v_pk_mul_f32 v[128:129], v[128:129], v[30:31] op_sel_hi:[1,0]
	v_pk_fma_f32 v[4:5], v[152:153], v[126:127], v[110:111]
	v_pk_fma_f32 v[6:7], v[154:155], v[128:129], v[112:113]
	global_store_dwordx4 v[86:87], v[4:7], off offset:3072 sc1 nt
	v_pk_fma_f32 v[126:127], v[238:239], v[4:5], v[222:223]
	v_pk_fma_f32 v[128:129], v[240:241], v[6:7], v[224:225]
	s_nop 0
	v_cvt_pk_bf16_f32 v18, v126, v127
	v_cvt_pk_bf16_f32 v19, v128, v129
	global_store_dwordx2 v[88:89], v[18:19], off offset:1536 sc1
	v_lshl_add_u64 v[86:87], v[86:87], 0, s[0:1]
	v_lshl_add_u64 v[88:89], v[88:89], 0, s[20:21]
	global_load_dwordx4 v[20:23], v[82:83], off nt
	global_load_dwordx4 v[24:27], v[82:83], off offset:1024 nt
	global_load_dwordx4 v[0:3], v[82:83], off offset:2048 nt
	global_load_dwordx4 v[4:7], v[82:83], off offset:3072 nt
	global_load_dwordx2 v[12:13], v[84:85], off
	global_load_dwordx2 v[14:15], v[84:85], off offset:512
	global_load_dwordx2 v[16:17], v[84:85], off offset:1024
	global_load_dwordx2 v[18:19], v[84:85], off offset:1536
	v_lshl_add_u64 v[82:83], v[82:83], 0, s[0:1]
	v_lshl_add_u64 v[84:85], v[84:85], 0, s[20:21]
	s_waitcnt vmcnt(32)
	v_lshlrev_b32_e32 v156, 16, v50
	v_and_b32_e32 v157, 0xffff0000, v50
	v_lshlrev_b32_e32 v50, 16, v51
	v_and_b32_e32 v51, 0xffff0000, v51
	v_lshlrev_b32_e32 v158, 16, v52
	v_and_b32_e32 v159, 0xffff0000, v52
	v_lshlrev_b32_e32 v52, 16, v53
	v_and_b32_e32 v53, 0xffff0000, v53
	v_lshlrev_b32_e32 v160, 16, v54
	v_and_b32_e32 v161, 0xffff0000, v54
	v_lshlrev_b32_e32 v54, 16, v55
	v_and_b32_e32 v55, 0xffff0000, v55
	v_lshlrev_b32_e32 v162, 16, v56
	v_and_b32_e32 v163, 0xffff0000, v56
	v_lshlrev_b32_e32 v56, 16, v57
	v_and_b32_e32 v57, 0xffff0000, v57
	v_pk_mul_f32 v[114:115], v[194:195], v[156:157]
	v_pk_mul_f32 v[116:117], v[196:197], v[50:51]
	v_pk_mul_f32 v[118:119], v[198:199], v[158:159]
	v_pk_mul_f32 v[120:121], v[200:201], v[52:53]
	v_pk_mul_f32 v[122:123], v[202:203], v[160:161]
	v_pk_mul_f32 v[124:125], v[204:205], v[54:55]
	v_pk_mul_f32 v[126:127], v[206:207], v[162:163]
	v_pk_mul_f32 v[128:129], v[208:209], v[56:57]
	v_pk_mul_f32 v[114:115], v[10:11], v[114:115]
	v_pk_mul_f32 v[116:117], v[10:11], v[116:117]
	v_pk_mul_f32 v[118:119], v[10:11], v[118:119]
	v_pk_mul_f32 v[120:121], v[10:11], v[120:121]
	v_pk_mul_f32 v[122:123], v[10:11], v[122:123]
	v_pk_mul_f32 v[124:125], v[10:11], v[124:125]
	v_pk_mul_f32 v[126:127], v[10:11], v[126:127]
	v_pk_mul_f32 v[128:129], v[10:11], v[128:129]
	v_pk_fma_f32 v[114:115], v[34:35], s[28:29], v[114:115] op_sel_hi:[1,0,1]
	v_pk_fma_f32 v[116:117], v[36:37], s[28:29], v[116:117] op_sel_hi:[1,0,1]
	v_pk_fma_f32 v[118:119], v[38:39], s[28:29], v[118:119] op_sel_hi:[1,0,1]
	v_pk_fma_f32 v[120:121], v[40:41], s[28:29], v[120:121] op_sel_hi:[1,0,1]
	v_pk_fma_f32 v[122:123], v[42:43], s[28:29], v[122:123] op_sel_hi:[1,0,1]
	v_pk_fma_f32 v[124:125], v[44:45], s[28:29], v[124:125] op_sel_hi:[1,0,1]
	v_pk_fma_f32 v[126:127], v[46:47], s[28:29], v[126:127] op_sel_hi:[1,0,1]
	v_pk_fma_f32 v[128:129], v[48:49], s[28:29], v[128:129] op_sel_hi:[1,0,1]
	v_add_f32_e32 v164, v114, v115
	v_add_f32_e32 v165, v116, v117
	v_add_f32_e32 v166, v118, v119
	v_add_f32_e32 v167, v120, v121
	v_add_f32_e32 v168, v122, v123
	v_add_f32_e32 v169, v124, v125
	v_add_f32_e32 v242, v126, v127
	v_add_f32_e32 v243, v128, v129
	v_add_f32_e32 v164, v164, v165
	v_add_f32_e32 v166, v166, v167
	v_add_f32_e32 v168, v168, v169
	v_add_f32_e32 v242, v242, v243
	v_add_f32_e32 v9, 0, v164
	v_add_f32_e32 v9, v9, v166
	v_add_f32_e32 v9, v9, v168
	v_add_f32_e32 v9, v9, v242
	ds_bpermute_b32 v28, v96, v9
	s_waitcnt lgkmcnt(0)
	v_add_f32_e32 v9, v9, v28
	ds_swizzle_b32 v28, v9 offset:swizzle(SWAP,16)
	s_waitcnt lgkmcnt(0)
	v_add_f32_e32 v9, v9, v28
	ds_swizzle_b32 v28, v9 offset:swizzle(SWAP,8)
	s_waitcnt lgkmcnt(0)
	v_add_f32_e32 v9, v9, v28
	ds_swizzle_b32 v28, v9 offset:swizzle(SWAP,4)
	s_waitcnt lgkmcnt(0)
	v_add_f32_e32 v9, v9, v28
	ds_swizzle_b32 v28, v9 offset:swizzle(SWAP,2)
	s_waitcnt lgkmcnt(0)
	v_add_f32_e32 v9, v9, v28
	ds_swizzle_b32 v28, v9 offset:swizzle(SWAP,1)
	s_waitcnt lgkmcnt(0)
	v_add_f32_e32 v9, v9, v28
	v_fmac_f32_e32 v114, 0xba800000, v9
	v_fmac_f32_e32 v115, 0xba800000, v9
	v_fmac_f32_e32 v116, 0xba800000, v9
	v_fmac_f32_e32 v117, 0xba800000, v9
	v_fmac_f32_e32 v118, 0xba800000, v9
	v_fmac_f32_e32 v119, 0xba800000, v9
	v_fmac_f32_e32 v120, 0xba800000, v9
	v_fmac_f32_e32 v121, 0xba800000, v9
	v_fmac_f32_e32 v122, 0xba800000, v9
	v_fmac_f32_e32 v123, 0xba800000, v9
	v_fmac_f32_e32 v124, 0xba800000, v9
	v_fmac_f32_e32 v125, 0xba800000, v9
	v_fmac_f32_e32 v126, 0xba800000, v9
	v_fmac_f32_e32 v127, 0xba800000, v9
	v_fmac_f32_e32 v128, 0xba800000, v9
	v_fmac_f32_e32 v129, 0xba800000, v9
	v_pk_mul_f32 v[244:245], v[114:115], v[114:115]
	v_pk_mul_f32 v[246:247], v[116:117], v[116:117]
	v_add_f32_e32 v244, v245, v244
	v_add_f32_e32 v246, v246, v247
	v_add_f32_e32 v164, v244, v246
	v_pk_mul_f32 v[244:245], v[118:119], v[118:119]
	v_pk_mul_f32 v[246:247], v[120:121], v[120:121]
	v_add_f32_e32 v244, v245, v244
	v_add_f32_e32 v246, v246, v247
	v_add_f32_e32 v165, v244, v246
	v_mul_f32_e32 v248, v122, v122
	v_mul_f32_e32 v249, v124, v124
	v_fmac_f32_e32 v248, v123, v123
	v_fmac_f32_e32 v249, v125, v125
	v_add_f32_e32 v166, v248, v249
	v_pk_mul_f32 v[244:245], v[126:127], v[126:127]
	v_pk_mul_f32 v[246:247], v[128:129], v[128:129]
	v_add_f32_e32 v244, v244, v245
	v_add_f32_e32 v246, v246, v247
	v_add_f32_e32 v167, v244, v246
	v_add_f32_e32 v164, v164, v165
	v_add_f32_e32 v164, v166, v164
	v_add_f32_e32 v9, v167, v164
	ds_bpermute_b32 v28, v96, v9
	s_waitcnt lgkmcnt(0)
	v_add_f32_e32 v9, v9, v28
	ds_swizzle_b32 v28, v9 offset:swizzle(SWAP,16)
	s_waitcnt lgkmcnt(0)
	v_add_f32_e32 v9, v9, v28
	ds_swizzle_b32 v28, v9 offset:swizzle(SWAP,8)
	s_waitcnt lgkmcnt(0)
	v_add_f32_e32 v9, v9, v28
	ds_swizzle_b32 v28, v9 offset:swizzle(SWAP,4)
	s_waitcnt lgkmcnt(0)
	v_add_f32_e32 v9, v9, v28
	ds_swizzle_b32 v28, v9 offset:swizzle(SWAP,2)
	s_waitcnt lgkmcnt(0)
	v_add_f32_e32 v9, v9, v28
	ds_swizzle_b32 v28, v9 offset:swizzle(SWAP,1)
	s_waitcnt lgkmcnt(0)
	v_add_f32_e32 v9, v9, v28
	v_mov_b32_e32 v28, 0x3727c5ac
	v_fmamk_f32 v9, v9, 0x3a800000, v28
	v_mul_f32_e32 v28, 0x4b800000, v9
	v_cmp_gt_f32_e32 vcc, s37, v9
	s_nop 1
	v_cndmask_b32_e32 v9, v9, v28, vcc
	v_rsq_f32_e32 v9, v9
	s_nop 0
	v_mul_f32_e32 v28, 0x45800000, v9
	v_cndmask_b32_e32 v30, v9, v28, vcc
	v_pk_mul_f32 v[114:115], v[114:115], v[30:31] op_sel_hi:[1,0]
	v_pk_mul_f32 v[116:117], v[116:117], v[30:31] op_sel_hi:[1,0]
	v_pk_fma_f32 v[34:35], v[140:141], v[114:115], v[98:99]
	v_pk_fma_f32 v[36:37], v[142:143], v[116:117], v[100:101]
	global_store_dwordx4 v[86:87], v[34:37], off sc1 nt
	v_pk_fma_f32 v[114:115], v[226:227], v[34:35], v[210:211]
	v_pk_fma_f32 v[116:117], v[228:229], v[36:37], v[212:213]
	s_nop 0
	v_cvt_pk_bf16_f32 v50, v114, v115
	v_cvt_pk_bf16_f32 v51, v116, v117
	global_store_dwordx2 v[88:89], v[50:51], off sc1
	v_pk_mul_f32 v[118:119], v[118:119], v[30:31] op_sel_hi:[1,0]
	v_pk_mul_f32 v[120:121], v[120:121], v[30:31] op_sel_hi:[1,0]
	v_pk_fma_f32 v[38:39], v[144:145], v[118:119], v[102:103]
	v_pk_fma_f32 v[40:41], v[146:147], v[120:121], v[104:105]
	global_store_dwordx4 v[86:87], v[38:41], off offset:1024 sc1 nt
	v_pk_fma_f32 v[118:119], v[230:231], v[38:39], v[214:215]
	v_pk_fma_f32 v[120:121], v[232:233], v[40:41], v[216:217]
	s_nop 0
	v_cvt_pk_bf16_f32 v52, v118, v119
	v_cvt_pk_bf16_f32 v53, v120, v121
	global_store_dwordx2 v[88:89], v[52:53], off offset:512 sc1
	v_pk_mul_f32 v[122:123], v[122:123], v[30:31] op_sel_hi:[1,0]
	v_pk_mul_f32 v[124:125], v[124:125], v[30:31] op_sel_hi:[1,0]
	v_pk_fma_f32 v[42:43], v[148:149], v[122:123], v[106:107]
	v_pk_fma_f32 v[44:45], v[150:151], v[124:125], v[108:109]
	global_store_dwordx4 v[86:87], v[42:45], off offset:2048 sc1 nt
	v_pk_fma_f32 v[122:123], v[234:235], v[42:43], v[218:219]
	v_pk_fma_f32 v[124:125], v[236:237], v[44:45], v[220:221]
	s_nop 0
	v_cvt_pk_bf16_f32 v54, v122, v123
	v_cvt_pk_bf16_f32 v55, v124, v125
	global_store_dwordx2 v[88:89], v[54:55], off offset:1024 sc1
	v_pk_mul_f32 v[126:127], v[126:127], v[30:31] op_sel_hi:[1,0]
	v_pk_mul_f32 v[128:129], v[128:129], v[30:31] op_sel_hi:[1,0]
	v_pk_fma_f32 v[46:47], v[152:153], v[126:127], v[110:111]
	v_pk_fma_f32 v[48:49], v[154:155], v[128:129], v[112:113]
	global_store_dwordx4 v[86:87], v[46:49], off offset:3072 sc1 nt
	v_pk_fma_f32 v[126:127], v[238:239], v[46:47], v[222:223]
	v_pk_fma_f32 v[128:129], v[240:241], v[48:49], v[224:225]
	s_nop 0
	v_cvt_pk_bf16_f32 v56, v126, v127
	v_cvt_pk_bf16_f32 v57, v128, v129
	global_store_dwordx2 v[88:89], v[56:57], off offset:1536 sc1
	v_lshl_add_u64 v[86:87], v[86:87], 0, s[0:1]
	v_lshl_add_u64 v[88:89], v[88:89], 0, s[20:21]
	global_load_dwordx4 v[34:37], v[82:83], off nt
	global_load_dwordx4 v[38:41], v[82:83], off offset:1024 nt
	global_load_dwordx4 v[42:45], v[82:83], off offset:2048 nt
	global_load_dwordx4 v[46:49], v[82:83], off offset:3072 nt
	global_load_dwordx2 v[50:51], v[84:85], off
	global_load_dwordx2 v[52:53], v[84:85], off offset:512
	global_load_dwordx2 v[54:55], v[84:85], off offset:1024
	global_load_dwordx2 v[56:57], v[84:85], off offset:1536
	v_lshl_add_u64 v[82:83], v[82:83], 0, s[0:1]
	v_lshl_add_u64 v[84:85], v[84:85], 0, s[20:21]
	s_waitcnt vmcnt(32)
	v_lshlrev_b32_e32 v156, 16, v74
	v_and_b32_e32 v157, 0xffff0000, v74
	v_lshlrev_b32_e32 v74, 16, v75
	v_and_b32_e32 v75, 0xffff0000, v75
	v_lshlrev_b32_e32 v158, 16, v76
	v_and_b32_e32 v159, 0xffff0000, v76
	v_lshlrev_b32_e32 v76, 16, v77
	v_and_b32_e32 v77, 0xffff0000, v77
	v_lshlrev_b32_e32 v160, 16, v78
	v_and_b32_e32 v161, 0xffff0000, v78
	v_lshlrev_b32_e32 v78, 16, v79
	v_and_b32_e32 v79, 0xffff0000, v79
	v_lshlrev_b32_e32 v162, 16, v80
	v_and_b32_e32 v163, 0xffff0000, v80
	v_lshlrev_b32_e32 v80, 16, v81
	v_and_b32_e32 v81, 0xffff0000, v81
	v_pk_mul_f32 v[114:115], v[194:195], v[156:157]
	v_pk_mul_f32 v[116:117], v[196:197], v[74:75]
	v_pk_mul_f32 v[118:119], v[198:199], v[158:159]
	v_pk_mul_f32 v[120:121], v[200:201], v[76:77]
	v_pk_mul_f32 v[122:123], v[202:203], v[160:161]
	v_pk_mul_f32 v[124:125], v[204:205], v[78:79]
	v_pk_mul_f32 v[126:127], v[206:207], v[162:163]
	v_pk_mul_f32 v[128:129], v[208:209], v[80:81]
	v_pk_mul_f32 v[114:115], v[10:11], v[114:115]
	v_pk_mul_f32 v[116:117], v[10:11], v[116:117]
	v_pk_mul_f32 v[118:119], v[10:11], v[118:119]
	v_pk_mul_f32 v[120:121], v[10:11], v[120:121]
	v_pk_mul_f32 v[122:123], v[10:11], v[122:123]
	v_pk_mul_f32 v[124:125], v[10:11], v[124:125]
	v_pk_mul_f32 v[126:127], v[10:11], v[126:127]
	v_pk_mul_f32 v[128:129], v[10:11], v[128:129]
	v_pk_fma_f32 v[114:115], v[58:59], s[28:29], v[114:115] op_sel_hi:[1,0,1]
	v_pk_fma_f32 v[116:117], v[60:61], s[28:29], v[116:117] op_sel_hi:[1,0,1]
	v_pk_fma_f32 v[118:119], v[62:63], s[28:29], v[118:119] op_sel_hi:[1,0,1]
	v_pk_fma_f32 v[120:121], v[64:65], s[28:29], v[120:121] op_sel_hi:[1,0,1]
	v_pk_fma_f32 v[122:123], v[66:67], s[28:29], v[122:123] op_sel_hi:[1,0,1]
	v_pk_fma_f32 v[124:125], v[68:69], s[28:29], v[124:125] op_sel_hi:[1,0,1]
	v_pk_fma_f32 v[126:127], v[70:71], s[28:29], v[126:127] op_sel_hi:[1,0,1]
	v_pk_fma_f32 v[128:129], v[72:73], s[28:29], v[128:129] op_sel_hi:[1,0,1]
	v_add_f32_e32 v164, v114, v115
	v_add_f32_e32 v165, v116, v117
	v_add_f32_e32 v166, v118, v119
	v_add_f32_e32 v167, v120, v121
	v_add_f32_e32 v168, v122, v123
	v_add_f32_e32 v169, v124, v125
	v_add_f32_e32 v242, v126, v127
	v_add_f32_e32 v243, v128, v129
	v_add_f32_e32 v164, v164, v165
	v_add_f32_e32 v166, v166, v167
	v_add_f32_e32 v168, v168, v169
	v_add_f32_e32 v242, v242, v243
	v_add_f32_e32 v9, 0, v164
	v_add_f32_e32 v9, v9, v166
	v_add_f32_e32 v9, v9, v168
	v_add_f32_e32 v9, v9, v242
	ds_bpermute_b32 v28, v96, v9
	s_waitcnt lgkmcnt(0)
	v_add_f32_e32 v9, v9, v28
	ds_swizzle_b32 v28, v9 offset:swizzle(SWAP,16)
	s_waitcnt lgkmcnt(0)
	v_add_f32_e32 v9, v9, v28
	ds_swizzle_b32 v28, v9 offset:swizzle(SWAP,8)
	s_waitcnt lgkmcnt(0)
	v_add_f32_e32 v9, v9, v28
	ds_swizzle_b32 v28, v9 offset:swizzle(SWAP,4)
	s_waitcnt lgkmcnt(0)
	v_add_f32_e32 v9, v9, v28
	ds_swizzle_b32 v28, v9 offset:swizzle(SWAP,2)
	s_waitcnt lgkmcnt(0)
	v_add_f32_e32 v9, v9, v28
	ds_swizzle_b32 v28, v9 offset:swizzle(SWAP,1)
	s_waitcnt lgkmcnt(0)
	v_add_f32_e32 v9, v9, v28
	v_fmac_f32_e32 v114, 0xba800000, v9
	v_fmac_f32_e32 v115, 0xba800000, v9
	v_fmac_f32_e32 v116, 0xba800000, v9
	v_fmac_f32_e32 v117, 0xba800000, v9
	v_fmac_f32_e32 v118, 0xba800000, v9
	v_fmac_f32_e32 v119, 0xba800000, v9
	v_fmac_f32_e32 v120, 0xba800000, v9
	v_fmac_f32_e32 v121, 0xba800000, v9
	v_fmac_f32_e32 v122, 0xba800000, v9
	v_fmac_f32_e32 v123, 0xba800000, v9
	v_fmac_f32_e32 v124, 0xba800000, v9
	v_fmac_f32_e32 v125, 0xba800000, v9
	v_fmac_f32_e32 v126, 0xba800000, v9
	v_fmac_f32_e32 v127, 0xba800000, v9
	v_fmac_f32_e32 v128, 0xba800000, v9
	v_fmac_f32_e32 v129, 0xba800000, v9
	v_pk_mul_f32 v[244:245], v[114:115], v[114:115]
	v_pk_mul_f32 v[246:247], v[116:117], v[116:117]
	v_add_f32_e32 v244, v245, v244
	v_add_f32_e32 v246, v246, v247
	v_add_f32_e32 v164, v244, v246
	v_pk_mul_f32 v[244:245], v[118:119], v[118:119]
	v_pk_mul_f32 v[246:247], v[120:121], v[120:121]
	v_add_f32_e32 v244, v245, v244
	v_add_f32_e32 v246, v246, v247
	v_add_f32_e32 v165, v244, v246
	v_mul_f32_e32 v248, v122, v122
	v_mul_f32_e32 v249, v124, v124
	v_fmac_f32_e32 v248, v123, v123
	v_fmac_f32_e32 v249, v125, v125
	v_add_f32_e32 v166, v248, v249
	v_pk_mul_f32 v[244:245], v[126:127], v[126:127]
	v_pk_mul_f32 v[246:247], v[128:129], v[128:129]
	v_add_f32_e32 v244, v244, v245
	v_add_f32_e32 v246, v246, v247
	v_add_f32_e32 v167, v244, v246
	v_add_f32_e32 v164, v164, v165
	v_add_f32_e32 v164, v166, v164
	v_add_f32_e32 v9, v167, v164
	ds_bpermute_b32 v28, v96, v9
	s_waitcnt lgkmcnt(0)
	v_add_f32_e32 v9, v9, v28
	ds_swizzle_b32 v28, v9 offset:swizzle(SWAP,16)
	s_waitcnt lgkmcnt(0)
	v_add_f32_e32 v9, v9, v28
	ds_swizzle_b32 v28, v9 offset:swizzle(SWAP,8)
	s_waitcnt lgkmcnt(0)
	v_add_f32_e32 v9, v9, v28
	ds_swizzle_b32 v28, v9 offset:swizzle(SWAP,4)
	s_waitcnt lgkmcnt(0)
	v_add_f32_e32 v9, v9, v28
	ds_swizzle_b32 v28, v9 offset:swizzle(SWAP,2)
	s_waitcnt lgkmcnt(0)
	v_add_f32_e32 v9, v9, v28
	ds_swizzle_b32 v28, v9 offset:swizzle(SWAP,1)
	s_waitcnt lgkmcnt(0)
	v_add_f32_e32 v9, v9, v28
	v_mov_b32_e32 v28, 0x3727c5ac
	v_fmamk_f32 v9, v9, 0x3a800000, v28
	v_mul_f32_e32 v28, 0x4b800000, v9
	v_cmp_gt_f32_e32 vcc, s37, v9
	s_nop 1
	v_cndmask_b32_e32 v9, v9, v28, vcc
	v_rsq_f32_e32 v9, v9
	s_nop 0
	v_mul_f32_e32 v28, 0x45800000, v9
	v_cndmask_b32_e32 v30, v9, v28, vcc
	v_pk_mul_f32 v[114:115], v[114:115], v[30:31] op_sel_hi:[1,0]
	v_pk_mul_f32 v[116:117], v[116:117], v[30:31] op_sel_hi:[1,0]
	v_pk_fma_f32 v[58:59], v[140:141], v[114:115], v[98:99]
	v_pk_fma_f32 v[60:61], v[142:143], v[116:117], v[100:101]
	global_store_dwordx4 v[86:87], v[58:61], off sc1 nt
	v_pk_fma_f32 v[114:115], v[226:227], v[58:59], v[210:211]
	v_pk_fma_f32 v[116:117], v[228:229], v[60:61], v[212:213]
	s_nop 0
	v_cvt_pk_bf16_f32 v74, v114, v115
	v_cvt_pk_bf16_f32 v75, v116, v117
	global_store_dwordx2 v[88:89], v[74:75], off sc1
	v_pk_mul_f32 v[118:119], v[118:119], v[30:31] op_sel_hi:[1,0]
	v_pk_mul_f32 v[120:121], v[120:121], v[30:31] op_sel_hi:[1,0]
	v_pk_fma_f32 v[62:63], v[144:145], v[118:119], v[102:103]
	v_pk_fma_f32 v[64:65], v[146:147], v[120:121], v[104:105]
	global_store_dwordx4 v[86:87], v[62:65], off offset:1024 sc1 nt
	v_pk_fma_f32 v[118:119], v[230:231], v[62:63], v[214:215]
	v_pk_fma_f32 v[120:121], v[232:233], v[64:65], v[216:217]
	s_nop 0
	v_cvt_pk_bf16_f32 v76, v118, v119
	v_cvt_pk_bf16_f32 v77, v120, v121
	global_store_dwordx2 v[88:89], v[76:77], off offset:512 sc1
	v_pk_mul_f32 v[122:123], v[122:123], v[30:31] op_sel_hi:[1,0]
	v_pk_mul_f32 v[124:125], v[124:125], v[30:31] op_sel_hi:[1,0]
	v_pk_fma_f32 v[66:67], v[148:149], v[122:123], v[106:107]
	v_pk_fma_f32 v[68:69], v[150:151], v[124:125], v[108:109]
	global_store_dwordx4 v[86:87], v[66:69], off offset:2048 sc1 nt
	v_pk_fma_f32 v[122:123], v[234:235], v[66:67], v[218:219]
	v_pk_fma_f32 v[124:125], v[236:237], v[68:69], v[220:221]
	s_nop 0
	v_cvt_pk_bf16_f32 v78, v122, v123
	v_cvt_pk_bf16_f32 v79, v124, v125
	global_store_dwordx2 v[88:89], v[78:79], off offset:1024 sc1
	v_pk_mul_f32 v[126:127], v[126:127], v[30:31] op_sel_hi:[1,0]
	v_pk_mul_f32 v[128:129], v[128:129], v[30:31] op_sel_hi:[1,0]
	v_pk_fma_f32 v[70:71], v[152:153], v[126:127], v[110:111]
	v_pk_fma_f32 v[72:73], v[154:155], v[128:129], v[112:113]
	global_store_dwordx4 v[86:87], v[70:73], off offset:3072 sc1 nt
	v_pk_fma_f32 v[126:127], v[238:239], v[70:71], v[222:223]
	v_pk_fma_f32 v[128:129], v[240:241], v[72:73], v[224:225]
	s_nop 0
	v_cvt_pk_bf16_f32 v80, v126, v127
	v_cvt_pk_bf16_f32 v81, v128, v129
	global_store_dwordx2 v[88:89], v[80:81], off offset:1536 sc1
	v_lshl_add_u64 v[86:87], v[86:87], 0, s[0:1]
	v_lshl_add_u64 v[88:89], v[88:89], 0, s[20:21]
	s_waitcnt vmcnt(24)
	v_lshlrev_b32_e32 v156, 16, v12
	v_and_b32_e32 v157, 0xffff0000, v12
	v_lshlrev_b32_e32 v12, 16, v13
	v_and_b32_e32 v13, 0xffff0000, v13
	v_lshlrev_b32_e32 v158, 16, v14
	v_and_b32_e32 v159, 0xffff0000, v14
	v_lshlrev_b32_e32 v14, 16, v15
	v_and_b32_e32 v15, 0xffff0000, v15
	v_lshlrev_b32_e32 v160, 16, v16
	v_and_b32_e32 v161, 0xffff0000, v16
	v_lshlrev_b32_e32 v16, 16, v17
	v_and_b32_e32 v17, 0xffff0000, v17
	v_lshlrev_b32_e32 v162, 16, v18
	v_and_b32_e32 v163, 0xffff0000, v18
	v_lshlrev_b32_e32 v18, 16, v19
	v_and_b32_e32 v19, 0xffff0000, v19
	v_pk_mul_f32 v[114:115], v[194:195], v[156:157]
	v_pk_mul_f32 v[116:117], v[196:197], v[12:13]
	v_pk_mul_f32 v[118:119], v[198:199], v[158:159]
	v_pk_mul_f32 v[120:121], v[200:201], v[14:15]
	v_pk_mul_f32 v[122:123], v[202:203], v[160:161]
	v_pk_mul_f32 v[124:125], v[204:205], v[16:17]
	v_pk_mul_f32 v[126:127], v[206:207], v[162:163]
	v_pk_mul_f32 v[128:129], v[208:209], v[18:19]
	v_pk_mul_f32 v[114:115], v[10:11], v[114:115]
	v_pk_mul_f32 v[116:117], v[10:11], v[116:117]
	v_pk_mul_f32 v[118:119], v[10:11], v[118:119]
	v_pk_mul_f32 v[120:121], v[10:11], v[120:121]
	v_pk_mul_f32 v[122:123], v[10:11], v[122:123]
	v_pk_mul_f32 v[124:125], v[10:11], v[124:125]
	v_pk_mul_f32 v[126:127], v[10:11], v[126:127]
	v_pk_mul_f32 v[128:129], v[10:11], v[128:129]
	v_pk_fma_f32 v[114:115], v[20:21], s[28:29], v[114:115] op_sel_hi:[1,0,1]
	v_pk_fma_f32 v[116:117], v[22:23], s[28:29], v[116:117] op_sel_hi:[1,0,1]
	v_pk_fma_f32 v[118:119], v[24:25], s[28:29], v[118:119] op_sel_hi:[1,0,1]
	v_pk_fma_f32 v[120:121], v[26:27], s[28:29], v[120:121] op_sel_hi:[1,0,1]
	v_pk_fma_f32 v[122:123], v[0:1], s[28:29], v[122:123] op_sel_hi:[1,0,1]
	v_pk_fma_f32 v[124:125], v[2:3], s[28:29], v[124:125] op_sel_hi:[1,0,1]
	v_pk_fma_f32 v[126:127], v[4:5], s[28:29], v[126:127] op_sel_hi:[1,0,1]
	v_pk_fma_f32 v[128:129], v[6:7], s[28:29], v[128:129] op_sel_hi:[1,0,1]
	v_add_f32_e32 v164, v114, v115
	v_add_f32_e32 v165, v116, v117
	v_add_f32_e32 v166, v118, v119
	v_add_f32_e32 v167, v120, v121
	v_add_f32_e32 v168, v122, v123
	v_add_f32_e32 v169, v124, v125
	v_add_f32_e32 v242, v126, v127
	v_add_f32_e32 v243, v128, v129
	v_add_f32_e32 v164, v164, v165
	v_add_f32_e32 v166, v166, v167
	v_add_f32_e32 v168, v168, v169
	v_add_f32_e32 v242, v242, v243
	v_add_f32_e32 v9, 0, v164
	v_add_f32_e32 v9, v9, v166
	v_add_f32_e32 v9, v9, v168
	v_add_f32_e32 v9, v9, v242
	ds_bpermute_b32 v28, v96, v9
	s_waitcnt lgkmcnt(0)
	v_add_f32_e32 v9, v9, v28
	ds_swizzle_b32 v28, v9 offset:swizzle(SWAP,16)
	s_waitcnt lgkmcnt(0)
	v_add_f32_e32 v9, v9, v28
	ds_swizzle_b32 v28, v9 offset:swizzle(SWAP,8)
	s_waitcnt lgkmcnt(0)
	v_add_f32_e32 v9, v9, v28
	ds_swizzle_b32 v28, v9 offset:swizzle(SWAP,4)
	s_waitcnt lgkmcnt(0)
	v_add_f32_e32 v9, v9, v28
	ds_swizzle_b32 v28, v9 offset:swizzle(SWAP,2)
	s_waitcnt lgkmcnt(0)
	v_add_f32_e32 v9, v9, v28
	ds_swizzle_b32 v28, v9 offset:swizzle(SWAP,1)
	s_waitcnt lgkmcnt(0)
	v_add_f32_e32 v9, v9, v28
	v_fmac_f32_e32 v114, 0xba800000, v9
	v_fmac_f32_e32 v115, 0xba800000, v9
	v_fmac_f32_e32 v116, 0xba800000, v9
	v_fmac_f32_e32 v117, 0xba800000, v9
	v_fmac_f32_e32 v118, 0xba800000, v9
	v_fmac_f32_e32 v119, 0xba800000, v9
	v_fmac_f32_e32 v120, 0xba800000, v9
	v_fmac_f32_e32 v121, 0xba800000, v9
	v_fmac_f32_e32 v122, 0xba800000, v9
	v_fmac_f32_e32 v123, 0xba800000, v9
	v_fmac_f32_e32 v124, 0xba800000, v9
	v_fmac_f32_e32 v125, 0xba800000, v9
	v_fmac_f32_e32 v126, 0xba800000, v9
	v_fmac_f32_e32 v127, 0xba800000, v9
	v_fmac_f32_e32 v128, 0xba800000, v9
	v_fmac_f32_e32 v129, 0xba800000, v9
	v_pk_mul_f32 v[244:245], v[114:115], v[114:115]
	v_pk_mul_f32 v[246:247], v[116:117], v[116:117]
	v_add_f32_e32 v244, v245, v244
	v_add_f32_e32 v246, v246, v247
	v_add_f32_e32 v164, v244, v246
	v_pk_mul_f32 v[244:245], v[118:119], v[118:119]
	v_pk_mul_f32 v[246:247], v[120:121], v[120:121]
	v_add_f32_e32 v244, v245, v244
	v_add_f32_e32 v246, v246, v247
	v_add_f32_e32 v165, v244, v246
	v_mul_f32_e32 v248, v122, v122
	v_mul_f32_e32 v249, v124, v124
	v_fmac_f32_e32 v248, v123, v123
	v_fmac_f32_e32 v249, v125, v125
	v_add_f32_e32 v166, v248, v249
	v_pk_mul_f32 v[244:245], v[126:127], v[126:127]
	v_pk_mul_f32 v[246:247], v[128:129], v[128:129]
	v_add_f32_e32 v244, v244, v245
	v_add_f32_e32 v246, v246, v247
	v_add_f32_e32 v167, v244, v246
	v_add_f32_e32 v164, v164, v165
	v_add_f32_e32 v164, v166, v164
	v_add_f32_e32 v9, v167, v164
	ds_bpermute_b32 v28, v96, v9
	s_waitcnt lgkmcnt(0)
	v_add_f32_e32 v9, v9, v28
	ds_swizzle_b32 v28, v9 offset:swizzle(SWAP,16)
	s_waitcnt lgkmcnt(0)
	v_add_f32_e32 v9, v9, v28
	ds_swizzle_b32 v28, v9 offset:swizzle(SWAP,8)
	s_waitcnt lgkmcnt(0)
	v_add_f32_e32 v9, v9, v28
	ds_swizzle_b32 v28, v9 offset:swizzle(SWAP,4)
	s_waitcnt lgkmcnt(0)
	v_add_f32_e32 v9, v9, v28
	ds_swizzle_b32 v28, v9 offset:swizzle(SWAP,2)
	s_waitcnt lgkmcnt(0)
	v_add_f32_e32 v9, v9, v28
	ds_swizzle_b32 v28, v9 offset:swizzle(SWAP,1)
	s_waitcnt lgkmcnt(0)
	v_add_f32_e32 v9, v9, v28
	v_mov_b32_e32 v28, 0x3727c5ac
	v_fmamk_f32 v9, v9, 0x3a800000, v28
	v_mul_f32_e32 v28, 0x4b800000, v9
	v_cmp_gt_f32_e32 vcc, s37, v9
	s_nop 1
	v_cndmask_b32_e32 v9, v9, v28, vcc
	v_rsq_f32_e32 v9, v9
	s_nop 0
	v_mul_f32_e32 v28, 0x45800000, v9
	v_cndmask_b32_e32 v30, v9, v28, vcc
	v_pk_mul_f32 v[114:115], v[114:115], v[30:31] op_sel_hi:[1,0]
	v_pk_mul_f32 v[116:117], v[116:117], v[30:31] op_sel_hi:[1,0]
	v_pk_fma_f32 v[20:21], v[140:141], v[114:115], v[98:99]
	v_pk_fma_f32 v[22:23], v[142:143], v[116:117], v[100:101]
	global_store_dwordx4 v[86:87], v[20:23], off sc1 nt
	v_pk_fma_f32 v[114:115], v[226:227], v[20:21], v[210:211]
	v_pk_fma_f32 v[116:117], v[228:229], v[22:23], v[212:213]
	s_nop 0
	v_cvt_pk_bf16_f32 v12, v114, v115
	v_cvt_pk_bf16_f32 v13, v116, v117
	global_store_dwordx2 v[88:89], v[12:13], off sc1
	v_pk_mul_f32 v[118:119], v[118:119], v[30:31] op_sel_hi:[1,0]
	v_pk_mul_f32 v[120:121], v[120:121], v[30:31] op_sel_hi:[1,0]
	v_pk_fma_f32 v[24:25], v[144:145], v[118:119], v[102:103]
	v_pk_fma_f32 v[26:27], v[146:147], v[120:121], v[104:105]
	global_store_dwordx4 v[86:87], v[24:27], off offset:1024 sc1 nt
	v_pk_fma_f32 v[118:119], v[230:231], v[24:25], v[214:215]
	v_pk_fma_f32 v[120:121], v[232:233], v[26:27], v[216:217]
	s_nop 0
	v_cvt_pk_bf16_f32 v14, v118, v119
	v_cvt_pk_bf16_f32 v15, v120, v121
	global_store_dwordx2 v[88:89], v[14:15], off offset:512 sc1
	v_pk_mul_f32 v[122:123], v[122:123], v[30:31] op_sel_hi:[1,0]
	v_pk_mul_f32 v[124:125], v[124:125], v[30:31] op_sel_hi:[1,0]
	v_pk_fma_f32 v[0:1], v[148:149], v[122:123], v[106:107]
	v_pk_fma_f32 v[2:3], v[150:151], v[124:125], v[108:109]
	global_store_dwordx4 v[86:87], v[0:3], off offset:2048 sc1 nt
	v_pk_fma_f32 v[122:123], v[234:235], v[0:1], v[218:219]
	v_pk_fma_f32 v[124:125], v[236:237], v[2:3], v[220:221]
	s_nop 0
	v_cvt_pk_bf16_f32 v16, v122, v123
	v_cvt_pk_bf16_f32 v17, v124, v125
	global_store_dwordx2 v[88:89], v[16:17], off offset:1024 sc1
	v_pk_mul_f32 v[126:127], v[126:127], v[30:31] op_sel_hi:[1,0]
	v_pk_mul_f32 v[128:129], v[128:129], v[30:31] op_sel_hi:[1,0]
	v_pk_fma_f32 v[4:5], v[152:153], v[126:127], v[110:111]
	v_pk_fma_f32 v[6:7], v[154:155], v[128:129], v[112:113]
	global_store_dwordx4 v[86:87], v[4:7], off offset:3072 sc1 nt
	v_pk_fma_f32 v[126:127], v[238:239], v[4:5], v[222:223]
	v_pk_fma_f32 v[128:129], v[240:241], v[6:7], v[224:225]
	s_nop 0
	v_cvt_pk_bf16_f32 v18, v126, v127
	v_cvt_pk_bf16_f32 v19, v128, v129
	global_store_dwordx2 v[88:89], v[18:19], off offset:1536 sc1
	v_lshl_add_u64 v[86:87], v[86:87], 0, s[0:1]
	v_lshl_add_u64 v[88:89], v[88:89], 0, s[20:21]
	s_waitcnt vmcnt(16)
	v_lshlrev_b32_e32 v156, 16, v50
	v_and_b32_e32 v157, 0xffff0000, v50
	v_lshlrev_b32_e32 v50, 16, v51
	v_and_b32_e32 v51, 0xffff0000, v51
	v_lshlrev_b32_e32 v158, 16, v52
	v_and_b32_e32 v159, 0xffff0000, v52
	v_lshlrev_b32_e32 v52, 16, v53
	v_and_b32_e32 v53, 0xffff0000, v53
	v_lshlrev_b32_e32 v160, 16, v54
	v_and_b32_e32 v161, 0xffff0000, v54
	v_lshlrev_b32_e32 v54, 16, v55
	v_and_b32_e32 v55, 0xffff0000, v55
	v_lshlrev_b32_e32 v162, 16, v56
	v_and_b32_e32 v163, 0xffff0000, v56
	v_lshlrev_b32_e32 v56, 16, v57
	v_and_b32_e32 v57, 0xffff0000, v57
	v_pk_mul_f32 v[114:115], v[194:195], v[156:157]
	v_pk_mul_f32 v[116:117], v[196:197], v[50:51]
	v_pk_mul_f32 v[118:119], v[198:199], v[158:159]
	v_pk_mul_f32 v[120:121], v[200:201], v[52:53]
	v_pk_mul_f32 v[122:123], v[202:203], v[160:161]
	v_pk_mul_f32 v[124:125], v[204:205], v[54:55]
	v_pk_mul_f32 v[126:127], v[206:207], v[162:163]
	v_pk_mul_f32 v[128:129], v[208:209], v[56:57]
	v_pk_mul_f32 v[114:115], v[10:11], v[114:115]
	v_pk_mul_f32 v[116:117], v[10:11], v[116:117]
	v_pk_mul_f32 v[118:119], v[10:11], v[118:119]
	v_pk_mul_f32 v[120:121], v[10:11], v[120:121]
	v_pk_mul_f32 v[122:123], v[10:11], v[122:123]
	v_pk_mul_f32 v[124:125], v[10:11], v[124:125]
	v_pk_mul_f32 v[126:127], v[10:11], v[126:127]
	v_pk_mul_f32 v[128:129], v[10:11], v[128:129]
	v_pk_fma_f32 v[114:115], v[34:35], s[28:29], v[114:115] op_sel_hi:[1,0,1]
	v_pk_fma_f32 v[116:117], v[36:37], s[28:29], v[116:117] op_sel_hi:[1,0,1]
	v_pk_fma_f32 v[118:119], v[38:39], s[28:29], v[118:119] op_sel_hi:[1,0,1]
	v_pk_fma_f32 v[120:121], v[40:41], s[28:29], v[120:121] op_sel_hi:[1,0,1]
	v_pk_fma_f32 v[122:123], v[42:43], s[28:29], v[122:123] op_sel_hi:[1,0,1]
	v_pk_fma_f32 v[124:125], v[44:45], s[28:29], v[124:125] op_sel_hi:[1,0,1]
	v_pk_fma_f32 v[126:127], v[46:47], s[28:29], v[126:127] op_sel_hi:[1,0,1]
	v_pk_fma_f32 v[128:129], v[48:49], s[28:29], v[128:129] op_sel_hi:[1,0,1]
	v_add_f32_e32 v164, v114, v115
	v_add_f32_e32 v165, v116, v117
	v_add_f32_e32 v166, v118, v119
	v_add_f32_e32 v167, v120, v121
	v_add_f32_e32 v168, v122, v123
	v_add_f32_e32 v169, v124, v125
	v_add_f32_e32 v242, v126, v127
	v_add_f32_e32 v243, v128, v129
	v_add_f32_e32 v164, v164, v165
	v_add_f32_e32 v166, v166, v167
	v_add_f32_e32 v168, v168, v169
	v_add_f32_e32 v242, v242, v243
	v_add_f32_e32 v9, 0, v164
	v_add_f32_e32 v9, v9, v166
	v_add_f32_e32 v9, v9, v168
	v_add_f32_e32 v9, v9, v242
	ds_bpermute_b32 v28, v96, v9
	s_waitcnt lgkmcnt(0)
	v_add_f32_e32 v9, v9, v28
	ds_swizzle_b32 v28, v9 offset:swizzle(SWAP,16)
	s_waitcnt lgkmcnt(0)
	v_add_f32_e32 v9, v9, v28
	ds_swizzle_b32 v28, v9 offset:swizzle(SWAP,8)
	s_waitcnt lgkmcnt(0)
	v_add_f32_e32 v9, v9, v28
	ds_swizzle_b32 v28, v9 offset:swizzle(SWAP,4)
	s_waitcnt lgkmcnt(0)
	v_add_f32_e32 v9, v9, v28
	ds_swizzle_b32 v28, v9 offset:swizzle(SWAP,2)
	s_waitcnt lgkmcnt(0)
	v_add_f32_e32 v9, v9, v28
	ds_swizzle_b32 v28, v9 offset:swizzle(SWAP,1)
	s_waitcnt lgkmcnt(0)
	v_add_f32_e32 v9, v9, v28
	v_fmac_f32_e32 v114, 0xba800000, v9
	v_fmac_f32_e32 v115, 0xba800000, v9
	v_fmac_f32_e32 v116, 0xba800000, v9
	v_fmac_f32_e32 v117, 0xba800000, v9
	v_fmac_f32_e32 v118, 0xba800000, v9
	v_fmac_f32_e32 v119, 0xba800000, v9
	v_fmac_f32_e32 v120, 0xba800000, v9
	v_fmac_f32_e32 v121, 0xba800000, v9
	v_fmac_f32_e32 v122, 0xba800000, v9
	v_fmac_f32_e32 v123, 0xba800000, v9
	v_fmac_f32_e32 v124, 0xba800000, v9
	v_fmac_f32_e32 v125, 0xba800000, v9
	v_fmac_f32_e32 v126, 0xba800000, v9
	v_fmac_f32_e32 v127, 0xba800000, v9
	v_fmac_f32_e32 v128, 0xba800000, v9
	v_fmac_f32_e32 v129, 0xba800000, v9
	v_pk_mul_f32 v[244:245], v[114:115], v[114:115]
	v_pk_mul_f32 v[246:247], v[116:117], v[116:117]
	v_add_f32_e32 v244, v245, v244
	v_add_f32_e32 v246, v246, v247
	v_add_f32_e32 v164, v244, v246
	v_pk_mul_f32 v[244:245], v[118:119], v[118:119]
	v_pk_mul_f32 v[246:247], v[120:121], v[120:121]
	v_add_f32_e32 v244, v245, v244
	v_add_f32_e32 v246, v246, v247
	v_add_f32_e32 v165, v244, v246
	v_mul_f32_e32 v248, v122, v122
	v_mul_f32_e32 v249, v124, v124
	v_fmac_f32_e32 v248, v123, v123
	v_fmac_f32_e32 v249, v125, v125
	v_add_f32_e32 v166, v248, v249
	v_pk_mul_f32 v[244:245], v[126:127], v[126:127]
	v_pk_mul_f32 v[246:247], v[128:129], v[128:129]
	v_add_f32_e32 v244, v244, v245
	v_add_f32_e32 v246, v246, v247
	v_add_f32_e32 v167, v244, v246
	v_add_f32_e32 v164, v164, v165
	v_add_f32_e32 v164, v166, v164
	v_add_f32_e32 v9, v167, v164
	ds_bpermute_b32 v28, v96, v9
	s_waitcnt lgkmcnt(0)
	v_add_f32_e32 v9, v9, v28
	ds_swizzle_b32 v28, v9 offset:swizzle(SWAP,16)
	s_waitcnt lgkmcnt(0)
	v_add_f32_e32 v9, v9, v28
	ds_swizzle_b32 v28, v9 offset:swizzle(SWAP,8)
	s_waitcnt lgkmcnt(0)
	v_add_f32_e32 v9, v9, v28
	ds_swizzle_b32 v28, v9 offset:swizzle(SWAP,4)
	s_waitcnt lgkmcnt(0)
	v_add_f32_e32 v9, v9, v28
	ds_swizzle_b32 v28, v9 offset:swizzle(SWAP,2)
	s_waitcnt lgkmcnt(0)
	v_add_f32_e32 v9, v9, v28
	ds_swizzle_b32 v28, v9 offset:swizzle(SWAP,1)
	s_waitcnt lgkmcnt(0)
	v_add_f32_e32 v9, v9, v28
	v_mov_b32_e32 v28, 0x3727c5ac
	v_fmamk_f32 v9, v9, 0x3a800000, v28
	v_mul_f32_e32 v28, 0x4b800000, v9
	v_cmp_gt_f32_e32 vcc, s37, v9
	s_nop 1
	v_cndmask_b32_e32 v9, v9, v28, vcc
	v_rsq_f32_e32 v9, v9
	s_nop 0
	v_mul_f32_e32 v28, 0x45800000, v9
	v_cndmask_b32_e32 v30, v9, v28, vcc
	v_pk_mul_f32 v[114:115], v[114:115], v[30:31] op_sel_hi:[1,0]
	v_pk_mul_f32 v[116:117], v[116:117], v[30:31] op_sel_hi:[1,0]
	v_pk_fma_f32 v[34:35], v[140:141], v[114:115], v[98:99]
	v_pk_fma_f32 v[36:37], v[142:143], v[116:117], v[100:101]
	global_store_dwordx4 v[86:87], v[34:37], off sc1 nt
	v_pk_fma_f32 v[114:115], v[226:227], v[34:35], v[210:211]
	v_pk_fma_f32 v[116:117], v[228:229], v[36:37], v[212:213]
	s_nop 0
	v_cvt_pk_bf16_f32 v50, v114, v115
	v_cvt_pk_bf16_f32 v51, v116, v117
	global_store_dwordx2 v[88:89], v[50:51], off sc1
	v_pk_mul_f32 v[118:119], v[118:119], v[30:31] op_sel_hi:[1,0]
	v_pk_mul_f32 v[120:121], v[120:121], v[30:31] op_sel_hi:[1,0]
	v_pk_fma_f32 v[38:39], v[144:145], v[118:119], v[102:103]
	v_pk_fma_f32 v[40:41], v[146:147], v[120:121], v[104:105]
	global_store_dwordx4 v[86:87], v[38:41], off offset:1024 sc1 nt
	v_pk_fma_f32 v[118:119], v[230:231], v[38:39], v[214:215]
	v_pk_fma_f32 v[120:121], v[232:233], v[40:41], v[216:217]
	s_nop 0
	v_cvt_pk_bf16_f32 v52, v118, v119
	v_cvt_pk_bf16_f32 v53, v120, v121
	global_store_dwordx2 v[88:89], v[52:53], off offset:512 sc1
	v_pk_mul_f32 v[122:123], v[122:123], v[30:31] op_sel_hi:[1,0]
	v_pk_mul_f32 v[124:125], v[124:125], v[30:31] op_sel_hi:[1,0]
	v_pk_fma_f32 v[42:43], v[148:149], v[122:123], v[106:107]
	v_pk_fma_f32 v[44:45], v[150:151], v[124:125], v[108:109]
	global_store_dwordx4 v[86:87], v[42:45], off offset:2048 sc1 nt
	v_pk_fma_f32 v[122:123], v[234:235], v[42:43], v[218:219]
	v_pk_fma_f32 v[124:125], v[236:237], v[44:45], v[220:221]
	s_nop 0
	v_cvt_pk_bf16_f32 v54, v122, v123
	v_cvt_pk_bf16_f32 v55, v124, v125
	global_store_dwordx2 v[88:89], v[54:55], off offset:1024 sc1
	v_pk_mul_f32 v[126:127], v[126:127], v[30:31] op_sel_hi:[1,0]
	v_pk_mul_f32 v[128:129], v[128:129], v[30:31] op_sel_hi:[1,0]
	v_pk_fma_f32 v[46:47], v[152:153], v[126:127], v[110:111]
	v_pk_fma_f32 v[48:49], v[154:155], v[128:129], v[112:113]
	global_store_dwordx4 v[86:87], v[46:49], off offset:3072 sc1 nt
	v_pk_fma_f32 v[126:127], v[238:239], v[46:47], v[222:223]
	v_pk_fma_f32 v[128:129], v[240:241], v[48:49], v[224:225]
	s_nop 0
	v_cvt_pk_bf16_f32 v56, v126, v127
	v_cvt_pk_bf16_f32 v57, v128, v129
	global_store_dwordx2 v[88:89], v[56:57], off offset:1536 sc1
	v_lshl_add_u64 v[86:87], v[86:87], 0, s[0:1]
	v_lshl_add_u64 v[88:89], v[88:89], 0, s[20:21]
	s_branch .LBB0_53
